# adds: S5 block loops hand-written (FMA recurrence, prefetch), gelu rcp in S5, ret_sample and swa_sample state/key rows via LDS-DMA
# speedup vs baseline: 1.0101x; 1.0101x over previous
; #define LAS __attribute__((address_space(3)))
; template <int MODE>
; __device__ __forceinline__ void ssm_unit(const Ctx& P, int li, int g, int cidx, LAS unsigned char* hs, const bf16_t* H, bf16_t* Z, float* E, int lane) {
;     ...
;     if (MODE >= 1) {
;         const float* crp = P.in[I_CRE] + ((size_t)(li * 128 + g) * 16 + fr) * 64; const float* cip = P.in[I_CIM] + ((size_t)(li * 128 + g) * 16 + fr) * 64;
; #pragma unroll
;         for (int kk = 0; kk < 4; ++kk) { const int c0 = 8 * kk + 2 * fq;
;             const float r0 = crp[c0], r1 = crp[c0 + 1], r2 = crp[c0 + 32], r3 = crp[c0 + 33];
;             const float i0 = cip[c0], i1 = cip[c0 + 1], i2 = cip[c0 + 32], i3 = cip[c0 + 33];
;             u32x4 w; w.x = pk_bf16(r0, -i0); w.y = pk_bf16(r2, -i2); w.z = pk_bf16(r1, -i1); w.w = pk_bf16(r3, -i3);
;             Cf[kk] = __builtin_bit_cast(bf16x8, w); }
;     }
;     const int nblk = (MODE == 2) ? 1 : 8;
;     for (int blk = 0; blk < nblk; ++blk) {
;         {   const int bsel = (c >> 2) & 1, tj = (c & 3) + 4 * (c >> 3);
;             const size_t rowg = (MODE == 2) ? (size_t)TP + 32 * cidx + 16 * bsel + tj : (size_t)bsel * SEQ + (size_t)cidx * 128 + blk * 16 + tj;
;             const bf16x8 af = *(const bf16x8*)(H + rowg * DM + g * 16 + 8 * half);
;             const f32x16 z16 = {0.f, 0.f, 0.f, 0.f, 0.f, 0.f, 0.f, 0.f, 0.f, 0.f, 0.f, 0.f, 0.f, 0.f, 0.f, 0.f};
;             const f32x16 d0 = mfma32(af, Bf[0], z16), d1 = mfma32(af, Bf[1], z16), d2 = mfma32(af, Bf[2], z16), d3 = mfma32(af, Bf[3], z16);
; #pragma unroll
;             for (int r = 0; r < 16; ++r) {
;                 if (MODE == 2 && (r & 3) == 0) { const int batch = 8 * cidx + 4 * half + (r >> 2); const size_t sp = ((size_t)(li * 32 + batch) * 128 + g) * 64 + c;
;                     hr[0] = P.in[I_SSRE][sp]; hi[0] = P.in[I_SSIM][sp]; hr[1] = P.in[I_SSRE][sp + 32]; hi[1] = P.in[I_SSIM][sp + 32]; }
;                 { const float t = lre[0] * hr[0] - lim[0] * hi[0] + d0[r]; hi[0] = lre[0] * hi[0] + lim[0] * hr[0] + d1[r]; hr[0] = t; }
;                 { const float t = lre[1] * hr[1] - lim[1] * hi[1] + d2[r]; hi[1] = lre[1] * hi[1] + lim[1] * hr[1] + d3[r]; hr[1] = t; }
;                 if (MODE >= 1) { u32x2 w; w.x = pk_bf16(hr[0], hi[0]); w.y = pk_bf16(hr[1], hi[1]); *(LAS u32x2*)(hs + (16 * half + r) * 272 + c * 8) = w; }
.LBB0_86:
	s_or_b64 exec, exec, s[40:41]
	v_lshlrev_b64 v[0:1], 12, v[16:17]
	v_lshl_or_b32 v0, v102, 2, v0
	v_lshl_add_u64 v[2:3], v[112:113], 0, v[0:1]
	v_lshl_add_u64 v[0:1], v[114:115], 0, v[0:1]
	global_load_dwordx2 v[4:5], v[2:3], off
	global_load_dwordx2 v[6:7], v[2:3], off offset:128
	global_load_dwordx2 v[8:9], v[0:1], off
	global_load_dwordx2 v[10:11], v[0:1], off offset:128
	v_ashrrev_i32_e32 v123, 31, v122
	v_lshlrev_b32_e32 v128, 6, v153
	v_pk_mov_b32 v[140:141], v[124:125], v[124:125] op_sel:[1,0]
	v_pk_mov_b32 v[142:143], v[126:127], v[126:127] op_sel:[1,0]
	v_lshl_add_u64 v[144:145], v[108:109], 0, v[128:129]
	v_mov_b32_e32 v146, v126
	v_mov_b32_e32 v147, v126
	s_mov_b64 s[0:1], 0
	s_waitcnt vmcnt(1)
	v_xor_b32_e32 v8, 0x80000000, v8
	v_cvt_pk_bf16_f32 v80, v4, v8
	s_waitcnt vmcnt(0)
	v_xor_b32_e32 v4, 0x80000000, v10
	v_cvt_pk_bf16_f32 v81, v6, v4
	v_xor_b32_e32 v4, 0x80000000, v9
	v_cvt_pk_bf16_f32 v82, v5, v4
	v_xor_b32_e32 v4, 0x80000000, v11
	v_cvt_pk_bf16_f32 v83, v7, v4
	global_load_dwordx2 v[4:5], v[2:3], off offset:32
	global_load_dwordx2 v[6:7], v[2:3], off offset:160
	global_load_dwordx2 v[8:9], v[0:1], off offset:32
	global_load_dwordx2 v[10:11], v[0:1], off offset:160
	s_waitcnt vmcnt(1)
	v_xor_b32_e32 v8, 0x80000000, v8
	v_cvt_pk_bf16_f32 v84, v4, v8
	s_waitcnt vmcnt(0)
	v_xor_b32_e32 v4, 0x80000000, v10
	v_cvt_pk_bf16_f32 v85, v6, v4
	v_xor_b32_e32 v4, 0x80000000, v9
	v_cvt_pk_bf16_f32 v86, v5, v4
	v_xor_b32_e32 v4, 0x80000000, v11
	v_cvt_pk_bf16_f32 v87, v7, v4
	global_load_dwordx2 v[4:5], v[2:3], off offset:64
	global_load_dwordx2 v[6:7], v[2:3], off offset:192
	global_load_dwordx2 v[8:9], v[0:1], off offset:64
	global_load_dwordx2 v[10:11], v[0:1], off offset:192
	s_waitcnt vmcnt(1)
	v_xor_b32_e32 v8, 0x80000000, v8
	v_cvt_pk_bf16_f32 v88, v4, v8
	s_waitcnt vmcnt(0)
	v_xor_b32_e32 v4, 0x80000000, v10
	v_cvt_pk_bf16_f32 v89, v6, v4
	v_xor_b32_e32 v4, 0x80000000, v9
	v_cvt_pk_bf16_f32 v90, v5, v4
	v_xor_b32_e32 v4, 0x80000000, v11
	v_cvt_pk_bf16_f32 v91, v7, v4
	global_load_dwordx2 v[4:5], v[2:3], off offset:96
	s_nop 0
	global_load_dwordx2 v[2:3], v[2:3], off offset:224
	s_nop 0
	global_load_dwordx2 v[6:7], v[0:1], off offset:96
	s_nop 0
	global_load_dwordx2 v[0:1], v[0:1], off offset:224
	s_waitcnt vmcnt(1)
	v_xor_b32_e32 v6, 0x80000000, v6
	s_waitcnt vmcnt(0)
	v_xor_b32_e32 v0, 0x80000000, v0
	v_cvt_pk_bf16_f32 v92, v4, v6
	v_cvt_pk_bf16_f32 v93, v2, v0
	v_xor_b32_e32 v0, 0x80000000, v7
	v_cvt_pk_bf16_f32 v94, v5, v0
	v_xor_b32_e32 v0, 0x80000000, v1
	v_cvt_pk_bf16_f32 v95, v3, v0
	v_lshlrev_b64 v[0:1], 19, v[122:123]
	v_lshl_or_b32 v0, v20, 5, v0
	v_lshl_add_u64 v[148:149], v[118:119], 0, v[0:1]
	v_lshl_add_u64 v[150:151], v[120:121], 0, v[0:1]
	s_nop 0
	global_load_dwordx4 v[212:215], v[150:151], off
	global_load_dwordx4 v[216:219], v[144:145], off
	s_waitcnt vmcnt(0)
.LBB0_87:
	v_mov_b64_e32 v[16:17], v[212:213]
	v_mov_b64_e32 v[18:19], v[214:215]
	v_lshl_add_u64 v[220:221], v[148:149], 0, s[0:1]
	v_lshl_add_u64 v[0:1], v[150:151], 0, s[0:1]
	v_add_co_u32_e32 v222, vcc, 0x16200000, v220
	s_nop 1
	v_addc_co_u32_e32 v223, vcc, 0, v221, vcc
	global_load_dwordx2 v[224:225], v[222:223], off
	v_add_co_u32_e32 v222, vcc, 0x17200000, v220
	s_nop 1
	v_addc_co_u32_e32 v223, vcc, 0, v221, vcc
	global_load_dwordx2 v[226:227], v[222:223], off
	v_add_co_u32_e32 v0, vcc, 0x10000, v0
	s_nop 1
	v_addc_co_u32_e32 v1, vcc, 0, v1, vcc
	global_load_dwordx4 v[212:215], v[0:1], off
	s_mov_b32 s24, 0x16200000
	v_mfma_f32_32x32x16_bf16 v[32:47], v[16:19], v[64:67], 0
	v_mfma_f32_32x32x16_bf16 v[0:15], v[16:19], v[68:71], 0
	v_mfma_f32_32x32x16_bf16 v[48:63], v[16:19], v[72:75], 0
	v_mfma_f32_32x32x16_bf16 v[16:31], v[16:19], v[76:79], 0
	s_nop 11
	v_fma_f32 v228, -v125, v136, v32
	v_fma_f32 v229, v125, v138, v0
	v_fma_f32 v230, -v127, v137, v48
	v_fma_f32 v231, v127, v139, v16
	v_fma_f32 v138, v124, v138, v228
	v_fma_f32 v136, v124, v136, v229
	v_fma_f32 v139, v126, v139, v230
	v_fma_f32 v137, v126, v137, v231
	v_cvt_pk_bf16_f32 v236, v138, v136
	v_cvt_pk_bf16_f32 v237, v139, v137
	ds_write_b64 v133, v[236:237]
	v_fma_f32 v232, -v125, v136, v33
	v_fma_f32 v233, v125, v138, v1
	v_fma_f32 v234, -v127, v137, v49
	v_fma_f32 v235, v127, v139, v17
	v_fma_f32 v138, v124, v138, v232
	v_fma_f32 v136, v124, v136, v233
	v_fma_f32 v139, v126, v139, v234
	v_fma_f32 v137, v126, v137, v235
	v_cvt_pk_bf16_f32 v238, v138, v136
	v_cvt_pk_bf16_f32 v239, v139, v137
	ds_write_b64 v133, v[238:239] offset:272
	v_fma_f32 v228, -v125, v136, v34
	v_fma_f32 v229, v125, v138, v2
	v_fma_f32 v230, -v127, v137, v50
	v_fma_f32 v231, v127, v139, v18
	v_fma_f32 v138, v124, v138, v228
	v_fma_f32 v136, v124, v136, v229
	v_fma_f32 v139, v126, v139, v230
	v_fma_f32 v137, v126, v137, v231
	v_cvt_pk_bf16_f32 v240, v138, v136
	v_cvt_pk_bf16_f32 v241, v139, v137
	ds_write_b64 v133, v[240:241] offset:544
	v_fma_f32 v232, -v125, v136, v35
	v_fma_f32 v233, v125, v138, v3
	v_fma_f32 v234, -v127, v137, v51
	v_fma_f32 v235, v127, v139, v19
	v_fma_f32 v138, v124, v138, v232
	v_fma_f32 v136, v124, v136, v233
	v_fma_f32 v139, v126, v139, v234
	v_fma_f32 v137, v126, v137, v235
	v_cvt_pk_bf16_f32 v242, v138, v136
	v_cvt_pk_bf16_f32 v243, v139, v137
	ds_write_b64 v133, v[242:243] offset:816
	v_fma_f32 v228, -v125, v136, v36
	v_fma_f32 v229, v125, v138, v4
	v_fma_f32 v230, -v127, v137, v52
	v_fma_f32 v231, v127, v139, v20
	v_fma_f32 v138, v124, v138, v228
	v_fma_f32 v136, v124, v136, v229
	v_fma_f32 v139, v126, v139, v230
	v_fma_f32 v137, v126, v137, v231
	v_cvt_pk_bf16_f32 v236, v138, v136
	v_cvt_pk_bf16_f32 v237, v139, v137
	ds_write_b64 v133, v[236:237] offset:1088
; #define LAS __attribute__((address_space(3)))
; __device__ __forceinline__ unsigned pk_bf16(float lo, float hi) { unsigned r; asm volatile("v_cvt_pk_bf16_f32 %0, %1, %2" : "=v"(r) : "v"(lo), "v"(hi)); return r; }
; __device__ __forceinline__ f32x4 mfma16(bf16x8 a, bf16x8 b, f32x4 c) { return __builtin_amdgcn_mfma_f32_16x16x32_bf16(a, b, c, 0, 0, 0); }
; __device__ __forceinline__ void lds_wave_sync() { asm volatile("s_waitcnt lgkmcnt(0)" ::: "memory"); }
; template <int MODE>
; __device__ __forceinline__ void ssm_unit(const Ctx& P, int li, int g, int cidx, LAS unsigned char* hs, const bf16_t* H, bf16_t* Z, float* E, int lane) {
;     ...
;             for (int r = 0; r < 16; ++r) {
;                 if (MODE == 2 && (r & 3) == 0) { const int batch = 8 * cidx + 4 * half + (r >> 2); const size_t sp = ((size_t)(li * 32 + batch) * 128 + g) * 64 + c;
;                     hr[0] = P.in[I_SSRE][sp]; hi[0] = P.in[I_SSIM][sp]; hr[1] = P.in[I_SSRE][sp + 32]; hi[1] = P.in[I_SSIM][sp + 32]; }
;                 { const float t = lre[0] * hr[0] - lim[0] * hi[0] + d0[r]; hi[0] = lre[0] * hi[0] + lim[0] * hr[0] + d1[r]; hr[0] = t; }
;                 { const float t = lre[1] * hr[1] - lim[1] * hi[1] + d2[r]; hi[1] = lre[1] * hi[1] + lim[1] * hr[1] + d3[r]; hr[1] = t; }
;                 if (MODE >= 1) { u32x2 w; w.x = pk_bf16(hr[0], hi[0]); w.y = pk_bf16(hr[1], hi[1]); *(LAS u32x2*)(hs + (16 * half + r) * 272 + c * 8) = w; }
;                 if (MODE == 2 && (r & 3) == 3) { const int batch = 8 * cidx + 4 * half + (r >> 2); const size_t sp = ((size_t)(li * 32 + batch) * 128 + g) * 64 + c;
;                     P.out[O_SRES + sp] = hr[0]; P.out[O_SIMS + sp] = hi[0]; P.out[O_SRES + sp + 32] = hr[1]; P.out[O_SIMS + sp + 32] = hi[1]; }
;             }
;         }
;         if (MODE >= 1) {
;             lds_wave_sync();
; #pragma unroll
;             for (int rb = 0; rb < 2; ++rb) { f32x4 acc = {0.f, 0.f, 0.f, 0.f};
; #pragma unroll
;                 for (int kk = 0; kk < 4; ++kk) { const bf16x8 hf = *(const LAS bf16x8*)(hs + (16 * rb + fr) * 272 + (32 * kk + 8 * fq) * 2); acc = mfma16(Cf[kk], hf, acc); }
;                 const size_t rowg = (MODE == 2) ? (size_t)TP + 32 * cidx + 16 * rb + fr : (size_t)rb * SEQ + (size_t)cidx * 128 + blk * 16 + fr;
	v_fma_f32 v232, -v125, v136, v37
	v_fma_f32 v233, v125, v138, v5
	v_fma_f32 v234, -v127, v137, v53
	v_fma_f32 v235, v127, v139, v21
	v_fma_f32 v138, v124, v138, v232
	v_fma_f32 v136, v124, v136, v233
	v_fma_f32 v139, v126, v139, v234
	v_fma_f32 v137, v126, v137, v235
	v_cvt_pk_bf16_f32 v238, v138, v136
	v_cvt_pk_bf16_f32 v239, v139, v137
	ds_write_b64 v133, v[238:239] offset:1360
	v_fma_f32 v228, -v125, v136, v38
	v_fma_f32 v229, v125, v138, v6
	v_fma_f32 v230, -v127, v137, v54
	v_fma_f32 v231, v127, v139, v22
	v_fma_f32 v138, v124, v138, v228
	v_fma_f32 v136, v124, v136, v229
	v_fma_f32 v139, v126, v139, v230
	v_fma_f32 v137, v126, v137, v231
	v_cvt_pk_bf16_f32 v240, v138, v136
	v_cvt_pk_bf16_f32 v241, v139, v137
	ds_write_b64 v133, v[240:241] offset:1632
	v_fma_f32 v232, -v125, v136, v39
	v_fma_f32 v233, v125, v138, v7
	v_fma_f32 v234, -v127, v137, v55
	v_fma_f32 v235, v127, v139, v23
	v_fma_f32 v138, v124, v138, v232
	v_fma_f32 v136, v124, v136, v233
	v_fma_f32 v139, v126, v139, v234
	v_fma_f32 v137, v126, v137, v235
	v_cvt_pk_bf16_f32 v242, v138, v136
	v_cvt_pk_bf16_f32 v243, v139, v137
	ds_write_b64 v133, v[242:243] offset:1904
	v_fma_f32 v228, -v125, v136, v40
	v_fma_f32 v229, v125, v138, v8
	v_fma_f32 v230, -v127, v137, v56
	v_fma_f32 v231, v127, v139, v24
	v_fma_f32 v138, v124, v138, v228
	v_fma_f32 v136, v124, v136, v229
	v_fma_f32 v139, v126, v139, v230
	v_fma_f32 v137, v126, v137, v231
	v_cvt_pk_bf16_f32 v236, v138, v136
	v_cvt_pk_bf16_f32 v237, v139, v137
	ds_write_b64 v133, v[236:237] offset:2176
	v_fma_f32 v232, -v125, v136, v41
	v_fma_f32 v233, v125, v138, v9
	v_fma_f32 v234, -v127, v137, v57
	v_fma_f32 v235, v127, v139, v25
	v_fma_f32 v138, v124, v138, v232
	v_fma_f32 v136, v124, v136, v233
	v_fma_f32 v139, v126, v139, v234
	v_fma_f32 v137, v126, v137, v235
	v_cvt_pk_bf16_f32 v238, v138, v136
	v_cvt_pk_bf16_f32 v239, v139, v137
	ds_write_b64 v133, v[238:239] offset:2448
	v_fma_f32 v228, -v125, v136, v42
	v_fma_f32 v229, v125, v138, v10
	v_fma_f32 v230, -v127, v137, v58
	v_fma_f32 v231, v127, v139, v26
	v_fma_f32 v138, v124, v138, v228
	v_fma_f32 v136, v124, v136, v229
	v_fma_f32 v139, v126, v139, v230
	v_fma_f32 v137, v126, v137, v231
	v_cvt_pk_bf16_f32 v240, v138, v136
	v_cvt_pk_bf16_f32 v241, v139, v137
	ds_write_b64 v133, v[240:241] offset:2720
	v_fma_f32 v232, -v125, v136, v43
	v_fma_f32 v233, v125, v138, v11
	v_fma_f32 v234, -v127, v137, v59
	v_fma_f32 v235, v127, v139, v27
	v_fma_f32 v138, v124, v138, v232
	v_fma_f32 v136, v124, v136, v233
	v_fma_f32 v139, v126, v139, v234
	v_fma_f32 v137, v126, v137, v235
	v_cvt_pk_bf16_f32 v242, v138, v136
	v_cvt_pk_bf16_f32 v243, v139, v137
	ds_write_b64 v133, v[242:243] offset:2992
	v_fma_f32 v228, -v125, v136, v44
	v_fma_f32 v229, v125, v138, v12
	v_fma_f32 v230, -v127, v137, v60
	v_fma_f32 v231, v127, v139, v28
	v_fma_f32 v138, v124, v138, v228
	v_fma_f32 v136, v124, v136, v229
	v_fma_f32 v139, v126, v139, v230
	v_fma_f32 v137, v126, v137, v231
	v_cvt_pk_bf16_f32 v236, v138, v136
	v_cvt_pk_bf16_f32 v237, v139, v137
	ds_write_b64 v133, v[236:237] offset:3264
	v_fma_f32 v232, -v125, v136, v45
	v_fma_f32 v233, v125, v138, v13
	v_fma_f32 v234, -v127, v137, v61
	v_fma_f32 v235, v127, v139, v29
	v_fma_f32 v138, v124, v138, v232
	v_fma_f32 v136, v124, v136, v233
	v_fma_f32 v139, v126, v139, v234
	v_fma_f32 v137, v126, v137, v235
	v_cvt_pk_bf16_f32 v238, v138, v136
	v_cvt_pk_bf16_f32 v239, v139, v137
	ds_write_b64 v133, v[238:239] offset:3536
	v_fma_f32 v228, -v125, v136, v46
	v_fma_f32 v229, v125, v138, v14
	v_fma_f32 v230, -v127, v137, v62
	v_fma_f32 v231, v127, v139, v30
	v_fma_f32 v138, v124, v138, v228
	v_fma_f32 v136, v124, v136, v229
	v_fma_f32 v139, v126, v139, v230
	v_fma_f32 v137, v126, v137, v231
	v_cvt_pk_bf16_f32 v240, v138, v136
	v_cvt_pk_bf16_f32 v241, v139, v137
	ds_write_b64 v133, v[240:241] offset:3808
	v_fma_f32 v232, -v125, v136, v47
	v_fma_f32 v233, v125, v138, v15
	v_fma_f32 v234, -v127, v137, v63
	v_fma_f32 v235, v127, v139, v31
	v_fma_f32 v138, v124, v138, v232
	v_fma_f32 v136, v124, v136, v233
	v_fma_f32 v139, v126, v139, v234
	v_fma_f32 v137, v126, v137, v235
	v_cvt_pk_bf16_f32 v242, v138, v136
	v_cvt_pk_bf16_f32 v243, v139, v137
	ds_write_b64 v133, v[242:243] offset:4080
	s_waitcnt lgkmcnt(0)
	ds_read_b128 v[0:3], v152
	ds_read_b128 v[4:7], v152 offset:64
	s_waitcnt lgkmcnt(1)
	v_mfma_f32_16x16x32_bf16 v[0:3], v[80:83], v[0:3], 0
	s_waitcnt lgkmcnt(0)
	v_mfma_f32_16x16x32_bf16 v[0:3], v[84:87], v[4:7], v[0:3]
	ds_read_b128 v[4:7], v152 offset:128
	s_waitcnt lgkmcnt(0)
; #define LAS __attribute__((address_space(3)))
; __device__ __forceinline__ unsigned pk_bf16(float lo, float hi) { unsigned r; asm volatile("v_cvt_pk_bf16_f32 %0, %1, %2" : "=v"(r) : "v"(lo), "v"(hi)); return r; }
; __device__ __forceinline__ float bflo(unsigned w) { return __uint_as_float(w << 16); }
; __device__ __forceinline__ float bfhi(unsigned w) { return __uint_as_float(w & 0xffff0000u); }
; __device__ __forceinline__ float gelu_t(float x) { const float u = 0.7978845608028654f * (x + 0.044715f * x * x * x); return x / (1.0f + __expf(-2.0f * u)); }
; __device__ __forceinline__ f32x4 mfma16(bf16x8 a, bf16x8 b, f32x4 c) { return __builtin_amdgcn_mfma_f32_16x16x32_bf16(a, b, c, 0, 0, 0); }
; template <int MODE>
; __device__ __forceinline__ void ssm_unit(const Ctx& P, int li, int g, int cidx, LAS unsigned char* hs, const bf16_t* H, bf16_t* Z, float* E, int lane) {
;     ...
; #pragma unroll
;             for (int rb = 0; rb < 2; ++rb) { f32x4 acc = {0.f, 0.f, 0.f, 0.f};
; #pragma unroll
;                 for (int kk = 0; kk < 4; ++kk) { const bf16x8 hf = *(const LAS bf16x8*)(hs + (16 * rb + fr) * 272 + (32 * kk + 8 * fq) * 2); acc = mfma16(Cf[kk], hf, acc); }
;                 const size_t rowg = (MODE == 2) ? (size_t)TP + 32 * cidx + 16 * rb + fr : (size_t)rb * SEQ + (size_t)cidx * 128 + blk * 16 + fr;
;                 const size_t off = rowg * DM + g * 16 + 4 * fq;
;                 const u32x2 uw = *(const u32x2*)(H + off);
;                 const f32x4 dsk = *(const f32x4*)(P.in[I_SD] + (size_t)li * DM + g * 16 + 4 * fq);
;                 const float y0 = acc[0] + dsk[0] * bflo(uw.x), y1 = acc[1] + dsk[1] * bfhi(uw.x), y2 = acc[2] + dsk[2] * bflo(uw.y), y3 = acc[3] + dsk[3] * bfhi(uw.y);
;                 u32x2 w; w.x = pk_bf16(gelu_t(y0), gelu_t(y1)); w.y = pk_bf16(gelu_t(y2), gelu_t(y3));
;                 *(u32x2*)(Z + off) = w; }
;             lds_wave_sync();
;         }
;     }
;     if (MODE == 0) {
; #pragma unroll
;         for (int s = 0; s < 2; ++s) { float* ep = E + (((size_t)(half * 32 + cidx) * 128 + g) * 64 + c + 32 * s) * 2; ep[0] = hr[s]; ep[1] = hi[s]; }
;     }
;     if (MODE == 1 && cidx == 31) {
; #pragma unroll
;         for (int s = 0; s < 2; ++s) { const size_t sp = ((size_t)(li * 2 + half) * 128 + g) * 64 + c + 32 * s; P.out[O_SREP + sp] = hr[s]; P.out[O_SIMP + sp] = hi[s]; }
;     }
	v_mfma_f32_16x16x32_bf16 v[0:3], v[88:91], v[4:7], v[0:3]
	ds_read_b128 v[4:7], v152 offset:192
	s_waitcnt lgkmcnt(0)
	v_mfma_f32_16x16x32_bf16 v[0:3], v[92:95], v[4:7], v[0:3]
	v_lshl_add_u64 v[4:5], v[148:149], 0, s[0:1]
	s_mov_b32 s24, 0x1c500000
	s_waitcnt vmcnt(2)
	v_mov_b64_e32 v[10:11], v[224:225]
	v_mov_b64_e32 v[6:7], v[216:217]
	v_mov_b64_e32 v[8:9], v[218:219]
	s_add_u32 s0, s0, 0x10000
	s_addc_u32 s1, s1, 0
	s_cmp_eq_u32 s0, 0x80000
	s_nop 1
	v_lshlrev_b32_e32 v12, 16, v10
	v_fma_f32 v0, v6, v12, v0
	v_and_b32_e32 v6, 0xffff0000, v10
	v_fma_f32 v1, v7, v6, v1
	v_lshlrev_b32_e32 v6, 16, v11
	v_fma_f32 v2, v8, v6, v2
	v_and_b32_e32 v6, 0xffff0000, v11
	v_fmac_f32_e32 v3, v9, v6
	v_mul_f32_e32 v6, 0x3d372713, v0
	v_mul_f32_e32 v6, v0, v6
	v_fma_f32 v6, v0, v6, v0
	v_mul_f32_e32 v6, 0xc0135761, v6
	v_exp_f32_e32 v6, v6
	s_nop 0
	v_add_f32_e32 v6, 1.0, v6
	v_rcp_f32_e32 v8, v6
	s_nop 0
	v_mul_f32_e32 v0, v0, v8
	v_mul_f32_e32 v6, 0x3d372713, v1
	v_mul_f32_e32 v6, v1, v6
	v_fma_f32 v6, v1, v6, v1
	v_mul_f32_e32 v6, 0xc0135761, v6
	v_exp_f32_e32 v6, v6
	s_nop 0
	v_add_f32_e32 v6, 1.0, v6
	v_rcp_f32_e32 v8, v6
	s_nop 0
	v_mul_f32_e32 v1, v1, v8
	v_cvt_pk_bf16_f32 v0, v0, v1
	v_mul_f32_e32 v1, 0x3d372713, v2
	v_mul_f32_e32 v1, v2, v1
	v_fma_f32 v1, v2, v1, v2
	v_mul_f32_e32 v1, 0xc0135761, v1
	v_exp_f32_e32 v1, v1
	s_nop 0
	v_add_f32_e32 v1, 1.0, v1
	v_rcp_f32_e32 v7, v1
	s_nop 0
	v_mul_f32_e32 v1, v2, v7
	v_mul_f32_e32 v2, 0x3d372713, v3
	v_mul_f32_e32 v2, v3, v2
	v_fma_f32 v2, v3, v2, v3
	v_mul_f32_e32 v2, 0xc0135761, v2
	v_exp_f32_e32 v2, v2
	s_nop 0
	v_add_f32_e32 v2, 1.0, v2
	v_rcp_f32_e32 v7, v2
	s_nop 0
	v_mul_f32_e32 v2, v3, v7
	v_cvt_pk_bf16_f32 v1, v1, v2
	v_add_co_u32_e32 v2, vcc, s24, v4
	ds_read_b128 v[6:9], v152 offset:4416
	s_nop 0
	v_addc_co_u32_e32 v3, vcc, 0, v5, vcc
	global_store_dwordx2 v[2:3], v[0:1], off
	ds_read_b128 v[0:3], v152 offset:4352
	s_waitcnt lgkmcnt(0)
	v_mfma_f32_16x16x32_bf16 v[0:3], v[80:83], v[0:3], 0
	s_mov_b32 s24, 0x17200000
	v_mfma_f32_16x16x32_bf16 v[0:3], v[84:87], v[6:9], v[0:3]
	ds_read_b128 v[6:9], v152 offset:4480
	s_waitcnt lgkmcnt(0)
	v_mfma_f32_16x16x32_bf16 v[0:3], v[88:91], v[6:9], v[0:3]
	ds_read_b128 v[6:9], v152 offset:4544
	s_waitcnt lgkmcnt(0)
	v_mfma_f32_16x16x32_bf16 v[0:3], v[92:95], v[6:9], v[0:3]
	s_mov_b32 s24, 0x1d500000
	s_waitcnt vmcnt(2)
	v_mov_b64_e32 v[10:11], v[226:227]
	v_mov_b64_e32 v[6:7], v[216:217]
	v_mov_b64_e32 v[8:9], v[218:219]
	s_nop 3
	v_lshlrev_b32_e32 v12, 16, v10
	v_fma_f32 v0, v6, v12, v0
	v_and_b32_e32 v6, 0xffff0000, v10
	v_fma_f32 v1, v7, v6, v1
	v_lshlrev_b32_e32 v6, 16, v11
	v_fma_f32 v2, v8, v6, v2
	v_and_b32_e32 v6, 0xffff0000, v11
	v_fmac_f32_e32 v3, v9, v6
	v_mul_f32_e32 v6, 0x3d372713, v0
	v_mul_f32_e32 v6, v0, v6
	v_fma_f32 v6, v0, v6, v0
	v_mul_f32_e32 v6, 0xc0135761, v6
	v_exp_f32_e32 v6, v6
	s_nop 0
	v_add_f32_e32 v6, 1.0, v6
	v_rcp_f32_e32 v8, v6
	s_nop 0
	v_mul_f32_e32 v0, v0, v8
	v_mul_f32_e32 v6, 0x3d372713, v1
	v_mul_f32_e32 v6, v1, v6
	v_fma_f32 v6, v1, v6, v1
	v_mul_f32_e32 v6, 0xc0135761, v6
	v_exp_f32_e32 v6, v6
	s_nop 0
	v_add_f32_e32 v6, 1.0, v6
	v_rcp_f32_e32 v8, v6
	s_nop 0
	v_mul_f32_e32 v1, v1, v8
	v_cvt_pk_bf16_f32 v0, v0, v1
	v_mul_f32_e32 v1, 0x3d372713, v2
	v_mul_f32_e32 v1, v2, v1
	v_fma_f32 v1, v2, v1, v2
	v_mul_f32_e32 v1, 0xc0135761, v1
	v_exp_f32_e32 v1, v1
	s_nop 0
	v_add_f32_e32 v1, 1.0, v1
	v_rcp_f32_e32 v7, v1
	s_nop 0
	v_mul_f32_e32 v1, v2, v7
	v_mul_f32_e32 v2, 0x3d372713, v3
	v_mul_f32_e32 v2, v3, v2
	v_fma_f32 v2, v3, v2, v3
	v_mul_f32_e32 v2, 0xc0135761, v2
	v_exp_f32_e32 v2, v2
	s_nop 0
	v_add_f32_e32 v2, 1.0, v2
	v_rcp_f32_e32 v7, v2
	s_nop 0
	v_mul_f32_e32 v2, v3, v7
	v_cvt_pk_bf16_f32 v1, v1, v2
	v_add_co_u32_e32 v2, vcc, s24, v4
	s_nop 1
	v_addc_co_u32_e32 v3, vcc, 0, v5, vcc
	global_store_dwordx2 v[2:3], v[0:1], off
	s_waitcnt lgkmcnt(0)
	s_waitcnt vmcnt(2)
	s_cbranch_scc0 .LBB0_87
	v_cmp_eq_u32_e32 vcc, 31, v122
	s_and_saveexec_b64 s[0:1], vcc
	s_cbranch_execz .LBB0_65
	v_lshlrev_b32_e32 v128, 8, v153
	v_lshl_add_u64 v[0:1], v[110:111], 0, v[128:129]
	v_add_co_u32_e32 v2, vcc, 0x6b80000, v0
	s_nop 1
	v_addc_co_u32_e32 v3, vcc, 0, v1, vcc
	v_add_co_u32_e32 v0, vcc, 0x6da0000, v0
	global_store_dword v[2:3], v138, off
	s_nop 0
	v_addc_co_u32_e32 v1, vcc, 0, v1, vcc
	global_store_dword v[0:1], v136, off
	global_store_dword v[2:3], v139, off offset:128
	global_store_dword v[0:1], v137, off offset:128
	s_branch .LBB0_65

; __device__ __forceinline__ unsigned pk_bf16(float lo, float hi) { unsigned r; asm volatile("v_cvt_pk_bf16_f32 %0, %1, %2" : "=v"(r) : "v"(lo), "v"(hi)); return r; }
; template <int MODE>
; __device__ __forceinline__ void ssm_unit(const Ctx& P, int li, int g, int cidx, LAS unsigned char* hs, const bf16_t* H, bf16_t* Z, float* E, int lane) {
;     ...
;     const float delta = __expf(P.in[I_LSTEP][li * 128 + g]);
;     float lre[2], lim[2];
;     bf16x8 Bf[4];
; #pragma unroll
;     for (int s = 0; s < 2; ++s) { const int p = c + 32 * s; const size_t gp = (size_t)(li * 128 + g) * 64 + p;
;         const float ar = P.in[I_LRE][gp], ai = P.in[I_LIM][gp];
;         const float mag = __expf(ar * delta); float rev = ai * delta * 0.15915494309189535f; rev -= rintf(rev);
;         const float sn = __builtin_amdgcn_sinf(rev), cs = __builtin_amdgcn_cosf(rev);
;         lre[s] = mag * cs; lim[s] = mag * sn;
;         const float nr = lre[s] - 1.0f, ni = lim[s], den = 1.0f / (ar * ar + ai * ai);
;         const float cre = (nr * ar + ni * ai) * den, cim = (ni * ar - nr * ai) * den;
;         const float* brp = P.in[I_BRE] + gp * 16 + 8 * half; const float* bip = P.in[I_BIM] + gp * 16 + 8 * half;
;         const f32x4 br0 = *(const f32x4*)brp, br1 = *(const f32x4*)(brp + 4), bi0 = *(const f32x4*)bip, bi1 = *(const f32x4*)(bip + 4);
;         u32x4 wr_, wi_;
;         wr_.x = pk_bf16(cre * br0[0] - cim * bi0[0], cre * br0[1] - cim * bi0[1]); wr_.y = pk_bf16(cre * br0[2] - cim * bi0[2], cre * br0[3] - cim * bi0[3]);
;         wr_.z = pk_bf16(cre * br1[0] - cim * bi1[0], cre * br1[1] - cim * bi1[1]); wr_.w = pk_bf16(cre * br1[2] - cim * bi1[2], cre * br1[3] - cim * bi1[3]);
;         wi_.x = pk_bf16(cre * bi0[0] + cim * br0[0], cre * bi0[1] + cim * br0[1]); wi_.y = pk_bf16(cre * bi0[2] + cim * br0[2], cre * bi0[3] + cim * br0[3]);
;         wi_.z = pk_bf16(cre * bi1[0] + cim * br1[0], cre * bi1[1] + cim * br1[1]); wi_.w = pk_bf16(cre * bi1[2] + cim * br1[2], cre * bi1[3] + cim * br1[3]);
;         Bf[2 * s] = __builtin_bit_cast(bf16x8, wr_); Bf[2 * s + 1] = __builtin_bit_cast(bf16x8, wi_); }
.LBB0_100:
	s_movk_i32 s24, 0xfff
	v_and_b32_e32 v134, 0x7f, v85
	v_cmp_lt_i32_e32 vcc, s24, v85
	v_or_b32_e32 v4, s3, v134
	s_and_saveexec_b64 s[40:41], vcc
	s_xor_b64 s[40:41], exec, s[40:41]
	s_cbranch_execz .LBB0_102
	v_readlane_b32 s44, v253, 13
	v_add_u32_e32 v0, 0xfffff000, v85
	v_ashrrev_i32_e32 v5, 31, v4
	v_readlane_b32 s46, v253, 15
	v_readlane_b32 s47, v253, 16
	v_lshrrev_b32_e32 v37, 7, v0
	s_waitcnt vmcnt(6)
	v_lshlrev_b64 v[22:23], 6, v[4:5]
	v_lshl_add_u64 v[0:1], v[4:5], 2, s[46:47]
	global_load_dword v0, v[0:1], off
	v_or_b32_e32 v6, v22, v84
	v_mov_b32_e32 v7, v23
	v_lshlrev_b64 v[2:3], 2, v[6:7]
	v_readlane_b32 s45, v253, 14
	v_lshlrev_b64 v[6:7], 6, v[6:7]
	v_lshl_add_u64 v[18:19], v[94:95], 0, v[6:7]
	v_lshl_add_u32 v119, v37, 5, v165
	v_lshlrev_b64 v[4:5], 12, v[4:5]
	v_lshl_or_b32 v4, v88, 2, v4
	v_lshl_add_u64 v[32:33], v[98:99], 0, v[4:5]
	s_waitcnt vmcnt(5)
	v_lshl_add_u64 v[30:31], v[100:101], 0, v[4:5]
	v_or_b32_e32 v22, v22, v86
	v_lshl_add_u32 v108, v37, 3, v126
	v_readlane_b32 s48, v253, 17
	v_readlane_b32 s49, v253, 18
	v_readlane_b32 s50, v253, 19
	v_readlane_b32 s51, v253, 20
	v_readlane_b32 s52, v253, 21
	v_readlane_b32 s53, v253, 22
	v_readlane_b32 s54, v253, 23
	v_readlane_b32 s55, v253, 24
	v_readlane_b32 s56, v253, 25
	v_readlane_b32 s57, v253, 26
	v_readlane_b32 s58, v253, 27
	v_readlane_b32 s59, v253, 28
	v_lshlrev_b64 v[24:25], 2, v[22:23]
	v_mov_b32_e32 v105, v129
	v_ashrrev_i32_e32 v109, 31, v108
	v_lshl_add_u64 v[34:35], s[44:45], 0, v[24:25]
	v_lshlrev_b64 v[112:113], 15, v[108:109]
	v_lshl_add_u64 v[26:27], s[78:79], 0, v[24:25]
	v_lshlrev_b64 v[24:25], 6, v[22:23]
	v_lshl_add_u64 v[22:23], v[92:93], 0, v[24:25]
	v_lshl_add_u64 v[24:25], v[94:95], 0, v[24:25]
	v_lshlrev_b32_e32 v118, 4, v134
	s_waitcnt vmcnt(0)
	v_mul_f32_e32 v0, 0x3fb8aa3b, v0
	v_exp_f32_e32 v38, v0
	v_lshl_add_u64 v[0:1], s[78:79], 0, v[2:3]
	global_load_dword v0, v[0:1], off
	v_lshl_add_u64 v[2:3], s[44:45], 0, v[2:3]
	global_load_dword v1, v[2:3], off
	v_readlane_b32 s44, v254, 51
	v_readlane_b32 s54, v254, 61
	v_readlane_b32 s55, v254, 62
	v_readlane_b32 s56, v254, 63
	v_readlane_b32 s57, v252, 0
	v_readlane_b32 s45, v254, 52
	v_readlane_b32 s46, v254, 53
	v_readlane_b32 s47, v254, 54
	v_readlane_b32 s48, v254, 55
	v_readlane_b32 s49, v254, 56
	v_readlane_b32 s50, v254, 57
	v_readlane_b32 s51, v254, 58
	v_readlane_b32 s52, v254, 59
	v_readlane_b32 s53, v254, 60
	v_readlane_b32 s58, v252, 1
	v_readlane_b32 s59, v252, 2
	s_waitcnt vmcnt(1)
	v_mul_f32_e32 v2, v0, v38
	v_mul_f32_e32 v2, 0x3fb8aa3b, v2
	v_exp_f32_e32 v36, v2
	s_waitcnt vmcnt(0)
	v_mul_f32_e32 v2, v38, v1
	v_mul_f32_e32 v3, 0.15915494, v2
	v_rndne_f32_e32 v3, v3
	v_fma_f32 v2, v2, 0.15915494, -v3
	v_sin_f32_e32 v41, v2
	v_cos_f32_e32 v40, v2
	v_pk_mul_f32 v[2:3], v[0:1], v[0:1]
	v_pk_mul_f32 v[106:107], v[36:37], v[40:41] op_sel_hi:[0,1]
	v_add_f32_e32 v2, v2, v3
	v_div_scale_f32 v3, s[42:43], v2, v2, 1.0
	v_rcp_f32_e32 v8, v3
	v_mov_b32_e32 v40, v1
	v_mov_b32_e32 v41, v0
	v_mov_b32_e32 v36, v1
	v_fma_f32 v9, -v3, v8, 1.0
	v_fmac_f32_e32 v8, v9, v8
	v_div_scale_f32 v9, vcc, 1.0, v2, 1.0
	v_mul_f32_e32 v10, v9, v8
	v_fma_f32 v11, -v3, v10, v9
	v_fmac_f32_e32 v10, v11, v8
	v_fma_f32 v3, -v3, v10, v9
	v_div_fmas_f32 v3, v3, v8, v10
	v_lshl_add_u64 v[10:11], v[92:93], 0, v[6:7]
	global_load_dwordx4 v[6:9], v[10:11], off offset:16
	global_load_dwordx4 v[14:17], v[10:11], off
	s_nop 0
	global_load_dwordx4 v[10:13], v[18:19], off offset:16
	s_nop 0
	global_load_dwordx4 v[18:21], v[18:19], off
	v_div_fixup_f32 v2, v3, v2, 1.0
	v_or_b32_e32 v3, v119, v89
	v_lshlrev_b32_e32 v128, 12, v3
	v_lshl_add_u64 v[4:5], s[6:7], 0, v[128:129]
	v_lshlrev_b32_e32 v128, 5, v134
	v_lshl_add_u64 v[4:5], v[4:5], 0, v[128:129]
	v_lshlrev_b32_e32 v128, 6, v134
	v_or_b32_e32 v3, v128, v84
	v_lshl_add_u64 v[28:29], v[4:5], 0, v[104:105]
	v_lshlrev_b32_e32 v105, 2, v3
	v_or_b32_e32 v4, v112, v105
	v_mov_b32_e32 v5, v113
	v_lshl_add_u64 v[116:117], s[56:57], 0, v[4:5]
	v_lshl_add_u64 v[114:115], s[54:55], 0, v[4:5]
	v_add_f32_e32 v4, -1.0, v106
	v_pk_mul_f32 v[0:1], v[40:41], v[4:5] op_sel:[1,0] op_sel_hi:[0,0]
	v_pk_fma_f32 v[4:5], v[36:37], v[106:107], v[0:1] op_sel:[0,1,0]
	v_pk_fma_f32 v[0:1], v[40:41], v[106:107], v[0:1] op_sel:[0,1,0] neg_lo:[0,0,1] neg_hi:[0,0,1]
	s_nop 0
	v_mov_b32_e32 v5, v1
	v_pk_mul_f32 v[36:37], v[2:3], v[4:5] op_sel_hi:[0,1]
	s_waitcnt vmcnt(2)
	v_mov_b32_e32 v0, v14
	s_waitcnt vmcnt(1)
	v_mov_b32_e32 v5, v12
	s_waitcnt vmcnt(0)
	v_mov_b32_e32 v1, v18
	v_pk_mul_f32 v[0:1], v[0:1], v[36:37]
	v_mov_b32_e32 v3, v20
	v_sub_f32_e32 v2, v0, v1
	v_mov_b32_e32 v0, v15
	v_mov_b32_e32 v1, v19
	v_pk_mul_f32 v[0:1], v[0:1], v[36:37]
	s_nop 0
	v_sub_f32_e32 v0, v0, v1
	v_cvt_pk_bf16_f32 v0, v2, v0
	v_mov_b32_e32 v2, v16
	v_pk_mul_f32 v[2:3], v[2:3], v[36:37]
	s_nop 0
	v_sub_f32_e32 v1, v2, v3
	v_mov_b32_e32 v2, v17
	v_mov_b32_e32 v3, v21
	v_pk_mul_f32 v[2:3], v[2:3], v[36:37]
	s_nop 0
	v_sub_f32_e32 v2, v2, v3
	v_cvt_pk_bf16_f32 v1, v1, v2
	v_mov_b32_e32 v2, v6
	v_mov_b32_e32 v3, v10
	v_pk_mul_f32 v[2:3], v[2:3], v[36:37]
	s_nop 0
	v_sub_f32_e32 v4, v2, v3
	v_mov_b32_e32 v2, v7
	v_mov_b32_e32 v3, v11
	v_pk_mul_f32 v[2:3], v[2:3], v[36:37]
	s_nop 0
	v_sub_f32_e32 v2, v2, v3
	v_cvt_pk_bf16_f32 v2, v4, v2
	v_mov_b32_e32 v4, v8
	v_pk_mul_f32 v[4:5], v[4:5], v[36:37]
	s_nop 0
	v_sub_f32_e32 v3, v4, v5
	v_mov_b32_e32 v4, v9
	v_mov_b32_e32 v5, v13
	v_pk_mul_f32 v[4:5], v[4:5], v[36:37]
	s_nop 0
	v_sub_f32_e32 v4, v4, v5
	v_cvt_pk_bf16_f32 v3, v3, v4
	v_mov_b32_e32 v4, v18
	v_mov_b32_e32 v5, v14
	v_pk_mul_f32 v[4:5], v[4:5], v[36:37]
	v_mov_b32_e32 v14, v19
	v_add_f32_e32 v18, v4, v5
	v_pk_mul_f32 v[4:5], v[14:15], v[36:37]
	v_mov_b32_e32 v14, v20
	v_mov_b32_e32 v15, v16
	v_pk_mul_f32 v[14:15], v[14:15], v[36:37]
	v_mov_b32_e32 v16, v21
	v_add_f32_e32 v4, v4, v5
	v_add_f32_e32 v5, v14, v15
	v_pk_mul_f32 v[14:15], v[16:17], v[36:37]
	v_cvt_pk_bf16_f32 v4, v18, v4
	s_nop 0
	v_add_f32_e32 v14, v14, v15
	v_cvt_pk_bf16_f32 v5, v5, v14
	v_mov_b32_e32 v14, v10
	v_mov_b32_e32 v15, v6
	v_mov_b32_e32 v6, v11
	v_pk_mul_f32 v[14:15], v[14:15], v[36:37]
	v_pk_mul_f32 v[6:7], v[6:7], v[36:37]
	v_add_f32_e32 v10, v14, v15
	v_add_f32_e32 v6, v6, v7
	v_cvt_pk_bf16_f32 v6, v10, v6
	v_mov_b32_e32 v10, v12
	v_mov_b32_e32 v11, v8
	v_mov_b32_e32 v8, v13
	v_pk_mul_f32 v[10:11], v[10:11], v[36:37]
	v_pk_mul_f32 v[8:9], v[8:9], v[36:37]
	v_add_f32_e32 v7, v10, v11
	v_add_f32_e32 v8, v8, v9
	v_cvt_pk_bf16_f32 v7, v7, v8
	global_load_dword v8, v[26:27], off
	global_load_dword v9, v[34:35], off
	s_waitcnt vmcnt(1)
; template <int MODE>
; __device__ __forceinline__ void ssm_unit(const Ctx& P, int li, int g, int cidx, LAS unsigned char* hs, const bf16_t* H, bf16_t* Z, float* E, int lane) {
;     ...
;     for (int s = 0; s < 2; ++s) { const int p = c + 32 * s; const size_t gp = (size_t)(li * 128 + g) * 64 + p;
;         const float ar = P.in[I_LRE][gp], ai = P.in[I_LIM][gp];
;         const float mag = __expf(ar * delta); float rev = ai * delta * 0.15915494309189535f; rev -= rintf(rev);
;         const float sn = __builtin_amdgcn_sinf(rev), cs = __builtin_amdgcn_cosf(rev);
;         lre[s] = mag * cs; lim[s] = mag * sn;
;         const float nr = lre[s] - 1.0f, ni = lim[s], den = 1.0f / (ar * ar + ai * ai);
;         const float cre = (nr * ar + ni * ai) * den, cim = (ni * ar - nr * ai) * den;
;         const float* brp = P.in[I_BRE] + gp * 16 + 8 * half; const float* bip = P.in[I_BIM] + gp * 16 + 8 * half;
;         const f32x4 br0 = *(const f32x4*)brp, br1 = *(const f32x4*)(brp + 4), bi0 = *(const f32x4*)bip, bi1 = *(const f32x4*)(bip + 4);
;         u32x4 wr_, wi_;
;         wr_.x = pk_bf16(cre * br0[0] - cim * bi0[0], cre * br0[1] - cim * bi0[1]); wr_.y = pk_bf16(cre * br0[2] - cim * bi0[2], cre * br0[3] - cim * bi0[3]);
;         wr_.z = pk_bf16(cre * br1[0] - cim * bi1[0], cre * br1[1] - cim * bi1[1]); wr_.w = pk_bf16(cre * br1[2] - cim * bi1[2], cre * br1[3] - cim * bi1[3]);
;         wi_.x = pk_bf16(cre * bi0[0] + cim * br0[0], cre * bi0[1] + cim * br0[1]); wi_.y = pk_bf16(cre * bi0[2] + cim * br0[2], cre * bi0[3] + cim * br0[3]);
;         wi_.z = pk_bf16(cre * bi1[0] + cim * br1[0], cre * bi1[1] + cim * br1[1]); wi_.w = pk_bf16(cre * bi1[2] + cim * br1[2], cre * bi1[3] + cim * br1[3]);
;         Bf[2 * s] = __builtin_bit_cast(bf16x8, wr_); Bf[2 * s + 1] = __builtin_bit_cast(bf16x8, wi_); }
;     float hr[2] = {0.f, 0.f}, hi[2] = {0.f, 0.f};
;     if (MODE == 1) {
; #pragma unroll
;         for (int s = 0; s < 2; ++s) { float pr = lre[s], pi = lim[s];
; #pragma unroll
;             for (int q = 0; q < 7; ++q) { const float t = pr * pr - pi * pi; pi = 2.0f * pr * pi; pr = t; }
;             const int p = c + 32 * s;
; #pragma unroll 8
;             for (int j = 0; j < cidx; ++j) { const float* ep = E + (((size_t)(half * 32 + j) * 128 + g) * 64 + p) * 2; const float er = ep[0], ei = ep[1];
	v_mul_f32_e32 v10, v38, v8
	s_waitcnt vmcnt(0)
	v_mul_f32_e32 v11, v38, v9
	v_mul_f32_e32 v12, 0.15915494, v11
	v_rndne_f32_e32 v12, v12
	v_fma_f32 v11, v11, 0.15915494, -v12
	v_pk_mul_f32 v[12:13], v[8:9], v[8:9]
	v_sin_f32_e32 v35, v11
	v_cos_f32_e32 v34, v11
	v_add_f32_e32 v11, v12, v13
	v_div_scale_f32 v12, s[42:43], v11, v11, 1.0
	v_rcp_f32_e32 v13, v12
	v_mul_f32_e32 v10, 0x3fb8aa3b, v10
	v_exp_f32_e32 v10, v10
	v_mov_b32_e32 v38, v9
	v_fma_f32 v14, -v12, v13, 1.0
	v_fmac_f32_e32 v13, v14, v13
	v_div_scale_f32 v14, vcc, 1.0, v11, 1.0
	v_mul_f32_e32 v15, v14, v13
	v_fma_f32 v16, -v12, v15, v14
	v_fmac_f32_e32 v15, v16, v13
	v_fma_f32 v12, -v12, v15, v14
	v_div_fmas_f32 v12, v12, v13, v15
	v_div_fixup_f32 v36, v12, v11, 1.0
	global_load_dwordx4 v[12:15], v[22:23], off offset:16
	s_nop 0
	global_load_dwordx4 v[20:23], v[22:23], off
	s_nop 0
	global_load_dwordx4 v[16:19], v[24:25], off offset:16
	s_nop 0
	global_load_dwordx4 v[24:27], v[24:25], off
	v_pk_mul_f32 v[110:111], v[10:11], v[34:35] op_sel_hi:[0,1]
	v_add_f32_e32 v10, -1.0, v110
	v_mov_b32_e32 v39, v8
	v_mov_b32_e32 v34, v9
	v_pk_mul_f32 v[8:9], v[38:39], v[10:11] op_sel:[1,0] op_sel_hi:[0,0]
	v_pk_fma_f32 v[10:11], v[34:35], v[110:111], v[8:9] op_sel:[0,1,0]
	v_pk_fma_f32 v[8:9], v[38:39], v[110:111], v[8:9] op_sel:[0,1,0] neg_lo:[0,0,1] neg_hi:[0,0,1]
	s_nop 0
	v_mov_b32_e32 v11, v9
	v_pk_mul_f32 v[34:35], v[36:37], v[10:11] op_sel_hi:[0,1]
	s_waitcnt vmcnt(2)
	v_mov_b32_e32 v8, v20
	s_waitcnt vmcnt(1)
	v_mov_b32_e32 v37, v18
	s_waitcnt vmcnt(0)
	v_mov_b32_e32 v9, v24
	v_pk_mul_f32 v[8:9], v[8:9], v[34:35]
	v_mov_b32_e32 v11, v26
	v_sub_f32_e32 v10, v8, v9
	v_mov_b32_e32 v8, v21
	v_mov_b32_e32 v9, v25
	v_pk_mul_f32 v[8:9], v[8:9], v[34:35]
	s_nop 0
	v_sub_f32_e32 v8, v8, v9
	v_cvt_pk_bf16_f32 v8, v10, v8
	v_mov_b32_e32 v10, v22
	v_pk_mul_f32 v[10:11], v[10:11], v[34:35]
	s_nop 0
	v_sub_f32_e32 v9, v10, v11
	v_mov_b32_e32 v10, v23
	v_mov_b32_e32 v11, v27
	v_pk_mul_f32 v[10:11], v[10:11], v[34:35]
	s_nop 0
	v_sub_f32_e32 v10, v10, v11
	v_cvt_pk_bf16_f32 v9, v9, v10
	v_mov_b32_e32 v10, v12
	v_mov_b32_e32 v11, v16
	v_pk_mul_f32 v[10:11], v[10:11], v[34:35]
	s_nop 0
	v_sub_f32_e32 v36, v10, v11
	v_mov_b32_e32 v10, v13
	v_mov_b32_e32 v11, v17
	v_pk_mul_f32 v[10:11], v[10:11], v[34:35]
	s_nop 0
	v_sub_f32_e32 v10, v10, v11
	v_cvt_pk_bf16_f32 v10, v36, v10
	v_mov_b32_e32 v36, v14
	v_pk_mul_f32 v[36:37], v[36:37], v[34:35]
	s_nop 0
	v_sub_f32_e32 v11, v36, v37
	v_mov_b32_e32 v36, v15
	v_mov_b32_e32 v37, v19
	v_pk_mul_f32 v[36:37], v[36:37], v[34:35]
	s_nop 0
	v_sub_f32_e32 v36, v36, v37
	v_mov_b32_e32 v37, v20
	v_mov_b32_e32 v20, v25
	v_cvt_pk_bf16_f32 v11, v11, v36
	v_mov_b32_e32 v36, v24
	v_pk_mul_f32 v[20:21], v[20:21], v[34:35]
	v_pk_mul_f32 v[36:37], v[36:37], v[34:35]
	v_add_f32_e32 v20, v20, v21
	v_add_f32_e32 v24, v36, v37
	v_cvt_pk_bf16_f32 v80, v24, v20
	v_mov_b32_e32 v20, v26
	v_mov_b32_e32 v21, v22
	v_pk_mul_f32 v[20:21], v[20:21], v[34:35]
	v_mov_b32_e32 v22, v27
	v_add_f32_e32 v24, v20, v21
	v_pk_mul_f32 v[20:21], v[22:23], v[34:35]
	s_nop 0
	v_add_f32_e32 v20, v20, v21
	v_mov_b32_e32 v21, v12
	v_mov_b32_e32 v12, v17
	v_cvt_pk_bf16_f32 v81, v24, v20
	v_mov_b32_e32 v20, v16
	v_pk_mul_f32 v[12:13], v[12:13], v[34:35]
	v_pk_mul_f32 v[20:21], v[20:21], v[34:35]
	v_add_f32_e32 v12, v12, v13
	v_add_f32_e32 v16, v20, v21
	v_cvt_pk_bf16_f32 v82, v16, v12
	v_mov_b32_e32 v12, v18
	v_mov_b32_e32 v13, v14
	v_pk_mul_f32 v[12:13], v[12:13], v[34:35]
	v_mov_b32_e32 v14, v19
	v_add_f32_e32 v16, v12, v13
	v_pk_mul_f32 v[12:13], v[14:15], v[34:35]
	s_nop 0
	v_add_f32_e32 v12, v12, v13
	v_cvt_pk_bf16_f32 v83, v16, v12
	global_load_dwordx2 v[12:13], v[32:33], off
	global_load_dwordx2 v[14:15], v[32:33], off offset:128
	global_load_dwordx2 v[16:17], v[30:31], off
	global_load_dwordx2 v[18:19], v[30:31], off offset:128
	s_waitcnt vmcnt(1)
	v_xor_b32_e32 v16, 0x80000000, v16
	v_cvt_pk_bf16_f32 v64, v12, v16
	s_waitcnt vmcnt(0)
	v_xor_b32_e32 v12, 0x80000000, v18
	v_cvt_pk_bf16_f32 v65, v14, v12
	v_xor_b32_e32 v12, 0x80000000, v17
	v_cvt_pk_bf16_f32 v66, v13, v12
	v_xor_b32_e32 v12, 0x80000000, v19
	v_cvt_pk_bf16_f32 v67, v15, v12
	global_load_dwordx2 v[12:13], v[32:33], off offset:32
	global_load_dwordx2 v[14:15], v[32:33], off offset:160
	global_load_dwordx2 v[16:17], v[30:31], off offset:32
	global_load_dwordx2 v[18:19], v[30:31], off offset:160
	s_waitcnt vmcnt(1)
	v_xor_b32_e32 v16, 0x80000000, v16
	v_cvt_pk_bf16_f32 v68, v12, v16
	s_waitcnt vmcnt(0)
	v_xor_b32_e32 v12, 0x80000000, v18
	v_cvt_pk_bf16_f32 v69, v14, v12
	v_xor_b32_e32 v12, 0x80000000, v17
	v_cvt_pk_bf16_f32 v70, v13, v12
	v_xor_b32_e32 v12, 0x80000000, v19
	v_cvt_pk_bf16_f32 v71, v15, v12
	global_load_dwordx2 v[12:13], v[32:33], off offset:64
	global_load_dwordx2 v[14:15], v[32:33], off offset:192
	global_load_dwordx2 v[16:17], v[30:31], off offset:64
	global_load_dwordx2 v[18:19], v[30:31], off offset:192
	s_waitcnt vmcnt(1)
	v_xor_b32_e32 v16, 0x80000000, v16
	v_cvt_pk_bf16_f32 v72, v12, v16
	s_waitcnt vmcnt(0)
	v_xor_b32_e32 v12, 0x80000000, v18
	v_cvt_pk_bf16_f32 v73, v14, v12
	v_xor_b32_e32 v12, 0x80000000, v17
	v_cvt_pk_bf16_f32 v74, v13, v12
	v_xor_b32_e32 v12, 0x80000000, v19
	v_cvt_pk_bf16_f32 v75, v15, v12
	global_load_dwordx2 v[12:13], v[32:33], off offset:96
	global_load_dwordx2 v[14:15], v[32:33], off offset:224
	global_load_dwordx2 v[16:17], v[30:31], off offset:96
	global_load_dwordx2 v[18:19], v[30:31], off offset:224
	s_waitcnt vmcnt(1)
	v_xor_b32_e32 v16, 0x80000000, v16
	v_cvt_pk_bf16_f32 v76, v12, v16
	s_waitcnt vmcnt(0)
; #define LAS __attribute__((address_space(3)))
; __device__ __forceinline__ unsigned pk_bf16(float lo, float hi) { unsigned r; asm volatile("v_cvt_pk_bf16_f32 %0, %1, %2" : "=v"(r) : "v"(lo), "v"(hi)); return r; }
; __device__ __forceinline__ f32x16 mfma32(bf16x8 a, bf16x8 b, f32x16 c) { return __builtin_amdgcn_mfma_f32_32x32x16_bf16(a, b, c, 0, 0, 0); }
; template <int MODE>
; __device__ __forceinline__ void ssm_unit(const Ctx& P, int li, int g, int cidx, LAS unsigned char* hs, const bf16_t* H, bf16_t* Z, float* E, int lane) {
;     ...
;     for (int blk = 0; blk < nblk; ++blk) {
;         {   const int bsel = (c >> 2) & 1, tj = (c & 3) + 4 * (c >> 3);
;             const size_t rowg = (MODE == 2) ? (size_t)TP + 32 * cidx + 16 * bsel + tj : (size_t)bsel * SEQ + (size_t)cidx * 128 + blk * 16 + tj;
;             const bf16x8 af = *(const bf16x8*)(H + rowg * DM + g * 16 + 8 * half);
;             const f32x16 z16 = {0.f, 0.f, 0.f, 0.f, 0.f, 0.f, 0.f, 0.f, 0.f, 0.f, 0.f, 0.f, 0.f, 0.f, 0.f, 0.f};
;             const f32x16 d0 = mfma32(af, Bf[0], z16), d1 = mfma32(af, Bf[1], z16), d2 = mfma32(af, Bf[2], z16), d3 = mfma32(af, Bf[3], z16);
; #pragma unroll
;             for (int r = 0; r < 16; ++r) {
;                 if (MODE == 2 && (r & 3) == 0) { const int batch = 8 * cidx + 4 * half + (r >> 2); const size_t sp = ((size_t)(li * 32 + batch) * 128 + g) * 64 + c;
;                     hr[0] = P.in[I_SSRE][sp]; hi[0] = P.in[I_SSIM][sp]; hr[1] = P.in[I_SSRE][sp + 32]; hi[1] = P.in[I_SSIM][sp + 32]; }
;                 { const float t = lre[0] * hr[0] - lim[0] * hi[0] + d0[r]; hi[0] = lre[0] * hi[0] + lim[0] * hr[0] + d1[r]; hr[0] = t; }
;                 { const float t = lre[1] * hr[1] - lim[1] * hi[1] + d2[r]; hi[1] = lre[1] * hi[1] + lim[1] * hr[1] + d3[r]; hr[1] = t; }
;                 if (MODE >= 1) { u32x2 w; w.x = pk_bf16(hr[0], hi[0]); w.y = pk_bf16(hr[1], hi[1]); *(LAS u32x2*)(hs + (16 * half + r) * 272 + c * 8) = w; }
;                 if (MODE == 2 && (r & 3) == 3) { const int batch = 8 * cidx + 4 * half + (r >> 2); const size_t sp = ((size_t)(li * 32 + batch) * 128 + g) * 64 + c;
;                     P.out[O_SRES + sp] = hr[0]; P.out[O_SIMS + sp] = hi[0]; P.out[O_SRES + sp + 32] = hr[1]; P.out[O_SIMS + sp + 32] = hi[1]; }
	v_xor_b32_e32 v12, 0x80000000, v18
	v_cvt_pk_bf16_f32 v77, v14, v12
	v_xor_b32_e32 v12, 0x80000000, v17
	v_cvt_pk_bf16_f32 v78, v13, v12
	v_xor_b32_e32 v12, 0x80000000, v19
	v_cvt_pk_bf16_f32 v79, v15, v12
	global_load_dwordx4 v[12:15], v[28:29], off
	s_waitcnt vmcnt(0)
	v_mfma_f32_32x32x16_bf16 v[48:63], v[12:15], v[0:3], 0
	v_mfma_f32_32x32x16_bf16 v[32:47], v[12:15], v[4:7], 0
	v_mfma_f32_32x32x16_bf16 v[16:31], v[12:15], v[8:11], 0
	v_mfma_f32_32x32x16_bf16 v[0:15], v[12:15], v[80:83], 0
	global_load_dword v81, v[116:117], off offset:128
	global_load_dword v80, v[114:115], off offset:128
	global_load_dword v83, v[116:117], off
	global_load_dword v82, v[114:115], off
	s_waitcnt vmcnt(3)
	v_mov_b32_e32 v120, v81
	s_waitcnt vmcnt(2)
	v_mov_b32_e32 v121, v80
	s_waitcnt vmcnt(1)
	v_mul_f32_e32 v114, v107, v83
	s_waitcnt vmcnt(0)
	v_pk_fma_f32 v[114:115], v[106:107], v[82:83], v[114:115] op_sel_hi:[1,1,0] neg_lo:[0,0,1] neg_hi:[0,0,1]
	v_mov_b32_e32 v116, v83
	v_mov_b32_e32 v117, v82
	v_mul_f32_e32 v82, v106, v83
	v_pk_fma_f32 v[82:83], v[106:107], v[116:117], v[82:83] op_sel_hi:[1,1,0]
	s_nop 0
	v_mul_f32_e32 v82, v111, v81
	v_pk_fma_f32 v[116:117], v[110:111], v[80:81], v[82:83] op_sel_hi:[1,1,0] neg_lo:[0,0,1] neg_hi:[0,0,1]
	v_mul_f32_e32 v80, v110, v81
	v_pk_fma_f32 v[80:81], v[110:111], v[120:121], v[80:81] op_sel_hi:[1,1,0]
	v_mov_b32_e32 v120, v48
	v_mov_b32_e32 v121, v32
	v_mov_b32_e32 v115, v83
	v_pk_add_f32 v[82:83], v[120:121], v[114:115]
	v_mov_b32_e32 v120, v16
	v_mul_f32_e32 v32, v107, v83
	v_pk_fma_f32 v[114:115], v[106:107], v[82:83], v[32:33] op_sel_hi:[1,1,0] neg_lo:[0,0,1] neg_hi:[0,0,1]
	v_mul_f32_e32 v32, v106, v83
	v_mov_b32_e32 v121, v0
	v_mov_b32_e32 v117, v81
	v_cvt_pk_bf16_f32 v80, v82, v83
	v_pk_fma_f32 v[82:83], v[106:107], v[82:83], v[32:33] op_sel:[0,1,0] op_sel_hi:[1,0,0]
	v_pk_add_f32 v[116:117], v[120:121], v[116:117]
	v_mov_b32_e32 v32, v49
	v_cvt_pk_bf16_f32 v81, v116, v117
	v_mul_f32_e32 v0, v111, v117
	v_mov_b32_e32 v115, v83
	ds_write_b64 v130, v[80:81]
	v_pk_fma_f32 v[80:81], v[110:111], v[116:117], v[0:1] op_sel_hi:[1,1,0] neg_lo:[0,0,1] neg_hi:[0,0,1]
	v_mul_f32_e32 v0, v110, v117
	v_pk_add_f32 v[32:33], v[32:33], v[114:115]
	v_pk_fma_f32 v[116:117], v[110:111], v[116:117], v[0:1] op_sel:[0,1,0] op_sel_hi:[1,0,0]
	v_mul_f32_e32 v0, v107, v33
	v_pk_fma_f32 v[48:49], v[106:107], v[32:33], v[0:1] op_sel_hi:[1,1,0] neg_lo:[0,0,1] neg_hi:[0,0,1]
	v_mul_f32_e32 v0, v106, v33
	v_cvt_pk_bf16_f32 v16, v32, v33
	v_pk_fma_f32 v[32:33], v[106:107], v[32:33], v[0:1] op_sel:[0,1,0] op_sel_hi:[1,0,0]
	v_mov_b32_e32 v0, v17
	v_mov_b32_e32 v81, v117
	v_pk_add_f32 v[0:1], v[0:1], v[80:81]
	v_mov_b32_e32 v80, v50
	v_cvt_pk_bf16_f32 v17, v0, v1
	ds_write_b64 v130, v[16:17] offset:272
	v_mul_f32_e32 v16, v111, v1
	v_mul_f32_e32 v32, v110, v1
	v_mov_b32_e32 v81, v34
	v_mov_b32_e32 v49, v33
	v_pk_fma_f32 v[16:17], v[110:111], v[0:1], v[16:17] op_sel_hi:[1,1,0] neg_lo:[0,0,1] neg_hi:[0,0,1]
	v_pk_fma_f32 v[0:1], v[110:111], v[0:1], v[32:33] op_sel:[0,1,0] op_sel_hi:[1,0,0]
	v_pk_add_f32 v[32:33], v[80:81], v[48:49]
	s_nop 0
	v_pk_mul_f32 v[48:49], v[106:107], v[32:33]
	v_cvt_pk_bf16_f32 v0, v32, v33
	v_pk_mul_f32 v[32:33], v[106:107], v[32:33] op_sel:[0,1] op_sel_hi:[1,0]
	v_sub_f32_e32 v17, v48, v49
	v_add_f32_e32 v34, v51, v17
	v_add_f32_e32 v17, v32, v33
	v_add_f32_e32 v35, v35, v17
	v_mov_b32_e32 v32, v18
	v_mov_b32_e32 v33, v2
	v_mov_b32_e32 v17, v1
	v_pk_add_f32 v[16:17], v[32:33], v[16:17]
	s_nop 0
	v_cvt_pk_bf16_f32 v1, v16, v17
	ds_write_b64 v130, v[0:1] offset:544
	v_pk_mul_f32 v[0:1], v[110:111], v[16:17]
	s_nop 0
	v_sub_f32_e32 v0, v0, v1
	v_add_f32_e32 v32, v19, v0
	v_pk_mul_f32 v[0:1], v[110:111], v[16:17] op_sel:[0,1] op_sel_hi:[1,0]
	s_nop 0
	v_add_f32_e32 v0, v0, v1
	v_add_f32_e32 v33, v3, v0
	v_cvt_pk_bf16_f32 v0, v34, v35
	v_cvt_pk_bf16_f32 v1, v32, v33
	ds_write_b64 v130, v[0:1] offset:816
	v_lshl_add_u64 v[2:3], s[14:15], 0, v[112:113]
	v_lshlrev_b32_e32 v0, 8, v134
	v_mov_b32_e32 v1, v129
	v_lshl_add_u64 v[16:17], v[2:3], 0, v[0:1]
	v_lshlrev_b32_e32 v2, 2, v84
	v_mov_b32_e32 v3, v129
	v_lshl_add_u64 v[16:17], v[16:17], 0, v[2:3]
	v_add_co_u32_e32 v18, vcc, s31, v16
	s_nop 1
	v_addc_co_u32_e32 v19, vcc, 0, v17, vcc
	v_add_co_u32_e32 v16, vcc, s60, v16
	global_store_dword v[18:19], v34, off
	s_nop 0
	v_addc_co_u32_e32 v17, vcc, 0, v17, vcc
	global_store_dword v[16:17], v35, off
	global_store_dword v[18:19], v32, off offset:128
	global_store_dword v[16:17], v33, off offset:128
	v_or_b32_e32 v16, 1, v108
	v_ashrrev_i32_e32 v17, 31, v16
	v_lshlrev_b64 v[16:17], 15, v[16:17]
	v_or_b32_e32 v32, v16, v105
	v_mov_b32_e32 v33, v17
	v_lshl_add_u64 v[34:35], s[56:57], 0, v[32:33]
	v_lshl_add_u64 v[32:33], s[54:55], 0, v[32:33]
	global_load_dword v19, v[34:35], off offset:128
	global_load_dword v18, v[32:33], off offset:128
	s_nop 0
	global_load_dword v35, v[34:35], off
	s_nop 0
	global_load_dword v34, v[32:33], off
	s_waitcnt vmcnt(2)
	v_mov_b32_e32 v51, v18
	s_waitcnt vmcnt(1)
	v_mul_f32_e32 v32, v107, v35
	s_waitcnt vmcnt(0)
; #define LAS __attribute__((address_space(3)))
; __device__ __forceinline__ unsigned pk_bf16(float lo, float hi) { unsigned r; asm volatile("v_cvt_pk_bf16_f32 %0, %1, %2" : "=v"(r) : "v"(lo), "v"(hi)); return r; }
; template <int MODE>
; __device__ __forceinline__ void ssm_unit(const Ctx& P, int li, int g, int cidx, LAS unsigned char* hs, const bf16_t* H, bf16_t* Z, float* E, int lane) {
;     ...
;             for (int r = 0; r < 16; ++r) {
;                 if (MODE == 2 && (r & 3) == 0) { const int batch = 8 * cidx + 4 * half + (r >> 2); const size_t sp = ((size_t)(li * 32 + batch) * 128 + g) * 64 + c;
;                     hr[0] = P.in[I_SSRE][sp]; hi[0] = P.in[I_SSIM][sp]; hr[1] = P.in[I_SSRE][sp + 32]; hi[1] = P.in[I_SSIM][sp + 32]; }
;                 { const float t = lre[0] * hr[0] - lim[0] * hi[0] + d0[r]; hi[0] = lre[0] * hi[0] + lim[0] * hr[0] + d1[r]; hr[0] = t; }
;                 { const float t = lre[1] * hr[1] - lim[1] * hi[1] + d2[r]; hi[1] = lre[1] * hi[1] + lim[1] * hr[1] + d3[r]; hr[1] = t; }
;                 if (MODE >= 1) { u32x2 w; w.x = pk_bf16(hr[0], hi[0]); w.y = pk_bf16(hr[1], hi[1]); *(LAS u32x2*)(hs + (16 * half + r) * 272 + c * 8) = w; }
;                 if (MODE == 2 && (r & 3) == 3) { const int batch = 8 * cidx + 4 * half + (r >> 2); const size_t sp = ((size_t)(li * 32 + batch) * 128 + g) * 64 + c;
;                     P.out[O_SRES + sp] = hr[0]; P.out[O_SIMS + sp] = hi[0]; P.out[O_SRES + sp + 32] = hr[1]; P.out[O_SIMS + sp + 32] = hi[1]; }
	v_pk_fma_f32 v[32:33], v[106:107], v[34:35], v[32:33] op_sel_hi:[1,1,0] neg_lo:[0,0,1] neg_hi:[0,0,1]
	v_mov_b32_e32 v48, v35
	v_mov_b32_e32 v49, v34
	v_mul_f32_e32 v34, v106, v35
	v_pk_fma_f32 v[34:35], v[106:107], v[48:49], v[34:35] op_sel_hi:[1,1,0]
	v_mov_b32_e32 v50, v19
	v_mul_f32_e32 v34, v111, v19
	v_pk_fma_f32 v[48:49], v[110:111], v[18:19], v[34:35] op_sel_hi:[1,1,0] neg_lo:[0,0,1] neg_hi:[0,0,1]
	v_mul_f32_e32 v18, v110, v19
	v_pk_fma_f32 v[18:19], v[110:111], v[50:51], v[18:19] op_sel_hi:[1,1,0]
	v_mov_b32_e32 v50, v52
	v_mov_b32_e32 v51, v36
	v_mov_b32_e32 v33, v35
	v_pk_add_f32 v[32:33], v[50:51], v[32:33]
	v_mov_b32_e32 v50, v20
	v_mul_f32_e32 v34, v107, v33
	v_mul_f32_e32 v36, v106, v33
	v_mov_b32_e32 v51, v4
	v_mov_b32_e32 v49, v19
	v_cvt_pk_bf16_f32 v18, v32, v33
	v_pk_fma_f32 v[34:35], v[106:107], v[32:33], v[34:35] op_sel_hi:[1,1,0] neg_lo:[0,0,1] neg_hi:[0,0,1]
	v_pk_fma_f32 v[32:33], v[106:107], v[32:33], v[36:37] op_sel:[0,1,0] op_sel_hi:[1,0,0]
	v_pk_add_f32 v[48:49], v[50:51], v[48:49]
	v_mov_b32_e32 v36, v53
	v_cvt_pk_bf16_f32 v19, v48, v49
	v_mul_f32_e32 v4, v111, v49
	v_mov_b32_e32 v35, v33
	ds_write_b64 v130, v[18:19] offset:1088
	v_pk_fma_f32 v[18:19], v[110:111], v[48:49], v[4:5] op_sel_hi:[1,1,0] neg_lo:[0,0,1] neg_hi:[0,0,1]
	v_mul_f32_e32 v4, v110, v49
	v_pk_add_f32 v[32:33], v[36:37], v[34:35]
	v_pk_fma_f32 v[48:49], v[110:111], v[48:49], v[4:5] op_sel:[0,1,0] op_sel_hi:[1,0,0]
	v_mul_f32_e32 v4, v107, v33
	v_pk_fma_f32 v[34:35], v[106:107], v[32:33], v[4:5] op_sel_hi:[1,1,0] neg_lo:[0,0,1] neg_hi:[0,0,1]
	v_mul_f32_e32 v4, v106, v33
	v_cvt_pk_bf16_f32 v20, v32, v33
	v_pk_fma_f32 v[32:33], v[106:107], v[32:33], v[4:5] op_sel:[0,1,0] op_sel_hi:[1,0,0]
	v_mov_b32_e32 v4, v21
	v_mov_b32_e32 v19, v49
	v_pk_add_f32 v[4:5], v[4:5], v[18:19]
	v_mov_b32_e32 v35, v33
	v_cvt_pk_bf16_f32 v21, v4, v5
	ds_write_b64 v130, v[20:21] offset:1360
	v_mul_f32_e32 v18, v111, v5
	v_mul_f32_e32 v20, v110, v5
	v_pk_fma_f32 v[18:19], v[110:111], v[4:5], v[18:19] op_sel_hi:[1,1,0] neg_lo:[0,0,1] neg_hi:[0,0,1]
	v_pk_fma_f32 v[4:5], v[110:111], v[4:5], v[20:21] op_sel:[0,1,0] op_sel_hi:[1,0,0]
	v_mov_b32_e32 v20, v54
	v_mov_b32_e32 v21, v38
	v_pk_add_f32 v[20:21], v[20:21], v[34:35]
	s_nop 0
	v_pk_mul_f32 v[32:33], v[106:107], v[20:21]
	v_cvt_pk_bf16_f32 v4, v20, v21
	v_pk_mul_f32 v[20:21], v[106:107], v[20:21] op_sel:[0,1] op_sel_hi:[1,0]
	v_sub_f32_e32 v19, v32, v33
	v_add_f32_e32 v32, v55, v19
	v_add_f32_e32 v19, v20, v21
	v_add_f32_e32 v33, v39, v19
	v_mov_b32_e32 v20, v22
	v_mov_b32_e32 v21, v6
	v_mov_b32_e32 v19, v5
	v_pk_add_f32 v[18:19], v[20:21], v[18:19]
	s_nop 0
	v_cvt_pk_bf16_f32 v5, v18, v19
	ds_write_b64 v130, v[4:5] offset:1632
	v_pk_mul_f32 v[4:5], v[110:111], v[18:19]
	s_nop 0
	v_sub_f32_e32 v4, v4, v5
	v_add_f32_e32 v20, v23, v4
	v_pk_mul_f32 v[4:5], v[110:111], v[18:19] op_sel:[0,1] op_sel_hi:[1,0]
	s_nop 0
	v_add_f32_e32 v4, v4, v5
	v_add_f32_e32 v18, v7, v4
	v_cvt_pk_bf16_f32 v4, v32, v33
	v_cvt_pk_bf16_f32 v5, v20, v18
	ds_write_b64 v130, v[4:5] offset:1904
	v_lshl_add_u64 v[4:5], s[14:15], 0, v[16:17]
	v_lshl_add_u64 v[4:5], v[4:5], 0, v[0:1]
	v_lshl_add_u64 v[4:5], v[4:5], 0, v[2:3]
	v_add_co_u32_e32 v6, vcc, s31, v4
	s_nop 1
	v_addc_co_u32_e32 v7, vcc, 0, v5, vcc
	v_add_co_u32_e32 v4, vcc, s60, v4
	global_store_dword v[6:7], v32, off
	s_nop 0
	v_addc_co_u32_e32 v5, vcc, 0, v5, vcc
	global_store_dword v[4:5], v33, off
	global_store_dword v[6:7], v20, off offset:128
	global_store_dword v[4:5], v18, off offset:128
	v_or_b32_e32 v4, 2, v108
	v_ashrrev_i32_e32 v5, 31, v4
	v_lshlrev_b64 v[4:5], 15, v[4:5]
	v_or_b32_e32 v16, v4, v105
	v_mov_b32_e32 v17, v5
	v_lshl_add_u64 v[18:19], s[56:57], 0, v[16:17]
	v_lshl_add_u64 v[16:17], s[54:55], 0, v[16:17]
	global_load_dword v7, v[18:19], off offset:128
	global_load_dword v6, v[16:17], off offset:128
	s_nop 0
	global_load_dword v19, v[18:19], off
	s_nop 0
	global_load_dword v18, v[16:17], off
	v_lshl_add_u64 v[4:5], s[14:15], 0, v[4:5]
	v_lshl_add_u64 v[4:5], v[4:5], 0, v[0:1]
	v_lshl_add_u64 v[4:5], v[4:5], 0, v[2:3]
	s_waitcnt vmcnt(2)
	v_mov_b32_e32 v23, v6
	s_waitcnt vmcnt(1)
	v_mul_f32_e32 v16, v107, v19
	s_waitcnt vmcnt(0)
	v_pk_fma_f32 v[16:17], v[106:107], v[18:19], v[16:17] op_sel_hi:[1,1,0] neg_lo:[0,0,1] neg_hi:[0,0,1]
	v_mov_b32_e32 v20, v19
	v_mov_b32_e32 v21, v18
	v_mul_f32_e32 v18, v106, v19
	v_pk_fma_f32 v[18:19], v[106:107], v[20:21], v[18:19] op_sel_hi:[1,1,0]
	v_mov_b32_e32 v22, v7
	v_mul_f32_e32 v18, v111, v7
	v_pk_fma_f32 v[20:21], v[110:111], v[6:7], v[18:19] op_sel_hi:[1,1,0] neg_lo:[0,0,1] neg_hi:[0,0,1]
	v_mul_f32_e32 v6, v110, v7
	v_pk_fma_f32 v[6:7], v[110:111], v[22:23], v[6:7] op_sel_hi:[1,1,0]
	v_mov_b32_e32 v22, v56
	v_mov_b32_e32 v23, v40
	v_mov_b32_e32 v17, v19
	v_pk_add_f32 v[16:17], v[22:23], v[16:17]
	v_mov_b32_e32 v21, v7
	v_mul_f32_e32 v18, v107, v17
	v_mul_f32_e32 v22, v106, v17
	v_cvt_pk_bf16_f32 v6, v16, v17
	v_pk_fma_f32 v[18:19], v[106:107], v[16:17], v[18:19] op_sel_hi:[1,1,0] neg_lo:[0,0,1] neg_hi:[0,0,1]
	v_pk_fma_f32 v[16:17], v[106:107], v[16:17], v[22:23] op_sel:[0,1,0] op_sel_hi:[1,0,0]
	v_mov_b32_e32 v22, v24
	v_mov_b32_e32 v23, v8
	v_pk_add_f32 v[20:21], v[22:23], v[20:21]
	v_mov_b32_e32 v40, v57
	v_mov_b32_e32 v19, v17
	v_cvt_pk_bf16_f32 v7, v20, v21
	ds_write_b64 v130, v[6:7] offset:2176
	v_mul_f32_e32 v6, v111, v21
	v_mul_f32_e32 v8, v110, v21
	v_pk_add_f32 v[16:17], v[40:41], v[18:19]
	v_pk_fma_f32 v[6:7], v[110:111], v[20:21], v[6:7] op_sel_hi:[1,1,0] neg_lo:[0,0,1] neg_hi:[0,0,1]
	v_pk_fma_f32 v[20:21], v[110:111], v[20:21], v[8:9] op_sel:[0,1,0] op_sel_hi:[1,0,0]
	v_mul_f32_e32 v8, v107, v17
; #define LAS __attribute__((address_space(3)))
; __device__ __forceinline__ unsigned pk_bf16(float lo, float hi) { unsigned r; asm volatile("v_cvt_pk_bf16_f32 %0, %1, %2" : "=v"(r) : "v"(lo), "v"(hi)); return r; }
; template <int MODE>
; __device__ __forceinline__ void ssm_unit(const Ctx& P, int li, int g, int cidx, LAS unsigned char* hs, const bf16_t* H, bf16_t* Z, float* E, int lane) {
;     ...
;             for (int r = 0; r < 16; ++r) {
;                 if (MODE == 2 && (r & 3) == 0) { const int batch = 8 * cidx + 4 * half + (r >> 2); const size_t sp = ((size_t)(li * 32 + batch) * 128 + g) * 64 + c;
;                     hr[0] = P.in[I_SSRE][sp]; hi[0] = P.in[I_SSIM][sp]; hr[1] = P.in[I_SSRE][sp + 32]; hi[1] = P.in[I_SSIM][sp + 32]; }
;                 { const float t = lre[0] * hr[0] - lim[0] * hi[0] + d0[r]; hi[0] = lre[0] * hi[0] + lim[0] * hr[0] + d1[r]; hr[0] = t; }
;                 { const float t = lre[1] * hr[1] - lim[1] * hi[1] + d2[r]; hi[1] = lre[1] * hi[1] + lim[1] * hr[1] + d3[r]; hr[1] = t; }
;                 if (MODE >= 1) { u32x2 w; w.x = pk_bf16(hr[0], hi[0]); w.y = pk_bf16(hr[1], hi[1]); *(LAS u32x2*)(hs + (16 * half + r) * 272 + c * 8) = w; }
;                 if (MODE == 2 && (r & 3) == 3) { const int batch = 8 * cidx + 4 * half + (r >> 2); const size_t sp = ((size_t)(li * 32 + batch) * 128 + g) * 64 + c;
;                     P.out[O_SRES + sp] = hr[0]; P.out[O_SIMS + sp] = hi[0]; P.out[O_SRES + sp + 32] = hr[1]; P.out[O_SIMS + sp + 32] = hi[1]; }
	v_pk_fma_f32 v[22:23], v[106:107], v[16:17], v[8:9] op_sel_hi:[1,1,0] neg_lo:[0,0,1] neg_hi:[0,0,1]
	v_mul_f32_e32 v8, v106, v17
	v_cvt_pk_bf16_f32 v18, v16, v17
	v_pk_fma_f32 v[16:17], v[106:107], v[16:17], v[8:9] op_sel:[0,1,0] op_sel_hi:[1,0,0]
	v_mov_b32_e32 v8, v25
	v_mov_b32_e32 v7, v21
	v_pk_add_f32 v[6:7], v[8:9], v[6:7]
	v_mov_b32_e32 v23, v17
	v_cvt_pk_bf16_f32 v19, v6, v7
	ds_write_b64 v130, v[18:19] offset:2448
	v_mul_f32_e32 v8, v111, v7
	v_mul_f32_e32 v16, v110, v7
	v_mov_b32_e32 v18, v58
	v_mov_b32_e32 v19, v42
	v_pk_fma_f32 v[8:9], v[110:111], v[6:7], v[8:9] op_sel_hi:[1,1,0] neg_lo:[0,0,1] neg_hi:[0,0,1]
	v_pk_fma_f32 v[6:7], v[110:111], v[6:7], v[16:17] op_sel:[0,1,0] op_sel_hi:[1,0,0]
	v_pk_add_f32 v[16:17], v[18:19], v[22:23]
	s_nop 0
	v_pk_mul_f32 v[18:19], v[106:107], v[16:17]
	v_cvt_pk_bf16_f32 v6, v16, v17
	v_pk_mul_f32 v[16:17], v[106:107], v[16:17] op_sel:[0,1] op_sel_hi:[1,0]
	v_sub_f32_e32 v9, v18, v19
	v_add_f32_e32 v18, v59, v9
	v_add_f32_e32 v9, v16, v17
	v_add_f32_e32 v19, v43, v9
	v_mov_b32_e32 v16, v26
	v_mov_b32_e32 v17, v10
	v_mov_b32_e32 v9, v7
	v_pk_add_f32 v[8:9], v[16:17], v[8:9]
	s_nop 0
	v_cvt_pk_bf16_f32 v7, v8, v9
	ds_write_b64 v130, v[6:7] offset:2720
	v_pk_mul_f32 v[6:7], v[110:111], v[8:9]
	s_nop 0
	v_sub_f32_e32 v6, v6, v7
	v_add_f32_e32 v10, v27, v6
	v_pk_mul_f32 v[6:7], v[110:111], v[8:9] op_sel:[0,1] op_sel_hi:[1,0]
	s_nop 0
	v_add_f32_e32 v6, v6, v7
	v_add_f32_e32 v8, v11, v6
	v_cvt_pk_bf16_f32 v6, v18, v19
	v_cvt_pk_bf16_f32 v7, v10, v8
	ds_write_b64 v130, v[6:7] offset:2992
	v_add_co_u32_e32 v6, vcc, s31, v4
	s_nop 1
	v_addc_co_u32_e32 v7, vcc, 0, v5, vcc
	v_add_co_u32_e32 v4, vcc, s60, v4
	global_store_dword v[6:7], v18, off
	s_nop 0
	v_addc_co_u32_e32 v5, vcc, 0, v5, vcc
	global_store_dword v[4:5], v19, off
	global_store_dword v[6:7], v10, off offset:128
	global_store_dword v[4:5], v8, off offset:128
	v_or_b32_e32 v4, 3, v108
	v_ashrrev_i32_e32 v5, 31, v4
	v_lshlrev_b64 v[4:5], 15, v[4:5]
	v_or_b32_e32 v8, v4, v105
	v_mov_b32_e32 v9, v5
	v_lshl_add_u64 v[10:11], s[56:57], 0, v[8:9]
	v_lshl_add_u64 v[8:9], s[54:55], 0, v[8:9]
	global_load_dword v7, v[10:11], off offset:128
	global_load_dword v6, v[8:9], off offset:128
	s_nop 0
	global_load_dword v11, v[10:11], off
	s_nop 0
	global_load_dword v10, v[8:9], off
	v_lshl_add_u64 v[4:5], s[14:15], 0, v[4:5]
	v_lshl_add_u64 v[0:1], v[4:5], 0, v[0:1]
	v_lshl_add_u64 v[0:1], v[0:1], 0, v[2:3]
	v_add_co_u32_e32 v2, vcc, s31, v0
	s_waitcnt vmcnt(2)
	v_mov_b32_e32 v19, v6
	s_waitcnt vmcnt(1)
	v_mul_f32_e32 v8, v107, v11
	s_waitcnt vmcnt(0)
	v_pk_fma_f32 v[8:9], v[106:107], v[10:11], v[8:9] op_sel_hi:[1,1,0] neg_lo:[0,0,1] neg_hi:[0,0,1]
	v_mov_b32_e32 v16, v11
	v_mov_b32_e32 v17, v10
	v_mul_f32_e32 v10, v106, v11
	v_pk_fma_f32 v[10:11], v[106:107], v[16:17], v[10:11] op_sel_hi:[1,1,0]
	v_mov_b32_e32 v18, v7
	v_mul_f32_e32 v10, v111, v7
	v_pk_fma_f32 v[16:17], v[110:111], v[6:7], v[10:11] op_sel_hi:[1,1,0] neg_lo:[0,0,1] neg_hi:[0,0,1]
	v_mul_f32_e32 v6, v110, v7
	v_pk_fma_f32 v[6:7], v[110:111], v[18:19], v[6:7] op_sel_hi:[1,1,0]
	v_mov_b32_e32 v18, v60
	v_mov_b32_e32 v19, v44
	v_mov_b32_e32 v9, v11
	v_pk_add_f32 v[8:9], v[18:19], v[8:9]
	v_mov_b32_e32 v17, v7
	v_mul_f32_e32 v10, v107, v9
	v_mul_f32_e32 v18, v106, v9
	v_cvt_pk_bf16_f32 v6, v8, v9
	v_pk_fma_f32 v[10:11], v[106:107], v[8:9], v[10:11] op_sel_hi:[1,1,0] neg_lo:[0,0,1] neg_hi:[0,0,1]
	v_pk_fma_f32 v[8:9], v[106:107], v[8:9], v[18:19] op_sel:[0,1,0] op_sel_hi:[1,0,0]
	v_mov_b32_e32 v18, v28
	v_mov_b32_e32 v19, v12
	v_pk_add_f32 v[16:17], v[18:19], v[16:17]
	v_mov_b32_e32 v44, v61
	v_cvt_pk_bf16_f32 v7, v16, v17
	ds_write_b64 v130, v[6:7] offset:3264
	v_mul_f32_e32 v6, v111, v17
	v_mul_f32_e32 v8, v110, v17
	v_mov_b32_e32 v11, v9
	v_pk_fma_f32 v[6:7], v[110:111], v[16:17], v[6:7] op_sel_hi:[1,1,0] neg_lo:[0,0,1] neg_hi:[0,0,1]
	v_pk_fma_f32 v[16:17], v[110:111], v[16:17], v[8:9] op_sel:[0,1,0] op_sel_hi:[1,0,0]
	v_pk_add_f32 v[8:9], v[44:45], v[10:11]
	v_mov_b32_e32 v7, v17
	v_mul_f32_e32 v12, v107, v9
	v_pk_fma_f32 v[18:19], v[106:107], v[8:9], v[12:13] op_sel_hi:[1,1,0] neg_lo:[0,0,1] neg_hi:[0,0,1]
	v_mul_f32_e32 v12, v106, v9
	v_cvt_pk_bf16_f32 v10, v8, v9
	v_pk_fma_f32 v[8:9], v[106:107], v[8:9], v[12:13] op_sel:[0,1,0] op_sel_hi:[1,0,0]
	v_mov_b32_e32 v12, v29
	v_pk_add_f32 v[6:7], v[12:13], v[6:7]
	v_mov_b32_e32 v12, v62
	v_cvt_pk_bf16_f32 v11, v6, v7
	v_mul_f32_e32 v8, v111, v7
	ds_write_b64 v130, v[10:11] offset:3536
	v_pk_fma_f32 v[10:11], v[110:111], v[6:7], v[8:9] op_sel_hi:[1,1,0] neg_lo:[0,0,1] neg_hi:[0,0,1]
	v_mul_f32_e32 v8, v110, v7
	v_mov_b32_e32 v13, v46
	v_mov_b32_e32 v19, v9
	v_pk_fma_f32 v[6:7], v[110:111], v[6:7], v[8:9] op_sel:[0,1,0] op_sel_hi:[1,0,0]
	v_pk_add_f32 v[8:9], v[12:13], v[18:19]
	v_addc_co_u32_e32 v3, vcc, 0, v1, vcc
	v_cvt_pk_bf16_f32 v6, v8, v9
	v_pk_mul_f32 v[12:13], v[106:107], v[8:9]
	v_pk_mul_f32 v[8:9], v[106:107], v[8:9] op_sel:[0,1] op_sel_hi:[1,0]
	v_sub_f32_e32 v11, v12, v13
	v_add_f32_e32 v8, v8, v9
	v_add_f32_e32 v12, v63, v11
	v_add_f32_e32 v13, v47, v8
	v_mov_b32_e32 v8, v30
	v_mov_b32_e32 v9, v14
	v_mov_b32_e32 v11, v7
	v_pk_add_f32 v[8:9], v[8:9], v[10:11]
	v_add_co_u32_e32 v0, vcc, s60, v0
	v_cvt_pk_bf16_f32 v7, v8, v9
	ds_write_b64 v130, v[6:7] offset:3808
	v_pk_mul_f32 v[6:7], v[110:111], v[8:9]
	v_addc_co_u32_e32 v1, vcc, 0, v1, vcc
	v_sub_f32_e32 v6, v6, v7
	v_add_f32_e32 v10, v31, v6
	v_pk_mul_f32 v[6:7], v[110:111], v[8:9] op_sel:[0,1] op_sel_hi:[1,0]
	s_nop 0
	v_add_f32_e32 v6, v6, v7
	v_add_f32_e32 v8, v15, v6
	v_cvt_pk_bf16_f32 v6, v12, v13
	v_cvt_pk_bf16_f32 v7, v10, v8
	ds_write_b64 v130, v[6:7] offset:4080
	global_store_dword v[2:3], v12, off
	global_store_dword v[0:1], v13, off
	global_store_dword v[2:3], v10, off offset:128
	global_store_dword v[0:1], v8, off offset:128
	s_waitcnt lgkmcnt(0)
; #define LAS __attribute__((address_space(3)))
; __device__ __forceinline__ unsigned pk_bf16(float lo, float hi) { unsigned r; asm volatile("v_cvt_pk_bf16_f32 %0, %1, %2" : "=v"(r) : "v"(lo), "v"(hi)); return r; }
; __device__ __forceinline__ float bflo(unsigned w) { return __uint_as_float(w << 16); }
; __device__ __forceinline__ float bfhi(unsigned w) { return __uint_as_float(w & 0xffff0000u); }
; __device__ __forceinline__ float gelu_t(float x) { const float u = 0.7978845608028654f * (x + 0.044715f * x * x * x); return x / (1.0f + __expf(-2.0f * u)); }
; template <int MODE>
; __device__ __forceinline__ void ssm_unit(const Ctx& P, int li, int g, int cidx, LAS unsigned char* hs, const bf16_t* H, bf16_t* Z, float* E, int lane) {
;     ...
;     const float delta = __expf(P.in[I_LSTEP][li * 128 + g]);
;     float lre[2], lim[2];
;     bf16x8 Bf[4];
; #pragma unroll
;     for (int s = 0; s < 2; ++s) { const int p = c + 32 * s; const size_t gp = (size_t)(li * 128 + g) * 64 + p;
;         const float ar = P.in[I_LRE][gp], ai = P.in[I_LIM][gp];
;         const float mag = __expf(ar * delta); float rev = ai * delta * 0.15915494309189535f; rev -= rintf(rev);
;         const float sn = __builtin_amdgcn_sinf(rev), cs = __builtin_amdgcn_cosf(rev);
;         lre[s] = mag * cs; lim[s] = mag * sn;
;     ...
;         if (MODE >= 1) {
;             lds_wave_sync();
; #pragma unroll
;             for (int rb = 0; rb < 2; ++rb) { f32x4 acc = {0.f, 0.f, 0.f, 0.f};
; #pragma unroll
;                 for (int kk = 0; kk < 4; ++kk) { const bf16x8 hf = *(const LAS bf16x8*)(hs + (16 * rb + fr) * 272 + (32 * kk + 8 * fq) * 2); acc = mfma16(Cf[kk], hf, acc); }
;                 const size_t rowg = (MODE == 2) ? (size_t)TP + 32 * cidx + 16 * rb + fr : (size_t)rb * SEQ + (size_t)cidx * 128 + blk * 16 + fr;
;                 const size_t off = rowg * DM + g * 16 + 4 * fq;
;                 const u32x2 uw = *(const u32x2*)(H + off);
;                 const f32x4 dsk = *(const f32x4*)(P.in[I_SD] + (size_t)li * DM + g * 16 + 4 * fq);
;                 const float y0 = acc[0] + dsk[0] * bflo(uw.x), y1 = acc[1] + dsk[1] * bfhi(uw.x), y2 = acc[2] + dsk[2] * bflo(uw.y), y3 = acc[3] + dsk[3] * bfhi(uw.y);
;                 u32x2 w; w.x = pk_bf16(gelu_t(y0), gelu_t(y1)); w.y = pk_bf16(gelu_t(y2), gelu_t(y3));
;                 *(u32x2*)(Z + off) = w; }
;             lds_wave_sync();
	ds_read_b128 v[0:3], v133
	ds_read_b128 v[4:7], v133 offset:64
	s_waitcnt lgkmcnt(1)
	v_mfma_f32_16x16x32_bf16 v[0:3], v[64:67], v[0:3], 0
	v_or_b32_e32 v8, v119, v87
	s_waitcnt lgkmcnt(0)
	v_mfma_f32_16x16x32_bf16 v[0:3], v[68:71], v[4:7], v[0:3]
	ds_read_b128 v[4:7], v133 offset:128
	s_waitcnt lgkmcnt(0)
	v_mfma_f32_16x16x32_bf16 v[0:3], v[72:75], v[4:7], v[0:3]
	ds_read_b128 v[4:7], v133 offset:192
	s_waitcnt lgkmcnt(0)
	v_mfma_f32_16x16x32_bf16 v[0:3], v[76:79], v[4:7], v[0:3]
	v_lshlrev_b32_e32 v4, 11, v8
	v_or3_b32 v4, v127, v4, v118
	v_lshlrev_b32_e32 v6, 1, v4
	global_load_dwordx2 v[12:13], v6, s[6:7]
	v_lshl_add_u64 v[4:5], v[96:97], 0, v[128:129]
	global_load_dwordx4 v[8:11], v[4:5], off
	s_waitcnt vmcnt(1)
	v_lshlrev_b32_e32 v7, 16, v12
	s_waitcnt vmcnt(0)
	v_fma_f32 v0, v8, v7, v0
	v_and_b32_e32 v7, 0xffff0000, v12
	v_fma_f32 v1, v9, v7, v1
	v_lshlrev_b32_e32 v7, 16, v13
	v_fma_f32 v2, v10, v7, v2
	v_and_b32_e32 v7, 0xffff0000, v13
	v_fmac_f32_e32 v3, v11, v7
	v_mul_f32_e32 v7, 0x3d372713, v0
	v_mul_f32_e32 v7, v0, v7
	v_fma_f32 v7, v0, v7, v0
	v_mul_f32_e32 v7, 0xc0135761, v7
	v_exp_f32_e32 v7, v7
	s_nop 0
	v_add_f32_e32 v7, 1.0, v7
	v_rcp_f32_e32 v9, v7
	s_nop 0
	v_mul_f32_e32 v0, v0, v9
	v_mul_f32_e32 v7, 0x3d372713, v1
	v_mul_f32_e32 v7, v1, v7
	v_fma_f32 v7, v1, v7, v1
	v_mul_f32_e32 v7, 0xc0135761, v7
	v_exp_f32_e32 v7, v7
	s_nop 0
	v_add_f32_e32 v7, 1.0, v7
	v_rcp_f32_e32 v9, v7
	s_nop 0
	v_mul_f32_e32 v1, v1, v9
	v_cvt_pk_bf16_f32 v0, v0, v1
	v_mul_f32_e32 v1, 0x3d372713, v2
	v_mul_f32_e32 v1, v2, v1
	v_fma_f32 v1, v2, v1, v2
	v_mul_f32_e32 v1, 0xc0135761, v1
	v_exp_f32_e32 v1, v1
	s_nop 0
	v_add_f32_e32 v1, 1.0, v1
	v_rcp_f32_e32 v8, v1
	s_nop 0
	v_mul_f32_e32 v1, v2, v8
	v_mul_f32_e32 v2, 0x3d372713, v3
	v_mul_f32_e32 v2, v3, v2
	v_fma_f32 v2, v3, v2, v3
	v_mul_f32_e32 v2, 0xc0135761, v2
	v_exp_f32_e32 v2, v2
	s_nop 0
	v_add_f32_e32 v2, 1.0, v2
	v_rcp_f32_e32 v8, v2
	s_nop 0
	v_mul_f32_e32 v2, v3, v8
	v_cvt_pk_bf16_f32 v1, v1, v2
	global_store_dwordx2 v6, v[0:1], s[4:5]
	ds_read_b128 v[0:3], v133 offset:4352
	ds_read_b128 v[8:11], v133 offset:4416
	s_waitcnt lgkmcnt(1)
	v_mfma_f32_16x16x32_bf16 v[0:3], v[64:67], v[0:3], 0
	v_or_b32_e32 v6, 0x10000, v6
	s_waitcnt lgkmcnt(0)
	v_mfma_f32_16x16x32_bf16 v[0:3], v[68:71], v[8:11], v[0:3]
	ds_read_b128 v[8:11], v133 offset:4480
	s_waitcnt lgkmcnt(0)
	v_mfma_f32_16x16x32_bf16 v[0:3], v[72:75], v[8:11], v[0:3]
	ds_read_b128 v[8:11], v133 offset:4544
	s_waitcnt lgkmcnt(0)
	v_mfma_f32_16x16x32_bf16 v[0:3], v[76:79], v[8:11], v[0:3]
	global_load_dwordx2 v[12:13], v6, s[6:7]
	global_load_dwordx4 v[8:11], v[4:5], off
	s_waitcnt vmcnt(1)
	v_lshlrev_b32_e32 v4, 16, v12
	s_waitcnt vmcnt(0)
	s_nop 2
	v_fma_f32 v0, v8, v4, v0
	v_and_b32_e32 v4, 0xffff0000, v12
	v_fma_f32 v1, v9, v4, v1
	v_lshlrev_b32_e32 v4, 16, v13
	v_fma_f32 v2, v10, v4, v2
	v_and_b32_e32 v4, 0xffff0000, v13
	v_fmac_f32_e32 v3, v11, v4
	v_mul_f32_e32 v4, 0x3d372713, v0
	v_mul_f32_e32 v4, v0, v4
	v_fma_f32 v4, v0, v4, v0
	v_mul_f32_e32 v4, 0xc0135761, v4
	v_exp_f32_e32 v4, v4
	s_nop 0
	v_add_f32_e32 v4, 1.0, v4
	v_rcp_f32_e32 v7, v4
	s_nop 0
	v_mul_f32_e32 v0, v0, v7
	v_mul_f32_e32 v4, 0x3d372713, v1
	v_mul_f32_e32 v4, v1, v4
	v_fma_f32 v4, v1, v4, v1
	v_mul_f32_e32 v4, 0xc0135761, v4
	v_exp_f32_e32 v4, v4
	s_nop 0
	v_add_f32_e32 v4, 1.0, v4
	v_rcp_f32_e32 v7, v4
	s_nop 0
	v_mul_f32_e32 v1, v1, v7
	v_cvt_pk_bf16_f32 v0, v0, v1
	v_mul_f32_e32 v1, 0x3d372713, v2
	v_mul_f32_e32 v1, v2, v1
	v_fma_f32 v1, v2, v1, v2
	v_mul_f32_e32 v1, 0xc0135761, v1
	v_exp_f32_e32 v1, v1
	s_nop 0
	v_add_f32_e32 v1, 1.0, v1
	v_rcp_f32_e32 v5, v1
	s_nop 0
	v_mul_f32_e32 v1, v2, v5
	v_mul_f32_e32 v2, 0x3d372713, v3
	v_mul_f32_e32 v2, v3, v2
	v_fma_f32 v2, v3, v2, v3
	v_mul_f32_e32 v2, 0xc0135761, v2
	v_exp_f32_e32 v2, v2
	s_nop 0
	v_add_f32_e32 v2, 1.0, v2
	v_rcp_f32_e32 v5, v2
	s_nop 0
	v_mul_f32_e32 v2, v3, v5
	v_cvt_pk_bf16_f32 v1, v1, v2
	global_store_dwordx2 v6, v[0:1], s[4:5]
	s_waitcnt lgkmcnt(0)
.LBB0_102:
	s_andn2_saveexec_b64 s[40:41], s[40:41]
	s_cbranch_execz .LBB0_99
	v_readlane_b32 s44, v253, 13
	v_ashrrev_i32_e32 v5, 31, v4
	v_readlane_b32 s46, v253, 15
	v_readlane_b32 s47, v253, 16
	s_waitcnt vmcnt(8)
	v_lshlrev_b64 v[12:13], 6, v[4:5]
	v_readlane_b32 s45, v253, 14
	v_lshl_add_u64 v[0:1], v[4:5], 2, s[46:47]
	global_load_dword v0, v[0:1], off
	v_mov_b32_e32 v1, v13
	v_ashrrev_i32_e32 v80, 7, v85
	v_ashrrev_i32_e32 v81, 31, v80
	s_waitcnt vmcnt(8)
	v_and_b32_e32 v18, 0x7f, v91
	v_mov_b32_e32 v124, 0
	v_mov_b32_e32 v122, 0
	v_mov_b32_e32 v125, v124
	v_mov_b32_e32 v123, v124
	v_readlane_b32 s48, v253, 17
	v_readlane_b32 s49, v253, 18
	v_readlane_b32 s50, v253, 19
	v_readlane_b32 s51, v253, 20
	v_readlane_b32 s52, v253, 21
	v_readlane_b32 s53, v253, 22
	v_readlane_b32 s54, v253, 23
	v_readlane_b32 s55, v253, 24
	v_readlane_b32 s56, v253, 25
	v_readlane_b32 s57, v253, 26
	v_readlane_b32 s58, v253, 27
	v_readlane_b32 s59, v253, 28
	s_waitcnt vmcnt(0)
	v_mul_f32_e32 v0, 0x3fb8aa3b, v0
	v_exp_f32_e32 v16, v0
	v_or_b32_e32 v0, v12, v84
	v_lshlrev_b64 v[2:3], 2, v[0:1]
	v_lshl_add_u64 v[4:5], s[78:79], 0, v[2:3]
	v_lshl_add_u64 v[2:3], s[44:45], 0, v[2:3]
	global_load_dword v15, v[2:3], off
	global_load_dword v14, v[4:5], off
	v_lshlrev_b64 v[0:1], 6, v[0:1]
	v_lshl_add_u64 v[20:21], v[94:95], 0, v[0:1]
	v_or_b32_e32 v12, v12, v86
	s_waitcnt vmcnt(1)
	v_mul_f32_e32 v3, v16, v15
	v_mul_f32_e32 v4, 0.15915494, v3
	s_waitcnt vmcnt(0)
; __device__ __forceinline__ unsigned pk_bf16(float lo, float hi) { unsigned r; asm volatile("v_cvt_pk_bf16_f32 %0, %1, %2" : "=v"(r) : "v"(lo), "v"(hi)); return r; }
; template <int MODE>
; __device__ __forceinline__ void ssm_unit(const Ctx& P, int li, int g, int cidx, LAS unsigned char* hs, const bf16_t* H, bf16_t* Z, float* E, int lane) {
;     ...
;     for (int s = 0; s < 2; ++s) { const int p = c + 32 * s; const size_t gp = (size_t)(li * 128 + g) * 64 + p;
;         const float ar = P.in[I_LRE][gp], ai = P.in[I_LIM][gp];
;         const float mag = __expf(ar * delta); float rev = ai * delta * 0.15915494309189535f; rev -= rintf(rev);
;         const float sn = __builtin_amdgcn_sinf(rev), cs = __builtin_amdgcn_cosf(rev);
;         lre[s] = mag * cs; lim[s] = mag * sn;
;         const float nr = lre[s] - 1.0f, ni = lim[s], den = 1.0f / (ar * ar + ai * ai);
;         const float cre = (nr * ar + ni * ai) * den, cim = (ni * ar - nr * ai) * den;
;         const float* brp = P.in[I_BRE] + gp * 16 + 8 * half; const float* bip = P.in[I_BIM] + gp * 16 + 8 * half;
;         const f32x4 br0 = *(const f32x4*)brp, br1 = *(const f32x4*)(brp + 4), bi0 = *(const f32x4*)bip, bi1 = *(const f32x4*)(bip + 4);
;         u32x4 wr_, wi_;
;         wr_.x = pk_bf16(cre * br0[0] - cim * bi0[0], cre * br0[1] - cim * bi0[1]); wr_.y = pk_bf16(cre * br0[2] - cim * bi0[2], cre * br0[3] - cim * bi0[3]);
;         wr_.z = pk_bf16(cre * br1[0] - cim * bi1[0], cre * br1[1] - cim * bi1[1]); wr_.w = pk_bf16(cre * br1[2] - cim * bi1[2], cre * br1[3] - cim * bi1[3]);
;         wi_.x = pk_bf16(cre * bi0[0] + cim * br0[0], cre * bi0[1] + cim * br0[1]); wi_.y = pk_bf16(cre * bi0[2] + cim * br0[2], cre * bi0[3] + cim * br0[3]);
;         wi_.z = pk_bf16(cre * bi1[0] + cim * br1[0], cre * bi1[1] + cim * br1[1]); wi_.w = pk_bf16(cre * bi1[2] + cim * br1[2], cre * bi1[3] + cim * br1[3]);
;         Bf[2 * s] = __builtin_bit_cast(bf16x8, wr_); Bf[2 * s + 1] = __builtin_bit_cast(bf16x8, wi_); }
	v_mul_f32_e32 v2, v14, v16
	v_rndne_f32_e32 v4, v4
	v_mul_f32_e32 v2, 0x3fb8aa3b, v2
	v_fma_f32 v3, v3, 0.15915494, -v4
	v_exp_f32_e32 v2, v2
	v_sin_f32_e32 v5, v3
	v_cos_f32_e32 v4, v3
	v_mov_b32_e32 v30, v15
	v_mov_b32_e32 v31, v14
	v_mov_b32_e32 v28, v15
	v_pk_mul_f32 v[82:83], v[2:3], v[4:5] op_sel_hi:[0,1]
	v_pk_mul_f32 v[2:3], v[14:15], v[14:15]
	v_add_f32_e32 v24, -1.0, v82
	v_add_f32_e32 v2, v2, v3
	v_div_scale_f32 v3, s[42:43], v2, v2, 1.0
	v_rcp_f32_e32 v4, v3
	v_pk_mul_f32 v[14:15], v[30:31], v[24:25] op_sel:[1,0] op_sel_hi:[0,0]
	v_pk_fma_f32 v[24:25], v[28:29], v[82:83], v[14:15] op_sel:[0,1,0]
	v_pk_fma_f32 v[14:15], v[30:31], v[82:83], v[14:15] op_sel:[0,1,0] neg_lo:[0,0,1] neg_hi:[0,0,1]
	v_fma_f32 v5, -v3, v4, 1.0
	v_fmac_f32_e32 v4, v5, v4
	v_div_scale_f32 v5, vcc, 1.0, v2, 1.0
	v_mul_f32_e32 v6, v5, v4
	v_fma_f32 v7, -v3, v6, v5
	v_fmac_f32_e32 v6, v7, v4
	v_fma_f32 v3, -v3, v6, v5
	v_div_fmas_f32 v3, v3, v4, v6
	v_lshl_add_u64 v[4:5], v[92:93], 0, v[0:1]
	v_div_fixup_f32 v26, v3, v2, 1.0
	global_load_dwordx4 v[0:3], v[4:5], off offset:16
	global_load_dwordx4 v[8:11], v[4:5], off
	s_nop 0
	global_load_dwordx4 v[4:7], v[20:21], off offset:16
	s_nop 0
	global_load_dwordx4 v[20:23], v[20:21], off
	v_mov_b32_e32 v25, v15
	v_pk_mul_f32 v[14:15], v[26:27], v[24:25] op_sel_hi:[0,1]
	v_mov_b32_e32 v106, v83
	v_mov_b32_e32 v107, v83
	v_mov_b32_e32 v112, v82
	v_mov_b32_e32 v113, v82
	v_pk_mov_b32 v[116:117], v[82:83], v[82:83] op_sel:[1,0]
	s_waitcnt vmcnt(2)
	v_mov_b32_e32 v24, v8
	s_waitcnt vmcnt(0)
	v_mov_b32_e32 v25, v20
	v_pk_mul_f32 v[24:25], v[24:25], v[14:15]
	s_nop 0
	v_sub_f32_e32 v17, v24, v25
	v_mov_b32_e32 v24, v9
	v_mov_b32_e32 v25, v21
	v_pk_mul_f32 v[24:25], v[24:25], v[14:15]
	s_nop 0
	v_sub_f32_e32 v19, v24, v25
	v_mov_b32_e32 v24, v10
	v_mov_b32_e32 v25, v22
	v_pk_mul_f32 v[24:25], v[24:25], v[14:15]
	v_cvt_pk_bf16_f32 v64, v17, v19
	s_nop 0
	v_sub_f32_e32 v17, v24, v25
	v_mov_b32_e32 v24, v11
	v_mov_b32_e32 v25, v23
	v_pk_mul_f32 v[24:25], v[24:25], v[14:15]
	s_nop 0
	v_sub_f32_e32 v19, v24, v25
	v_mov_b32_e32 v24, v0
	v_mov_b32_e32 v25, v4
	v_pk_mul_f32 v[24:25], v[24:25], v[14:15]
	v_cvt_pk_bf16_f32 v65, v17, v19
	s_nop 0
	v_sub_f32_e32 v17, v24, v25
	v_mov_b32_e32 v24, v1
	v_mov_b32_e32 v25, v5
	v_pk_mul_f32 v[24:25], v[24:25], v[14:15]
	s_nop 0
	v_sub_f32_e32 v19, v24, v25
	v_mov_b32_e32 v24, v2
	v_mov_b32_e32 v25, v6
	v_pk_mul_f32 v[24:25], v[24:25], v[14:15]
	v_cvt_pk_bf16_f32 v66, v17, v19
	s_nop 0
	v_sub_f32_e32 v17, v24, v25
	v_mov_b32_e32 v24, v3
	v_mov_b32_e32 v25, v7
	v_pk_mul_f32 v[24:25], v[24:25], v[14:15]
	s_nop 0
	v_sub_f32_e32 v19, v24, v25
	v_mov_b32_e32 v25, v8
	v_mov_b32_e32 v8, v21
	v_mov_b32_e32 v24, v20
	v_pk_mul_f32 v[8:9], v[8:9], v[14:15]
	v_pk_mul_f32 v[24:25], v[24:25], v[14:15]
	v_add_f32_e32 v8, v8, v9
	v_cvt_pk_bf16_f32 v67, v17, v19
	v_add_f32_e32 v17, v24, v25
	v_cvt_pk_bf16_f32 v68, v17, v8
	v_mov_b32_e32 v8, v22
	v_mov_b32_e32 v9, v10
	v_pk_mul_f32 v[8:9], v[8:9], v[14:15]
	v_mov_b32_e32 v10, v23
	v_add_f32_e32 v17, v8, v9
	v_pk_mul_f32 v[8:9], v[10:11], v[14:15]
	s_nop 0
	v_add_f32_e32 v8, v8, v9
	v_mov_b32_e32 v9, v0
	v_mov_b32_e32 v0, v5
	v_cvt_pk_bf16_f32 v69, v17, v8
	v_mov_b32_e32 v8, v4
	v_pk_mul_f32 v[0:1], v[0:1], v[14:15]
	v_pk_mul_f32 v[8:9], v[8:9], v[14:15]
	v_add_f32_e32 v0, v0, v1
	v_add_f32_e32 v4, v8, v9
	v_cvt_pk_bf16_f32 v70, v4, v0
	v_mov_b32_e32 v0, v6
	v_mov_b32_e32 v1, v2
	v_pk_mul_f32 v[0:1], v[0:1], v[14:15]
	v_mov_b32_e32 v2, v7
	v_add_f32_e32 v4, v0, v1
	v_pk_mul_f32 v[0:1], v[2:3], v[14:15]
	s_nop 0
	v_add_f32_e32 v0, v0, v1
	v_cvt_pk_bf16_f32 v71, v4, v0
	v_lshlrev_b64 v[0:1], 2, v[12:13]
	v_lshl_add_u64 v[2:3], s[78:79], 0, v[0:1]
	v_lshl_add_u64 v[0:1], s[44:45], 0, v[0:1]
	global_load_dword v21, v[0:1], off
	global_load_dword v20, v[2:3], off
	s_waitcnt vmcnt(1)
	v_mul_f32_e32 v1, v16, v21
	v_mul_f32_e32 v2, 0.15915494, v1
	s_waitcnt vmcnt(0)
	v_mul_f32_e32 v0, v16, v20
	v_rndne_f32_e32 v2, v2
	v_mul_f32_e32 v0, 0x3fb8aa3b, v0
	v_fma_f32 v1, v1, 0.15915494, -v2
	v_exp_f32_e32 v0, v0
	v_sin_f32_e32 v3, v1
	v_cos_f32_e32 v2, v1
	v_mov_b32_e32 v26, v21
	v_mov_b32_e32 v27, v20
	v_mov_b32_e32 v24, v21
	v_pk_mul_f32 v[108:109], v[0:1], v[2:3] op_sel_hi:[0,1]
	v_pk_mul_f32 v[0:1], v[20:21], v[20:21]
	v_add_f32_e32 v16, -1.0, v108
	v_add_f32_e32 v0, v0, v1
	v_div_scale_f32 v1, s[42:43], v0, v0, 1.0
	v_rcp_f32_e32 v2, v1
	v_pk_mul_f32 v[16:17], v[26:27], v[16:17] op_sel:[1,0] op_sel_hi:[0,0]
	v_pk_fma_f32 v[20:21], v[24:25], v[108:109], v[16:17] op_sel:[0,1,0]
	v_pk_fma_f32 v[16:17], v[26:27], v[108:109], v[16:17] op_sel:[0,1,0] neg_lo:[0,0,1] neg_hi:[0,0,1]
	v_fma_f32 v3, -v1, v2, 1.0
	v_fmac_f32_e32 v2, v3, v2
	v_div_scale_f32 v3, vcc, 1.0, v0, 1.0
	v_mul_f32_e32 v4, v3, v2
	v_fma_f32 v5, -v1, v4, v3
	v_fmac_f32_e32 v4, v5, v2
	v_fma_f32 v1, -v1, v4, v3
	v_div_fmas_f32 v1, v1, v2, v4
	v_div_fixup_f32 v22, v1, v0, 1.0
	v_lshlrev_b64 v[0:1], 6, v[12:13]
	v_lshl_add_u64 v[4:5], v[92:93], 0, v[0:1]
	v_lshl_add_u64 v[12:13], v[94:95], 0, v[0:1]
	global_load_dwordx4 v[0:3], v[4:5], off offset:16
	global_load_dwordx4 v[8:11], v[4:5], off
	s_nop 0
	global_load_dwordx4 v[4:7], v[12:13], off offset:16
	s_nop 0
	global_load_dwordx4 v[12:15], v[12:13], off
	v_mov_b32_e32 v21, v17
	v_pk_mul_f32 v[16:17], v[22:23], v[20:21] op_sel_hi:[0,1]
	v_mov_b32_e32 v110, v109
	v_mov_b32_e32 v111, v109
	v_mov_b32_e32 v114, v108
	v_mov_b32_e32 v115, v108
	v_pk_mov_b32 v[118:119], v[108:109], v[108:109] op_sel:[1,0]
	s_mov_b64 s[42:43], 0
	s_waitcnt vmcnt(2)
	v_mov_b32_e32 v20, v8
	s_waitcnt vmcnt(0)
; template <int MODE>
; __device__ __forceinline__ void ssm_unit(const Ctx& P, int li, int g, int cidx, LAS unsigned char* hs, const bf16_t* H, bf16_t* Z, float* E, int lane) {
;     ...
;         wr_.x = pk_bf16(cre * br0[0] - cim * bi0[0], cre * br0[1] - cim * bi0[1]); wr_.y = pk_bf16(cre * br0[2] - cim * bi0[2], cre * br0[3] - cim * bi0[3]);
;         wr_.z = pk_bf16(cre * br1[0] - cim * bi1[0], cre * br1[1] - cim * bi1[1]); wr_.w = pk_bf16(cre * br1[2] - cim * bi1[2], cre * br1[3] - cim * bi1[3]);
;         wi_.x = pk_bf16(cre * bi0[0] + cim * br0[0], cre * bi0[1] + cim * br0[1]); wi_.y = pk_bf16(cre * bi0[2] + cim * br0[2], cre * bi0[3] + cim * br0[3]);
;         wi_.z = pk_bf16(cre * bi1[0] + cim * br1[0], cre * bi1[1] + cim * br1[1]); wi_.w = pk_bf16(cre * bi1[2] + cim * br1[2], cre * bi1[3] + cim * br1[3]);
;         Bf[2 * s] = __builtin_bit_cast(bf16x8, wr_); Bf[2 * s + 1] = __builtin_bit_cast(bf16x8, wi_); }
;     float hr[2] = {0.f, 0.f}, hi[2] = {0.f, 0.f};
;     if (MODE == 1) {
; #pragma unroll
;         for (int s = 0; s < 2; ++s) { float pr = lre[s], pi = lim[s];
; #pragma unroll
;             for (int q = 0; q < 7; ++q) { const float t = pr * pr - pi * pi; pi = 2.0f * pr * pi; pr = t; }
;             const int p = c + 32 * s;
; #pragma unroll 8
;             for (int j = 0; j < cidx; ++j) { const float* ep = E + (((size_t)(half * 32 + j) * 128 + g) * 64 + p) * 2; const float er = ep[0], ei = ep[1];
;                 const float t = hr[s] * pr - hi[s] * pi + er; hi[s] = hr[s] * pi + hi[s] * pr + ei; hr[s] = t; } }
;     }
;     bf16x8 Cf[4];
;     if (MODE >= 1) {
;         const float* crp = P.in[I_CRE] + ((size_t)(li * 128 + g) * 16 + fr) * 64; const float* cip = P.in[I_CIM] + ((size_t)(li * 128 + g) * 16 + fr) * 64;
; #pragma unroll
;         for (int kk = 0; kk < 4; ++kk) { const int c0 = 8 * kk + 2 * fq;
;             const float r0 = crp[c0], r1 = crp[c0 + 1], r2 = crp[c0 + 32], r3 = crp[c0 + 33];
;             const float i0 = cip[c0], i1 = cip[c0 + 1], i2 = cip[c0 + 32], i3 = cip[c0 + 33];
;             u32x4 w; w.x = pk_bf16(r0, -i0); w.y = pk_bf16(r2, -i2); w.z = pk_bf16(r1, -i1); w.w = pk_bf16(r3, -i3);
;             Cf[kk] = __builtin_bit_cast(bf16x8, w); }
;     }
;     const int nblk = (MODE == 2) ? 1 : 8;
;     for (int blk = 0; blk < nblk; ++blk) {
;         {   const int bsel = (c >> 2) & 1, tj = (c & 3) + 4 * (c >> 3);
	v_mov_b32_e32 v21, v12
	v_pk_mul_f32 v[20:21], v[20:21], v[16:17]
	s_nop 0
	v_sub_f32_e32 v19, v20, v21
	v_mov_b32_e32 v20, v9
	v_mov_b32_e32 v21, v13
	v_pk_mul_f32 v[20:21], v[20:21], v[16:17]
	s_nop 0
	v_sub_f32_e32 v20, v20, v21
	v_cvt_pk_bf16_f32 v72, v19, v20
	v_mov_b32_e32 v20, v10
	v_mov_b32_e32 v21, v14
	v_pk_mul_f32 v[20:21], v[20:21], v[16:17]
	s_nop 0
	v_sub_f32_e32 v19, v20, v21
	v_mov_b32_e32 v20, v11
	v_mov_b32_e32 v21, v15
	v_pk_mul_f32 v[20:21], v[20:21], v[16:17]
	s_nop 0
	v_sub_f32_e32 v20, v20, v21
	v_cvt_pk_bf16_f32 v73, v19, v20
	v_mov_b32_e32 v20, v0
	v_mov_b32_e32 v21, v4
	v_pk_mul_f32 v[20:21], v[20:21], v[16:17]
	s_nop 0
	v_sub_f32_e32 v19, v20, v21
	v_mov_b32_e32 v20, v1
	v_mov_b32_e32 v21, v5
	v_pk_mul_f32 v[20:21], v[20:21], v[16:17]
	s_nop 0
	v_sub_f32_e32 v20, v20, v21
	v_cvt_pk_bf16_f32 v74, v19, v20
	v_mov_b32_e32 v20, v2
	v_mov_b32_e32 v21, v6
	v_pk_mul_f32 v[20:21], v[20:21], v[16:17]
	s_nop 0
	v_sub_f32_e32 v19, v20, v21
	v_mov_b32_e32 v20, v3
	v_mov_b32_e32 v21, v7
	v_pk_mul_f32 v[20:21], v[20:21], v[16:17]
	s_nop 0
	v_sub_f32_e32 v20, v20, v21
	v_mov_b32_e32 v21, v8
	v_mov_b32_e32 v8, v13
	v_cvt_pk_bf16_f32 v75, v19, v20
	v_mov_b32_e32 v20, v12
	v_pk_mul_f32 v[8:9], v[8:9], v[16:17]
	v_pk_mul_f32 v[20:21], v[20:21], v[16:17]
	v_add_f32_e32 v8, v8, v9
	v_add_f32_e32 v12, v20, v21
	v_cvt_pk_bf16_f32 v76, v12, v8
	v_mov_b32_e32 v8, v14
	v_mov_b32_e32 v9, v10
	v_pk_mul_f32 v[8:9], v[8:9], v[16:17]
	v_mov_b32_e32 v10, v15
	v_add_f32_e32 v12, v8, v9
	v_pk_mul_f32 v[8:9], v[10:11], v[16:17]
	s_nop 0
	v_add_f32_e32 v8, v8, v9
	v_mov_b32_e32 v9, v0
	v_mov_b32_e32 v0, v5
	v_cvt_pk_bf16_f32 v77, v12, v8
	v_mov_b32_e32 v8, v4
	v_pk_mul_f32 v[0:1], v[0:1], v[16:17]
	v_pk_mul_f32 v[8:9], v[8:9], v[16:17]
	v_add_f32_e32 v0, v0, v1
	v_add_f32_e32 v4, v8, v9
	v_cvt_pk_bf16_f32 v78, v4, v0
	v_mov_b32_e32 v0, v6
	v_mov_b32_e32 v1, v2
	v_pk_mul_f32 v[0:1], v[0:1], v[16:17]
	v_mov_b32_e32 v2, v7
	v_add_f32_e32 v4, v0, v1
	v_pk_mul_f32 v[0:1], v[2:3], v[16:17]
	s_nop 0
	v_add_f32_e32 v0, v0, v1
	v_cvt_pk_bf16_f32 v79, v4, v0
	v_lshlrev_b64 v[0:1], 19, v[80:81]
	v_lshl_or_b32 v0, v18, 5, v0
	v_lshl_add_u64 v[120:121], v[102:103], 0, v[0:1]
	s_nop 0
	global_load_dwordx4 v[212:215], v[120:121], off
	s_waitcnt vmcnt(0)
; __device__ __forceinline__ f32x16 mfma32(bf16x8 a, bf16x8 b, f32x16 c) { return __builtin_amdgcn_mfma_f32_32x32x16_bf16(a, b, c, 0, 0, 0); }
; template <int MODE>
; __device__ __forceinline__ void ssm_unit(const Ctx& P, int li, int g, int cidx, LAS unsigned char* hs, const bf16_t* H, bf16_t* Z, float* E, int lane) {
;     ...
;     for (int blk = 0; blk < nblk; ++blk) {
;         {   const int bsel = (c >> 2) & 1, tj = (c & 3) + 4 * (c >> 3);
;             const size_t rowg = (MODE == 2) ? (size_t)TP + 32 * cidx + 16 * bsel + tj : (size_t)bsel * SEQ + (size_t)cidx * 128 + blk * 16 + tj;
;             const bf16x8 af = *(const bf16x8*)(H + rowg * DM + g * 16 + 8 * half);
;             const f32x16 z16 = {0.f, 0.f, 0.f, 0.f, 0.f, 0.f, 0.f, 0.f, 0.f, 0.f, 0.f, 0.f, 0.f, 0.f, 0.f, 0.f};
;             const f32x16 d0 = mfma32(af, Bf[0], z16), d1 = mfma32(af, Bf[1], z16), d2 = mfma32(af, Bf[2], z16), d3 = mfma32(af, Bf[3], z16);
; #pragma unroll
;             for (int r = 0; r < 16; ++r) {
;                 if (MODE == 2 && (r & 3) == 0) { const int batch = 8 * cidx + 4 * half + (r >> 2); const size_t sp = ((size_t)(li * 32 + batch) * 128 + g) * 64 + c;
;                     hr[0] = P.in[I_SSRE][sp]; hi[0] = P.in[I_SSIM][sp]; hr[1] = P.in[I_SSRE][sp + 32]; hi[1] = P.in[I_SSIM][sp + 32]; }
;                 { const float t = lre[0] * hr[0] - lim[0] * hi[0] + d0[r]; hi[0] = lre[0] * hi[0] + lim[0] * hr[0] + d1[r]; hr[0] = t; }
;                 { const float t = lre[1] * hr[1] - lim[1] * hi[1] + d2[r]; hi[1] = lre[1] * hi[1] + lim[1] * hr[1] + d3[r]; hr[1] = t; }
;     ...
;     if (MODE == 0) {
; #pragma unroll
;         for (int s = 0; s < 2; ++s) { float* ep = E + (((size_t)(half * 32 + cidx) * 128 + g) * 64 + c + 32 * s) * 2; ep[0] = hr[s]; ep[1] = hi[s]; }
;     }
.LBB0_104:
	v_lshl_add_u64 v[0:1], v[120:121], 0, s[42:43]
	v_mov_b64_e32 v[16:17], v[212:213]
	v_mov_b64_e32 v[18:19], v[214:215]
	v_add_co_u32_e32 v0, vcc, 0x10000, v0
	s_add_u32 s42, s42, 0x10000
	s_addc_u32 s43, s43, 0
	v_addc_co_u32_e32 v1, vcc, 0, v1, vcc
	s_cmp_lg_u32 s42, 0x80000
	global_load_dwordx4 v[212:215], v[0:1], off
	v_mfma_f32_32x32x16_bf16 v[32:47], v[16:19], v[64:67], 0
	v_mfma_f32_32x32x16_bf16 v[48:63], v[16:19], v[68:71], 0
	v_mfma_f32_32x32x16_bf16 v[0:15], v[16:19], v[72:75], 0
	v_mfma_f32_32x32x16_bf16 v[16:31], v[16:19], v[76:79], 0
	s_nop 11
	v_fma_f32 v216, -v83, v125, v32
	v_fma_f32 v217, v83, v124, v48
	v_fma_f32 v218, -v109, v123, v0
	v_fma_f32 v219, v109, v122, v16
	v_fma_f32 v124, v82, v124, v216
	v_fma_f32 v125, v82, v125, v217
	v_fma_f32 v122, v108, v122, v218
	v_fma_f32 v123, v108, v123, v219
	v_fma_f32 v220, -v83, v125, v33
	v_fma_f32 v221, v83, v124, v49
	v_fma_f32 v222, -v109, v123, v1
	v_fma_f32 v223, v109, v122, v17
	v_fma_f32 v124, v82, v124, v220
	v_fma_f32 v125, v82, v125, v221
	v_fma_f32 v122, v108, v122, v222
	v_fma_f32 v123, v108, v123, v223
	v_fma_f32 v216, -v83, v125, v34
	v_fma_f32 v217, v83, v124, v50
	v_fma_f32 v218, -v109, v123, v2
	v_fma_f32 v219, v109, v122, v18
	v_fma_f32 v124, v82, v124, v216
	v_fma_f32 v125, v82, v125, v217
	v_fma_f32 v122, v108, v122, v218
	v_fma_f32 v123, v108, v123, v219
	v_fma_f32 v220, -v83, v125, v35
	v_fma_f32 v221, v83, v124, v51
	v_fma_f32 v222, -v109, v123, v3
	v_fma_f32 v223, v109, v122, v19
	v_fma_f32 v124, v82, v124, v220
	v_fma_f32 v125, v82, v125, v221
	v_fma_f32 v122, v108, v122, v222
	v_fma_f32 v123, v108, v123, v223
	v_fma_f32 v216, -v83, v125, v36
	v_fma_f32 v217, v83, v124, v52
	v_fma_f32 v218, -v109, v123, v4
	v_fma_f32 v219, v109, v122, v20
	v_fma_f32 v124, v82, v124, v216
	v_fma_f32 v125, v82, v125, v217
	v_fma_f32 v122, v108, v122, v218
	v_fma_f32 v123, v108, v123, v219
	v_fma_f32 v220, -v83, v125, v37
	v_fma_f32 v221, v83, v124, v53
	v_fma_f32 v222, -v109, v123, v5
	v_fma_f32 v223, v109, v122, v21
	v_fma_f32 v124, v82, v124, v220
	v_fma_f32 v125, v82, v125, v221
	v_fma_f32 v122, v108, v122, v222
	v_fma_f32 v123, v108, v123, v223
	v_fma_f32 v216, -v83, v125, v38
	v_fma_f32 v217, v83, v124, v54
	v_fma_f32 v218, -v109, v123, v6
	v_fma_f32 v219, v109, v122, v22
	v_fma_f32 v124, v82, v124, v216
	v_fma_f32 v125, v82, v125, v217
	v_fma_f32 v122, v108, v122, v218
	v_fma_f32 v123, v108, v123, v219
	v_fma_f32 v220, -v83, v125, v39
	v_fma_f32 v221, v83, v124, v55
	v_fma_f32 v222, -v109, v123, v7
	v_fma_f32 v223, v109, v122, v23
	v_fma_f32 v124, v82, v124, v220
	v_fma_f32 v125, v82, v125, v221
	v_fma_f32 v122, v108, v122, v222
	v_fma_f32 v123, v108, v123, v223
	v_fma_f32 v216, -v83, v125, v40
	v_fma_f32 v217, v83, v124, v56
	v_fma_f32 v218, -v109, v123, v8
	v_fma_f32 v219, v109, v122, v24
	v_fma_f32 v124, v82, v124, v216
	v_fma_f32 v125, v82, v125, v217
	v_fma_f32 v122, v108, v122, v218
	v_fma_f32 v123, v108, v123, v219
	v_fma_f32 v220, -v83, v125, v41
	v_fma_f32 v221, v83, v124, v57
	v_fma_f32 v222, -v109, v123, v9
	v_fma_f32 v223, v109, v122, v25
	v_fma_f32 v124, v82, v124, v220
	v_fma_f32 v125, v82, v125, v221
	v_fma_f32 v122, v108, v122, v222
	v_fma_f32 v123, v108, v123, v223
	v_fma_f32 v216, -v83, v125, v42
	v_fma_f32 v217, v83, v124, v58
	v_fma_f32 v218, -v109, v123, v10
	v_fma_f32 v219, v109, v122, v26
	v_fma_f32 v124, v82, v124, v216
	v_fma_f32 v125, v82, v125, v217
	v_fma_f32 v122, v108, v122, v218
	v_fma_f32 v123, v108, v123, v219
	v_fma_f32 v220, -v83, v125, v43
	v_fma_f32 v221, v83, v124, v59
	v_fma_f32 v222, -v109, v123, v11
	v_fma_f32 v223, v109, v122, v27
	v_fma_f32 v124, v82, v124, v220
	v_fma_f32 v125, v82, v125, v221
	v_fma_f32 v122, v108, v122, v222
	v_fma_f32 v123, v108, v123, v223
	v_fma_f32 v216, -v83, v125, v44
	v_fma_f32 v217, v83, v124, v60
	v_fma_f32 v218, -v109, v123, v12
	v_fma_f32 v219, v109, v122, v28
	v_fma_f32 v124, v82, v124, v216
	v_fma_f32 v125, v82, v125, v217
	v_fma_f32 v122, v108, v122, v218
	v_fma_f32 v123, v108, v123, v219
	v_fma_f32 v220, -v83, v125, v45
	v_fma_f32 v221, v83, v124, v61
	v_fma_f32 v222, -v109, v123, v13
	v_fma_f32 v223, v109, v122, v29
	v_fma_f32 v124, v82, v124, v220
	v_fma_f32 v125, v82, v125, v221
	v_fma_f32 v122, v108, v122, v222
	v_fma_f32 v123, v108, v123, v223
	v_fma_f32 v216, -v83, v125, v46
	v_fma_f32 v217, v83, v124, v62
	v_fma_f32 v218, -v109, v123, v14
	v_fma_f32 v219, v109, v122, v30
	v_fma_f32 v124, v82, v124, v216
	v_fma_f32 v125, v82, v125, v217
	v_fma_f32 v122, v108, v122, v218
	v_fma_f32 v123, v108, v123, v219
	v_fma_f32 v220, -v83, v125, v47
	v_fma_f32 v221, v83, v124, v63
	v_fma_f32 v222, -v109, v123, v15
	v_fma_f32 v223, v109, v122, v31
	v_fma_f32 v124, v82, v124, v220
	v_fma_f32 v125, v82, v125, v221
	v_fma_f32 v122, v108, v122, v222
	v_fma_f32 v123, v108, v123, v223
	s_waitcnt vmcnt(0)
	s_cbranch_scc1 .LBB0_104
	v_add_u32_e32 v0, v80, v90
	v_ashrrev_i32_e32 v1, 31, v0
	v_lshlrev_b64 v[0:1], 13, v[0:1]
	v_lshl_or_b32 v0, v134, 6, v0
	v_or_b32_e32 v0, v0, v84
	v_lshl_add_u64 v[0:1], v[0:1], 3, s[26:27]
	global_store_dwordx2 v[0:1], v[124:125], off
	global_store_dwordx2 v[0:1], v[122:123], off offset:256
	s_branch .LBB0_99

; __device__ __forceinline__ float bf2f(bf16_t b) { return __uint_as_float(((unsigned)b) << 16); }
; __device__ __forceinline__ float ret_lg2(int h) { return log2f(1.0f - exp2f(-5.0f - (float)h)); }
; __device__ __forceinline__ void ret_sample_unit(const Ctx& P, int li, int b, int h, LAS unsigned char* lds, const bf16_t* PROJ, bf16_t* H, int tid) {
;     ...
;     const float lg2 = ret_lg2(h);
;     const size_t prow = (size_t)TP + 4 * b;
;     for (int idx = tid; idx < 1536; idx += NTHREADS) { const int which = idx >> 9, r = idx & 511, t = r >> 7, d = r & 127;
;         const float v = bf2f(PROJ[(prow + t) * EIN + which * 1024 + h * 128 + d]);
;         if (which == 0) qs[r] = v; else if (which == 1) ks[r] = v * 0.08838834764831845f; else vs[r] = v; }
;     __syncthreads();
;     const int e = tid & 127, dq = tid >> 7;
;     const float g1 = exp2f(lg2), g2 = g1 * g1, g3 = g2 * g1, g4 = g2 * g2;
;     const float* S0 = P.in[I_SRET] + ((size_t)((li * 32 + b) * 8 + h)) * 16384;
;     float* S1 = P.out + O_RETS + ((size_t)((li * 32 + b) * 8 + h)) * 16384;
;     const float v0 = vs[e], v1 = vs[128 + e], v2 = vs[256 + e], v3 = vs[384 + e];
;     float a0 = 0.f, a1 = 0.f, a2 = 0.f, a3 = 0.f;
;     for (int dd = 0; dd < 32; ++dd) { const int d = dq * 32 + dd;
;         const float s0 = S0[(size_t)d * 128 + e];
;         const float sn = g4 * s0 + ks[d] * g3 * v0 + ks[128 + d] * g2 * v1 + ks[256 + d] * g1 * v2 + ks[384 + d] * v3;
;         S1[(size_t)d * 128 + e] = sn;
;         a0 += qs[d] * s0; a1 += qs[128 + d] * s0; a2 += qs[256 + d] * s0; a3 += qs[384 + d] * s0; }
.LBB0_473:
	s_or_b64 exec, exec, s[0:1]
	v_cvt_f32_ubyte0_e32 v0, s39
	v_sub_f32_e32 v0, 0xc0a00000, v0
	v_cmp_gt_f32_e32 vcc, s34, v0
	s_and_b64 s[0:1], vcc, exec
	s_cselect_b32 s0, 0xffffffc0, 0
	v_cndmask_b32_e32 v1, 0, v168, vcc
	v_add_f32_e32 v0, v0, v1
	v_exp_f32_e32 v0, v0
	v_lshl_add_u32 v4, v128, 2, 0
	s_waitcnt lgkmcnt(0)
	s_barrier
	v_ldexp_f32 v0, v0, s0
	v_sub_f32_e32 v0, 1.0, v0
	v_cmp_gt_f32_e32 vcc, s43, v0
	s_and_b64 s[0:1], vcc, exec
	s_cselect_b32 s0, 32, 0
	v_ldexp_f32 v0, v0, s0
	v_log_f32_e32 v0, v0
	v_cndmask_b32_e32 v1, 0, v170, vcc
	s_and_b32 s0, s38, 0xf8
	s_add_i32 s0, s22, s0
	v_sub_f32_e32 v1, v0, v1
	v_cmp_gt_f32_e32 vcc, s34, v1
	s_and_b32 s1, s31, 7
	s_add_i32 s0, s0, s1
	v_cndmask_b32_e32 v0, 0, v168, vcc
	v_add_f32_e32 v0, v1, v0
	s_ashr_i32 s1, s0, 31
	v_exp_f32_e32 v2, v0
	s_lshl_b64 s[0:1], s[0:1], 16
	s_and_b64 s[4:5], vcc, exec
	v_ashrrev_i32_e32 v0, 7, v47
	s_cselect_b32 s4, 0xffffffc0, 0
	s_waitcnt vmcnt(6)
	v_ldexp_f32 v20, v2, s4
	ds_read2st64_b32 v[2:3], v4 offset0:20 offset1:22
	v_lshlrev_b32_e32 v12, 5, v0
	ds_read2st64_b32 v[4:5], v4 offset0:16 offset1:18
	v_ashrrev_i32_e32 v13, 31, v12
	v_lshlrev_b64 v[12:13], 9, v[12:13]
	v_lshl_add_u64 v[12:13], s[0:1], 0, v[12:13]
	v_readlane_b32 s0, v252, 39
	v_readlane_b32 s44, v254, 51
	v_mov_b32_e32 v10, 0
	v_mul_f32_e32 v7, v20, v20
	v_lshl_add_u64 v[14:15], v[16:17], 2, v[12:13]
	v_readlane_b32 s1, v252, 40
	v_and_b32_e32 v11, 0xffffff80, v47
	v_readlane_b32 s48, v254, 55
	v_readlane_b32 s49, v254, 56
	v_mul_f32_e32 v6, v20, v7
	v_mul_f32_e32 v21, v7, v7
	s_waitcnt lgkmcnt(1)
	v_mov_b32_e32 v8, v3
	v_mov_b32_e32 v9, v2
	v_lshl_add_u64 v[12:13], s[0:1], 0, v[14:15]
	v_add_u32_e32 v22, 0, v11
	v_lshl_add_u64 v[14:15], s[48:49], 0, v[14:15]
	s_mov_b64 s[0:1], 0
	v_mov_b32_e32 v11, v10
	v_mov_b32_e32 v18, v10
	v_mov_b32_e32 v19, v10
	v_readlane_b32 s45, v254, 52
	v_readlane_b32 s46, v254, 53
	v_readlane_b32 s47, v254, 54
	v_readlane_b32 s50, v254, 57
	v_readlane_b32 s51, v254, 58
	v_readlane_b32 s52, v254, 59
	v_readlane_b32 s53, v254, 60
	v_readlane_b32 s54, v254, 61
	v_readlane_b32 s55, v254, 62
	v_readlane_b32 s56, v254, 63
	v_readlane_b32 s57, v252, 0
	v_readlane_b32 s58, v252, 1
	v_readlane_b32 s59, v252, 2
	v_lshrrev_b32_e32 v201, 6, v47
	v_and_b32_e32 v200, 63, v47
	v_lshlrev_b32_e32 v201, 13, v201
	v_add_u32_e32 v201, 0x10000, v201
	v_lshl_add_u32 v200, v200, 2, v201
	v_mov_b64_e32 v[202:203], v[14:15]
	v_readfirstlane_b32 s4, v201
	s_mov_b32 s5, 0
	s_mov_b32 m0, s4
	s_movk_i32 s4, 0x200
	global_load_lds_dword v[202:203], off
	v_lshl_add_u64 v[202:203], v[202:203], 0, s[4:5]
	s_add_i32 m0, m0, 0x100
	s_nop 0
	global_load_lds_dword v[202:203], off
	v_lshl_add_u64 v[202:203], v[202:203], 0, s[4:5]
	s_add_i32 m0, m0, 0x100
	s_nop 0
	global_load_lds_dword v[202:203], off
	v_lshl_add_u64 v[202:203], v[202:203], 0, s[4:5]
	s_add_i32 m0, m0, 0x100
	s_nop 0
	global_load_lds_dword v[202:203], off
	v_lshl_add_u64 v[202:203], v[202:203], 0, s[4:5]
	s_add_i32 m0, m0, 0x100
	s_nop 0
	global_load_lds_dword v[202:203], off
	v_lshl_add_u64 v[202:203], v[202:203], 0, s[4:5]
	s_add_i32 m0, m0, 0x100
	s_nop 0
	global_load_lds_dword v[202:203], off
	v_lshl_add_u64 v[202:203], v[202:203], 0, s[4:5]
	s_add_i32 m0, m0, 0x100
	s_nop 0
	global_load_lds_dword v[202:203], off
	v_lshl_add_u64 v[202:203], v[202:203], 0, s[4:5]
	s_add_i32 m0, m0, 0x100
	s_nop 0
	global_load_lds_dword v[202:203], off
	v_lshl_add_u64 v[202:203], v[202:203], 0, s[4:5]
	s_add_i32 m0, m0, 0x100
	s_nop 0
	global_load_lds_dword v[202:203], off
	v_lshl_add_u64 v[202:203], v[202:203], 0, s[4:5]
	s_add_i32 m0, m0, 0x100
	s_nop 0
	global_load_lds_dword v[202:203], off
	v_lshl_add_u64 v[202:203], v[202:203], 0, s[4:5]
	s_add_i32 m0, m0, 0x100
	s_nop 0
	global_load_lds_dword v[202:203], off
	v_lshl_add_u64 v[202:203], v[202:203], 0, s[4:5]
	s_add_i32 m0, m0, 0x100
	s_nop 0
	global_load_lds_dword v[202:203], off
	v_lshl_add_u64 v[202:203], v[202:203], 0, s[4:5]
	s_add_i32 m0, m0, 0x100
	s_nop 0
	global_load_lds_dword v[202:203], off
	v_lshl_add_u64 v[202:203], v[202:203], 0, s[4:5]
	s_add_i32 m0, m0, 0x100
	s_nop 0
	global_load_lds_dword v[202:203], off
	v_lshl_add_u64 v[202:203], v[202:203], 0, s[4:5]
	s_add_i32 m0, m0, 0x100
	s_nop 0
	global_load_lds_dword v[202:203], off
	v_lshl_add_u64 v[202:203], v[202:203], 0, s[4:5]
	s_add_i32 m0, m0, 0x100
	s_nop 0
	global_load_lds_dword v[202:203], off
	v_lshl_add_u64 v[202:203], v[202:203], 0, s[4:5]
	s_add_i32 m0, m0, 0x100
	s_nop 0
	global_load_lds_dword v[202:203], off
	v_lshl_add_u64 v[202:203], v[202:203], 0, s[4:5]
	s_add_i32 m0, m0, 0x100
	s_nop 0
	global_load_lds_dword v[202:203], off
	v_lshl_add_u64 v[202:203], v[202:203], 0, s[4:5]
	s_add_i32 m0, m0, 0x100
	s_nop 0
	global_load_lds_dword v[202:203], off
	v_lshl_add_u64 v[202:203], v[202:203], 0, s[4:5]
	s_add_i32 m0, m0, 0x100
	s_nop 0
	global_load_lds_dword v[202:203], off
	v_lshl_add_u64 v[202:203], v[202:203], 0, s[4:5]
	s_add_i32 m0, m0, 0x100
	s_nop 0
	global_load_lds_dword v[202:203], off
	v_lshl_add_u64 v[202:203], v[202:203], 0, s[4:5]
	s_add_i32 m0, m0, 0x100
	s_nop 0
	global_load_lds_dword v[202:203], off
	v_lshl_add_u64 v[202:203], v[202:203], 0, s[4:5]
	s_add_i32 m0, m0, 0x100
	s_nop 0
	global_load_lds_dword v[202:203], off
	v_lshl_add_u64 v[202:203], v[202:203], 0, s[4:5]
	s_add_i32 m0, m0, 0x100
	s_nop 0
	global_load_lds_dword v[202:203], off
	v_lshl_add_u64 v[202:203], v[202:203], 0, s[4:5]
	s_add_i32 m0, m0, 0x100
	s_nop 0
	global_load_lds_dword v[202:203], off
	v_lshl_add_u64 v[202:203], v[202:203], 0, s[4:5]
	s_add_i32 m0, m0, 0x100
	s_nop 0
	global_load_lds_dword v[202:203], off
	v_lshl_add_u64 v[202:203], v[202:203], 0, s[4:5]
	s_add_i32 m0, m0, 0x100
	s_nop 0
	global_load_lds_dword v[202:203], off
	v_lshl_add_u64 v[202:203], v[202:203], 0, s[4:5]
	s_add_i32 m0, m0, 0x100
	s_nop 0
	global_load_lds_dword v[202:203], off
	v_lshl_add_u64 v[202:203], v[202:203], 0, s[4:5]
	s_add_i32 m0, m0, 0x100
	s_nop 0
	global_load_lds_dword v[202:203], off
	v_lshl_add_u64 v[202:203], v[202:203], 0, s[4:5]
	s_add_i32 m0, m0, 0x100
	s_nop 0
	global_load_lds_dword v[202:203], off
	v_lshl_add_u64 v[202:203], v[202:203], 0, s[4:5]
	s_add_i32 m0, m0, 0x100
	s_nop 0
	global_load_lds_dword v[202:203], off
	v_lshl_add_u64 v[202:203], v[202:203], 0, s[4:5]
	s_add_i32 m0, m0, 0x100
	s_nop 0
	global_load_lds_dword v[202:203], off
	s_waitcnt vmcnt(0)
; __device__ __forceinline__ void ret_sample_unit(const Ctx& P, int li, int b, int h, LAS unsigned char* lds, const bf16_t* PROJ, bf16_t* H, int tid) {
;     ...
;     for (int dd = 0; dd < 32; ++dd) { const int d = dq * 32 + dd;
;         const float s0 = S0[(size_t)d * 128 + e];
;         const float sn = g4 * s0 + ks[d] * g3 * v0 + ks[128 + d] * g2 * v1 + ks[256 + d] * g1 * v2 + ks[384 + d] * v3;
;         S1[(size_t)d * 128 + e] = sn;
;         a0 += qs[d] * s0; a1 += qs[128 + d] * s0; a2 += qs[256 + d] * s0; a3 += qs[384 + d] * s0; }
;     part[(dq * 4 + 0) * 128 + e] = a0; part[(dq * 4 + 1) * 128 + e] = a1; part[(dq * 4 + 2) * 128 + e] = a2; part[(dq * 4 + 3) * 128 + e] = a3;
;     if (tid < 16) { const int i = tid >> 2, j = tid & 3; float a = 0.f;
;         if (j <= i) { for (int d = 0; d < 128; ++d) a += qs[i * 128 + d] * ks[j * 128 + d]; a *= exp2f(lg2 * (float)(i - j)); }
;         am[tid] = a; }
.LBB0_474:
	ds_read_b32 v42, v200
	ds_read2st64_b64 v[24:27], v22 offset0:4 offset1:5
	s_mov_b32 s4, 0x4300000
	s_waitcnt lgkmcnt(0)
	v_mov_b32_e32 v28, v24
	v_mov_b32_e32 v29, v26
	v_pk_mul_f32 v[28:29], v[6:7], v[28:29]
	v_mov_b32_e32 v26, v25
	v_pk_mul_f32 v[28:29], v[4:5], v[28:29]
	v_pk_mul_f32 v[26:27], v[6:7], v[26:27]
	v_fma_f32 v23, v21, v42, v28
	v_add_f32_e32 v23, v23, v29
	ds_read2st64_b64 v[28:31], v22 offset0:6 offset1:7
	v_pk_mul_f32 v[26:27], v[4:5], v[26:27]
	s_waitcnt lgkmcnt(0)
	v_mul_f32_e32 v33, v20, v28
	v_mov_b32_e32 v32, v30
	v_pk_mul_f32 v[32:33], v[8:9], v[32:33]
	s_nop 0
	v_add_f32_e32 v23, v23, v33
	v_add_f32_e32 v23, v32, v23
	v_lshl_add_u64 v[32:33], v[12:13], 0, s[0:1]
	v_add_co_u32_e32 v44, vcc, s4, v32
	s_add_u32 s0, s0, 0x400
	s_nop 0
	v_addc_co_u32_e32 v45, vcc, 0, v33, vcc
	global_store_dword v[44:45], v23, off
	ds_read_b32 v24, v200 offset:256
	ds_read2st64_b64 v[32:35], v22 offset1:1
	s_addc_u32 s1, s1, 0
	s_cmpk_eq_i32 s0, 0x4000
	s_waitcnt lgkmcnt(0)
	v_mov_b32_e32 v36, v32
	v_mov_b32_e32 v37, v34
	v_pk_fma_f32 v[10:11], v[42:43], v[36:37], v[10:11] op_sel_hi:[0,1,1]
	ds_read2st64_b64 v[36:39], v22 offset0:2 offset1:3
	v_mov_b32_e32 v34, v33
	v_add_u32_e32 v22, 8, v22
	s_waitcnt lgkmcnt(0)
	v_mov_b32_e32 v48, v36
	v_mov_b32_e32 v49, v38
	v_pk_fma_f32 v[18:19], v[42:43], v[48:49], v[18:19] op_sel_hi:[0,1,1]
	v_mov_b32_e32 v38, v37
	v_add_u32_e32 v200, 0x200, v200
	v_fma_f32 v23, v21, v24, v26
	v_add_f32_e32 v23, v23, v27
	v_mul_f32_e32 v27, v20, v29
	v_mov_b32_e32 v26, v31
	v_pk_mul_f32 v[26:27], v[8:9], v[26:27]
	v_pk_fma_f32 v[10:11], v[24:25], v[34:35], v[10:11] op_sel_hi:[0,1,1]
	v_add_f32_e32 v23, v23, v27
	v_add_f32_e32 v23, v26, v23
	v_pk_fma_f32 v[18:19], v[24:25], v[38:39], v[18:19] op_sel_hi:[0,1,1]
	global_store_dword v[44:45], v23, off offset:512
	s_cbranch_scc0 .LBB0_474
	v_lshlrev_b32_e32 v6, 11, v0
	v_lshlrev_b32_e32 v7, 2, v128
	v_add3_u32 v6, 0, v6, v7
	v_cmp_gt_i32_e32 vcc, 16, v47
	ds_write2st64_b32 v6, v10, v11 offset0:24 offset1:26
	ds_write2st64_b32 v6, v18, v19 offset0:28 offset1:30
	s_and_saveexec_b64 s[0:1], vcc
	s_cbranch_execz .LBB0_479
	v_ashrrev_i32_e32 v6, 2, v47
	v_and_b32_e32 v8, 3, v47
	v_cmp_ge_i32_e32 vcc, v6, v8
	v_mov_b32_e32 v9, 0
	s_and_saveexec_b64 s[4:5], vcc
	s_cbranch_execz .LBB0_478
	v_lshl_add_u32 v9, v6, 9, 0
	v_lshl_add_u32 v46, v8, 9, 0
	ds_read_b128 v[10:13], v9
	ds_read_b128 v[18:21], v9 offset:16
	ds_read_b128 v[22:25], v46 offset:2048
	ds_read_b128 v[26:29], v9 offset:32
	ds_read_b128 v[30:33], v9 offset:48
	ds_read_b128 v[34:37], v46 offset:2064
	ds_read_b128 v[38:41], v46 offset:2080
	ds_read_b128 v[42:45], v46 offset:2096
	s_waitcnt lgkmcnt(5)
	v_fma_f32 v14, v10, v22, 0
	v_fmac_f32_e32 v14, v11, v23
	v_fmac_f32_e32 v14, v12, v24
	v_fmac_f32_e32 v14, v13, v25
	s_waitcnt lgkmcnt(2)
	v_fmac_f32_e32 v14, v18, v34
	v_fmac_f32_e32 v14, v19, v35
	v_fmac_f32_e32 v14, v20, v36
	v_fmac_f32_e32 v14, v21, v37
	s_waitcnt lgkmcnt(1)
	v_fmac_f32_e32 v14, v26, v38
	v_fmac_f32_e32 v14, v27, v39
	v_fmac_f32_e32 v14, v28, v40
	v_fmac_f32_e32 v14, v29, v41
	ds_read_b128 v[10:13], v9 offset:64
	ds_read_b128 v[18:21], v46 offset:2112
	s_waitcnt lgkmcnt(2)
	v_fmac_f32_e32 v14, v30, v42
	v_fmac_f32_e32 v14, v31, v43
	v_fmac_f32_e32 v14, v32, v44
	v_fmac_f32_e32 v14, v33, v45
	ds_read_b128 v[22:25], v9 offset:80
	ds_read_b128 v[26:29], v46 offset:2128
	s_waitcnt lgkmcnt(2)
	v_fmac_f32_e32 v14, v10, v18
	v_fmac_f32_e32 v14, v11, v19
	v_fmac_f32_e32 v14, v12, v20
	v_fmac_f32_e32 v14, v13, v21
	ds_read_b128 v[10:13], v9 offset:96
	ds_read_b128 v[18:21], v46 offset:2144
	s_waitcnt lgkmcnt(2)
	v_fmac_f32_e32 v14, v22, v26
	v_fmac_f32_e32 v14, v23, v27
	v_fmac_f32_e32 v14, v24, v28
	v_fmac_f32_e32 v14, v25, v29
	ds_read_b128 v[22:25], v9 offset:112
	ds_read_b128 v[26:29], v46 offset:2160
	s_waitcnt lgkmcnt(2)
	v_fmac_f32_e32 v14, v10, v18
	v_fmac_f32_e32 v14, v11, v19
	v_fmac_f32_e32 v14, v12, v20
	v_fmac_f32_e32 v14, v13, v21
	ds_read_b128 v[10:13], v9 offset:128
	ds_read_b128 v[18:21], v46 offset:2176
	s_waitcnt lgkmcnt(2)
	v_fmac_f32_e32 v14, v22, v26
	v_fmac_f32_e32 v14, v23, v27
	v_fmac_f32_e32 v14, v24, v28
	v_fmac_f32_e32 v14, v25, v29
	ds_read_b128 v[22:25], v9 offset:144
	ds_read_b128 v[26:29], v46 offset:2192
	s_waitcnt lgkmcnt(2)
	v_fmac_f32_e32 v14, v10, v18
	v_fmac_f32_e32 v14, v11, v19
	v_fmac_f32_e32 v14, v12, v20
	v_fmac_f32_e32 v14, v13, v21
	ds_read_b128 v[10:13], v9 offset:160
	ds_read_b128 v[18:21], v46 offset:2208
	s_waitcnt lgkmcnt(2)
	v_fmac_f32_e32 v14, v22, v26
	v_fmac_f32_e32 v14, v23, v27
	v_fmac_f32_e32 v14, v24, v28
	v_fmac_f32_e32 v14, v25, v29
	ds_read_b128 v[22:25], v9 offset:176
	ds_read_b128 v[26:29], v46 offset:2224
	s_waitcnt lgkmcnt(2)
	v_fmac_f32_e32 v14, v10, v18
	v_fmac_f32_e32 v14, v11, v19
	v_fmac_f32_e32 v14, v12, v20
	v_fmac_f32_e32 v14, v13, v21
	ds_read_b128 v[10:13], v9 offset:192
	ds_read_b128 v[18:21], v46 offset:2240
	s_waitcnt lgkmcnt(2)
; __device__ __forceinline__ void ret_sample_unit(const Ctx& P, int li, int b, int h, LAS unsigned char* lds, const bf16_t* PROJ, bf16_t* H, int tid) {
;     ...
;     if (tid < 16) { const int i = tid >> 2, j = tid & 3; float a = 0.f;
;         if (j <= i) { for (int d = 0; d < 128; ++d) a += qs[i * 128 + d] * ks[j * 128 + d]; a *= exp2f(lg2 * (float)(i - j)); }
;         am[tid] = a; }
;     __syncthreads();
;     { const int i = dq;
;       const float qS = part[(0 * 4 + i) * 128 + e] + part[(1 * 4 + i) * 128 + e] + part[(2 * 4 + i) * 128 + e] + part[(3 * 4 + i) * 128 + e];
;       const float o = am[i * 4 + 0] * v0 + am[i * 4 + 1] * v1 + am[i * 4 + 2] * v2 + am[i * 4 + 3] * v3 + exp2f(lg2 * (float)(i + 1)) * qS;
;       ob[i * 128 + e] = o; }
	v_fmac_f32_e32 v14, v22, v26
	v_fmac_f32_e32 v14, v23, v27
	v_fmac_f32_e32 v14, v24, v28
	v_fmac_f32_e32 v14, v25, v29
	ds_read_b128 v[22:25], v9 offset:208
	ds_read_b128 v[26:29], v46 offset:2256
	s_waitcnt lgkmcnt(2)
	v_fmac_f32_e32 v14, v10, v18
	v_fmac_f32_e32 v14, v11, v19
	v_fmac_f32_e32 v14, v12, v20
	v_fmac_f32_e32 v14, v13, v21
	ds_read_b128 v[10:13], v9 offset:224
	ds_read_b128 v[18:21], v46 offset:2272
	s_waitcnt lgkmcnt(2)
	v_fmac_f32_e32 v14, v22, v26
	v_fmac_f32_e32 v14, v23, v27
	v_fmac_f32_e32 v14, v24, v28
	v_fmac_f32_e32 v14, v25, v29
	ds_read_b128 v[22:25], v9 offset:240
	ds_read_b128 v[26:29], v46 offset:2288
	s_waitcnt lgkmcnt(2)
	v_fmac_f32_e32 v14, v10, v18
	v_fmac_f32_e32 v14, v11, v19
	v_fmac_f32_e32 v14, v12, v20
	v_fmac_f32_e32 v14, v13, v21
	ds_read_b128 v[10:13], v9 offset:256
	ds_read_b128 v[18:21], v46 offset:2304
	s_waitcnt lgkmcnt(2)
	v_fmac_f32_e32 v14, v22, v26
	v_fmac_f32_e32 v14, v23, v27
	v_fmac_f32_e32 v14, v24, v28
	v_fmac_f32_e32 v14, v25, v29
	ds_read_b128 v[22:25], v9 offset:272
	ds_read_b128 v[26:29], v46 offset:2320
	s_waitcnt lgkmcnt(2)
	v_fmac_f32_e32 v14, v10, v18
	v_fmac_f32_e32 v14, v11, v19
	v_fmac_f32_e32 v14, v12, v20
	v_fmac_f32_e32 v14, v13, v21
	ds_read_b128 v[10:13], v9 offset:288
	ds_read_b128 v[18:21], v46 offset:2336
	s_waitcnt lgkmcnt(2)
	v_fmac_f32_e32 v14, v22, v26
	v_fmac_f32_e32 v14, v23, v27
	v_fmac_f32_e32 v14, v24, v28
	v_fmac_f32_e32 v14, v25, v29
	ds_read_b128 v[22:25], v9 offset:304
	ds_read_b128 v[26:29], v46 offset:2352
	s_waitcnt lgkmcnt(2)
	v_fmac_f32_e32 v14, v10, v18
	v_fmac_f32_e32 v14, v11, v19
	v_fmac_f32_e32 v14, v12, v20
	v_fmac_f32_e32 v14, v13, v21
	ds_read_b128 v[10:13], v9 offset:320
	ds_read_b128 v[18:21], v46 offset:2368
	s_waitcnt lgkmcnt(2)
	v_fmac_f32_e32 v14, v22, v26
	v_fmac_f32_e32 v14, v23, v27
	v_fmac_f32_e32 v14, v24, v28
	v_fmac_f32_e32 v14, v25, v29
	ds_read_b128 v[22:25], v9 offset:336
	ds_read_b128 v[26:29], v46 offset:2384
	s_waitcnt lgkmcnt(2)
	v_fmac_f32_e32 v14, v10, v18
	v_fmac_f32_e32 v14, v11, v19
	v_fmac_f32_e32 v14, v12, v20
	v_fmac_f32_e32 v14, v13, v21
	ds_read_b128 v[10:13], v9 offset:352
	ds_read_b128 v[18:21], v46 offset:2400
	s_waitcnt lgkmcnt(2)
	v_fmac_f32_e32 v14, v22, v26
	v_fmac_f32_e32 v14, v23, v27
	v_fmac_f32_e32 v14, v24, v28
	v_fmac_f32_e32 v14, v25, v29
	ds_read_b128 v[22:25], v9 offset:368
	ds_read_b128 v[26:29], v46 offset:2416
	s_waitcnt lgkmcnt(2)
	v_fmac_f32_e32 v14, v10, v18
	v_fmac_f32_e32 v14, v11, v19
	v_fmac_f32_e32 v14, v12, v20
	v_fmac_f32_e32 v14, v13, v21
	ds_read_b128 v[10:13], v9 offset:384
	ds_read_b128 v[18:21], v46 offset:2432
	s_waitcnt lgkmcnt(2)
	v_fmac_f32_e32 v14, v22, v26
	v_fmac_f32_e32 v14, v23, v27
	v_fmac_f32_e32 v14, v24, v28
	v_fmac_f32_e32 v14, v25, v29
	ds_read_b128 v[22:25], v9 offset:400
	ds_read_b128 v[26:29], v46 offset:2448
	s_waitcnt lgkmcnt(2)
	v_fmac_f32_e32 v14, v10, v18
	v_fmac_f32_e32 v14, v11, v19
	v_fmac_f32_e32 v14, v12, v20
	v_fmac_f32_e32 v14, v13, v21
	ds_read_b128 v[10:13], v9 offset:416
	ds_read_b128 v[18:21], v46 offset:2464
	s_waitcnt lgkmcnt(2)
	v_fmac_f32_e32 v14, v22, v26
	v_fmac_f32_e32 v14, v23, v27
	v_fmac_f32_e32 v14, v24, v28
	v_fmac_f32_e32 v14, v25, v29
	ds_read_b128 v[22:25], v9 offset:432
	ds_read_b128 v[26:29], v46 offset:2480
	s_waitcnt lgkmcnt(2)
	v_fmac_f32_e32 v14, v10, v18
	v_fmac_f32_e32 v14, v11, v19
	v_fmac_f32_e32 v14, v12, v20
	v_fmac_f32_e32 v14, v13, v21
	s_waitcnt lgkmcnt(0)
	v_fmac_f32_e32 v14, v22, v26
	ds_read_b128 v[10:13], v9 offset:448
	ds_read_b128 v[18:21], v46 offset:2496
	v_fmac_f32_e32 v14, v23, v27
	v_fmac_f32_e32 v14, v24, v28
	v_fmac_f32_e32 v14, v25, v29
	ds_read_b128 v[22:25], v9 offset:464
	ds_read_b128 v[26:29], v46 offset:2512
	s_waitcnt lgkmcnt(2)
	v_fmac_f32_e32 v14, v10, v18
	v_fmac_f32_e32 v14, v11, v19
	v_fmac_f32_e32 v14, v12, v20
	v_fmac_f32_e32 v14, v13, v21
	s_waitcnt lgkmcnt(0)
	v_pk_mul_f32 v[10:11], v[22:23], v[26:27]
	v_sub_u32_e32 v6, v6, v8
	v_add_f32_e32 v10, v14, v10
	v_add_f32_e32 v22, v10, v11
	ds_read_b128 v[10:13], v9 offset:480
	ds_read_b128 v[18:21], v46 offset:2528
	v_pk_mul_f32 v[14:15], v[24:25], v[28:29]
	v_cvt_f32_i32_e32 v6, v6
	v_add_f32_e32 v14, v22, v14
	ds_read_b128 v[22:25], v9 offset:496
	ds_read_b128 v[26:29], v46 offset:2544
	v_add_f32_e32 v14, v14, v15
	s_waitcnt lgkmcnt(2)
	v_pk_mul_f32 v[10:11], v[10:11], v[18:19]
	s_nop 0
	v_add_f32_e32 v9, v14, v10
	v_add_f32_e32 v9, v9, v11
	v_pk_mul_f32 v[10:11], v[12:13], v[20:21]
	s_nop 0
	v_add_f32_e32 v9, v9, v10
	v_add_f32_e32 v9, v9, v11
	s_waitcnt lgkmcnt(0)
	v_pk_mul_f32 v[10:11], v[22:23], v[26:27]
	s_nop 0
	v_add_f32_e32 v8, v9, v10
	v_add_f32_e32 v10, v8, v11
	v_mul_f32_e32 v11, v1, v6
	v_cmp_gt_f32_e32 vcc, s34, v11
	v_pk_mul_f32 v[8:9], v[24:25], v[28:29]
	s_nop 0
	v_cndmask_b32_e32 v11, 0, v168, vcc
	v_fmac_f32_e32 v11, v1, v6
	v_exp_f32_e32 v6, v11
	v_add_f32_e32 v8, v10, v8
	v_add_f32_e32 v8, v8, v9
	v_cndmask_b32_e32 v9, 0, v171, vcc
	v_ldexp_f32 v6, v6, v9
	v_mul_f32_e32 v9, v6, v8

; #define LAS __attribute__((address_space(3)))
; __device__ __forceinline__ void swa_sample_unit(const Ctx& P, int li, int b, int qh, LAS unsigned char* wl  , const bf16_t* PROJ, bf16_t* H, int lane) {
;     ...
;     for (int sl = 0; sl < 3; ++sl) { const int key = lane + 64 * sl;
;         float a0 = 0.f, a1 = 0.f, a2 = 0.f, a3 = 0.f;
;         if (key < 128) { const float* kp = ck + (size_t)key * 128 + kvh * 64;
; #pragma unroll 8
;             for (int d4 = 0; d4 < 16; ++d4) { const f32x4 kx = *(const f32x4*)(kp + 4 * d4);
;                 const f32x4 q0 = *(const LAS f32x4*)(qs + 4 * d4), q1 = *(const LAS f32x4*)(qs + 64 + 4 * d4), q2 = *(const LAS f32x4*)(qs + 128 + 4 * d4), q3 = *(const LAS f32x4*)(qs + 192 + 4 * d4);
;                 a0 += kx[0] * q0[0] + kx[1] * q0[1] + kx[2] * q0[2] + kx[3] * q0[3]; a1 += kx[0] * q1[0] + kx[1] * q1[1] + kx[2] * q1[2] + kx[3] * q1[3];
;                 a2 += kx[0] * q2[0] + kx[1] * q2[1] + kx[2] * q2[2] + kx[3] * q2[3]; a3 += kx[0] * q3[0] + kx[1] * q3[1] + kx[2] * q3[2] + kx[3] * q3[3]; }
.LBB0_486:
	global_load_dwordx4 v[8:11], v[0:1], off offset:-16
	global_load_dwordx4 v[12:15], v[0:1], off offset:-32
	global_load_dwordx4 v[36:39], v[0:1], off offset:-48
	global_load_dwordx4 v[44:47], v[0:1], off offset:-64
	v_add_u32_e32 v6, s0, v19
	ds_read_b128 v[48:51], v6
	ds_read_b128 v[52:55], v6 offset:16
	ds_read_b128 v[56:59], v6 offset:32
	ds_read_b128 v[60:63], v6 offset:48
	ds_read_b128 v[64:67], v6 offset:256
	ds_read_b128 v[68:71], v6 offset:512
	ds_read_b128 v[72:75], v6 offset:768
	s_addk_i32 s0, 0x80
	s_cmpk_lg_i32 s0, 0x100
	s_waitcnt lgkmcnt(2)
	v_pk_mov_b32 v[40:41], v[48:49], v[64:65] op_sel:[1,0]
	v_mov_b32_e32 v49, v65
	s_waitcnt vmcnt(0)
	v_pk_mul_f32 v[48:49], v[44:45], v[48:49]
	s_nop 0
	v_pk_fma_f32 v[40:41], v[44:45], v[40:41], v[48:49] op_sel:[1,0,0] op_sel_hi:[0,1,1]
	v_mov_b32_e32 v48, v50
	v_mov_b32_e32 v49, v66
	v_pk_fma_f32 v[40:41], v[46:47], v[48:49], v[40:41] op_sel_hi:[0,1,1]
	v_mov_b32_e32 v48, v47
	v_mov_b32_e32 v66, v51
	v_pk_fma_f32 v[40:41], v[48:49], v[66:67], v[40:41] op_sel_hi:[0,1,1]
	v_pk_add_f32 v[40:41], v[4:5], v[40:41]
	s_waitcnt lgkmcnt(0)
	v_pk_mov_b32 v[4:5], v[68:69], v[72:73] op_sel:[1,0]
	v_mov_b32_e32 v69, v73
	v_pk_mul_f32 v[50:51], v[44:45], v[68:69]
	s_nop 0
	v_pk_fma_f32 v[4:5], v[44:45], v[4:5], v[50:51] op_sel:[1,0,0] op_sel_hi:[0,1,1]
	v_mov_b32_e32 v44, v70
	v_mov_b32_e32 v45, v74
	v_pk_fma_f32 v[4:5], v[46:47], v[44:45], v[4:5] op_sel_hi:[0,1,1]
	v_mov_b32_e32 v74, v71
	v_pk_fma_f32 v[4:5], v[48:49], v[74:75], v[4:5] op_sel_hi:[0,1,1]
	v_pk_add_f32 v[64:65], v[2:3], v[4:5]
	ds_read_b128 v[2:5], v6 offset:272
	ds_read_b128 v[44:47], v6 offset:528
	ds_read_b128 v[48:51], v6 offset:784
	s_waitcnt lgkmcnt(2)
	v_pk_mov_b32 v[66:67], v[52:53], v[2:3] op_sel:[1,0]
	v_mov_b32_e32 v53, v3
	v_pk_mul_f32 v[2:3], v[36:37], v[52:53]
	v_mov_b32_e32 v52, v54
	v_pk_fma_f32 v[2:3], v[36:37], v[66:67], v[2:3] op_sel:[1,0,0] op_sel_hi:[0,1,1]
	v_mov_b32_e32 v53, v4
	v_pk_fma_f32 v[2:3], v[38:39], v[52:53], v[2:3] op_sel_hi:[0,1,1]
	v_mov_b32_e32 v52, v39
	v_mov_b32_e32 v4, v55
	v_pk_fma_f32 v[2:3], v[52:53], v[4:5], v[2:3] op_sel_hi:[0,1,1]
	v_pk_add_f32 v[40:41], v[40:41], v[2:3]
	s_waitcnt lgkmcnt(0)
	v_pk_mov_b32 v[2:3], v[44:45], v[48:49] op_sel:[1,0]
	v_mov_b32_e32 v45, v49
	v_pk_mul_f32 v[4:5], v[36:37], v[44:45]
	s_nop 0
	v_pk_fma_f32 v[2:3], v[36:37], v[2:3], v[4:5] op_sel:[1,0,0] op_sel_hi:[0,1,1]
	v_mov_b32_e32 v4, v46
	v_mov_b32_e32 v5, v50
	v_pk_fma_f32 v[2:3], v[38:39], v[4:5], v[2:3] op_sel_hi:[0,1,1]
	v_mov_b32_e32 v50, v47
	v_pk_fma_f32 v[2:3], v[52:53], v[50:51], v[2:3] op_sel_hi:[0,1,1]
	v_pk_add_f32 v[48:49], v[64:65], v[2:3]
	ds_read_b128 v[2:5], v6 offset:288
	ds_read_b128 v[36:39], v6 offset:544
	ds_read_b128 v[44:47], v6 offset:800
	s_waitcnt lgkmcnt(2)
	v_pk_mov_b32 v[50:51], v[56:57], v[2:3] op_sel:[1,0]
	v_mov_b32_e32 v57, v3
	v_pk_mul_f32 v[2:3], v[12:13], v[56:57]
	s_nop 0
	v_pk_fma_f32 v[2:3], v[12:13], v[50:51], v[2:3] op_sel:[1,0,0] op_sel_hi:[0,1,1]
	v_mov_b32_e32 v50, v58
	v_mov_b32_e32 v51, v4
	v_pk_fma_f32 v[2:3], v[14:15], v[50:51], v[2:3] op_sel_hi:[0,1,1]
	v_mov_b32_e32 v50, v15
	v_mov_b32_e32 v4, v59
	v_pk_fma_f32 v[2:3], v[50:51], v[4:5], v[2:3] op_sel_hi:[0,1,1]
	v_pk_add_f32 v[40:41], v[40:41], v[2:3]
	s_waitcnt lgkmcnt(0)
	v_pk_mov_b32 v[2:3], v[36:37], v[44:45] op_sel:[1,0]
	v_mov_b32_e32 v37, v45
	v_pk_mul_f32 v[4:5], v[12:13], v[36:37]
	s_nop 0
	v_pk_fma_f32 v[2:3], v[12:13], v[2:3], v[4:5] op_sel:[1,0,0] op_sel_hi:[0,1,1]
	v_mov_b32_e32 v4, v38
	v_mov_b32_e32 v5, v46
	v_pk_fma_f32 v[2:3], v[14:15], v[4:5], v[2:3] op_sel_hi:[0,1,1]
	v_mov_b32_e32 v46, v39
	v_pk_fma_f32 v[2:3], v[50:51], v[46:47], v[2:3] op_sel_hi:[0,1,1]
	v_pk_add_f32 v[44:45], v[48:49], v[2:3]
	ds_read_b128 v[2:5], v6 offset:304
	ds_read_b128 v[12:15], v6 offset:560
	ds_read_b128 v[36:39], v6 offset:816
	s_waitcnt lgkmcnt(2)
	v_pk_mov_b32 v[46:47], v[60:61], v[2:3] op_sel:[1,0]
	v_mov_b32_e32 v61, v3
	v_pk_mul_f32 v[2:3], v[8:9], v[60:61]
	s_nop 0
	v_pk_fma_f32 v[2:3], v[8:9], v[46:47], v[2:3] op_sel:[1,0,0] op_sel_hi:[0,1,1]
	v_mov_b32_e32 v46, v62
	v_mov_b32_e32 v47, v4
	v_pk_fma_f32 v[2:3], v[10:11], v[46:47], v[2:3] op_sel_hi:[0,1,1]
	v_mov_b32_e32 v46, v11
	v_mov_b32_e32 v4, v63
	v_pk_fma_f32 v[2:3], v[46:47], v[4:5], v[2:3] op_sel_hi:[0,1,1]
	s_waitcnt lgkmcnt(0)
	v_pk_mov_b32 v[4:5], v[12:13], v[36:37] op_sel:[1,0]
	v_mov_b32_e32 v13, v37
	v_pk_mul_f32 v[12:13], v[8:9], v[12:13]
	v_pk_add_f32 v[2:3], v[40:41], v[2:3]
	v_pk_fma_f32 v[4:5], v[8:9], v[4:5], v[12:13] op_sel:[1,0,0] op_sel_hi:[0,1,1]
	v_mov_b32_e32 v8, v14
	v_mov_b32_e32 v9, v38
	v_pk_fma_f32 v[4:5], v[10:11], v[8:9], v[4:5] op_sel_hi:[0,1,1]
	v_mov_b32_e32 v38, v15
	v_pk_fma_f32 v[4:5], v[46:47], v[38:39], v[4:5] op_sel_hi:[0,1,1]
	v_pk_add_f32 v[4:5], v[44:45], v[4:5]
	global_load_dwordx4 v[8:11], v[0:1], off offset:48
	global_load_dwordx4 v[12:15], v[0:1], off offset:32
	global_load_dwordx4 v[36:39], v[0:1], off offset:16
	global_load_dwordx4 v[44:47], v[0:1], off
	ds_read_b128 v[48:51], v6 offset:64
	ds_read_b128 v[52:55], v6 offset:320
	ds_read_b128 v[56:59], v6 offset:576
	ds_read_b128 v[60:63], v6 offset:832
	v_lshl_add_u64 v[0:1], v[0:1], 0, s[28:29]
	s_waitcnt lgkmcnt(2)
	v_pk_mov_b32 v[40:41], v[48:49], v[52:53] op_sel:[1,0]
	v_mov_b32_e32 v49, v53
	s_waitcnt vmcnt(0)
	v_pk_mul_f32 v[48:49], v[44:45], v[48:49]
	s_nop 0
	v_pk_fma_f32 v[40:41], v[44:45], v[40:41], v[48:49] op_sel:[1,0,0] op_sel_hi:[0,1,1]
	v_mov_b32_e32 v48, v50
	v_mov_b32_e32 v49, v54
	v_pk_fma_f32 v[40:41], v[46:47], v[48:49], v[40:41] op_sel_hi:[0,1,1]
	v_mov_b32_e32 v48, v47
	v_mov_b32_e32 v54, v51
	v_pk_fma_f32 v[40:41], v[48:49], v[54:55], v[40:41] op_sel_hi:[0,1,1]
	v_pk_add_f32 v[40:41], v[2:3], v[40:41]
	s_waitcnt lgkmcnt(0)
; #define LAS __attribute__((address_space(3)))
; __device__ __forceinline__ float bf2f(bf16_t b) { return __uint_as_float(((unsigned)b) << 16); }
; __device__ __forceinline__ void swa_sample_unit(const Ctx& P, int li, int b, int qh, LAS unsigned char* wl  , const bf16_t* PROJ, bf16_t* H, int lane) {
;     ...
;             for (int d4 = 0; d4 < 16; ++d4) { const f32x4 kx = *(const f32x4*)(kp + 4 * d4);
;                 const f32x4 q0 = *(const LAS f32x4*)(qs + 4 * d4), q1 = *(const LAS f32x4*)(qs + 64 + 4 * d4), q2 = *(const LAS f32x4*)(qs + 128 + 4 * d4), q3 = *(const LAS f32x4*)(qs + 192 + 4 * d4);
;                 a0 += kx[0] * q0[0] + kx[1] * q0[1] + kx[2] * q0[2] + kx[3] * q0[3]; a1 += kx[0] * q1[0] + kx[1] * q1[1] + kx[2] * q1[2] + kx[3] * q1[3];
;                 a2 += kx[0] * q2[0] + kx[1] * q2[1] + kx[2] * q2[2] + kx[3] * q2[3]; a3 += kx[0] * q3[0] + kx[1] * q3[1] + kx[2] * q3[2] + kx[3] * q3[3]; }
;         } else if (key < 132) { const bf16_t* kp = PROJ + (prow + key - 128) * EIN + 5120 + kvh * 64;
; #pragma unroll 2
;             for (int d = 0; d < 64; ++d) { const float kx = bf2f(kp[d]); a0 += kx * qs[d]; a1 += kx * qs[64 + d]; a2 += kx * qs[128 + d]; a3 += kx * qs[192 + d]; } }
	v_pk_mov_b32 v[2:3], v[56:57], v[60:61] op_sel:[1,0]
	v_mov_b32_e32 v57, v61
	v_pk_mul_f32 v[50:51], v[44:45], v[56:57]
	s_nop 0
	v_pk_fma_f32 v[2:3], v[44:45], v[2:3], v[50:51] op_sel:[1,0,0] op_sel_hi:[0,1,1]
	v_mov_b32_e32 v44, v58
	v_mov_b32_e32 v45, v62
	v_pk_fma_f32 v[2:3], v[46:47], v[44:45], v[2:3] op_sel_hi:[0,1,1]
	v_mov_b32_e32 v62, v59
	v_pk_fma_f32 v[2:3], v[48:49], v[62:63], v[2:3] op_sel_hi:[0,1,1]
	v_pk_add_f32 v[56:57], v[4:5], v[2:3]
	ds_read_b128 v[2:5], v6 offset:80
	ds_read_b128 v[44:47], v6 offset:336
	ds_read_b128 v[48:51], v6 offset:592
	ds_read_b128 v[52:55], v6 offset:848
	s_waitcnt lgkmcnt(2)
	v_pk_mov_b32 v[58:59], v[2:3], v[44:45] op_sel:[1,0]
	v_mov_b32_e32 v3, v45
	v_pk_mul_f32 v[2:3], v[36:37], v[2:3]
	v_mov_b32_e32 v44, v4
	v_pk_fma_f32 v[2:3], v[36:37], v[58:59], v[2:3] op_sel:[1,0,0] op_sel_hi:[0,1,1]
	v_mov_b32_e32 v45, v46
	v_pk_fma_f32 v[2:3], v[38:39], v[44:45], v[2:3] op_sel_hi:[0,1,1]
	v_mov_b32_e32 v4, v39
	v_mov_b32_e32 v46, v5
	v_pk_fma_f32 v[2:3], v[4:5], v[46:47], v[2:3] op_sel_hi:[0,1,1]
	v_pk_add_f32 v[40:41], v[40:41], v[2:3]
	s_waitcnt lgkmcnt(0)
	v_pk_mov_b32 v[2:3], v[48:49], v[52:53] op_sel:[1,0]
	v_mov_b32_e32 v49, v53
	v_pk_mul_f32 v[44:45], v[36:37], v[48:49]
	s_nop 0
	v_pk_fma_f32 v[2:3], v[36:37], v[2:3], v[44:45] op_sel:[1,0,0] op_sel_hi:[0,1,1]
	v_mov_b32_e32 v36, v50
	v_mov_b32_e32 v37, v54
	v_pk_fma_f32 v[2:3], v[38:39], v[36:37], v[2:3] op_sel_hi:[0,1,1]
	v_mov_b32_e32 v54, v51
	v_pk_fma_f32 v[2:3], v[4:5], v[54:55], v[2:3] op_sel_hi:[0,1,1]
	v_pk_add_f32 v[52:53], v[56:57], v[2:3]
	ds_read_b128 v[2:5], v6 offset:96
	ds_read_b128 v[36:39], v6 offset:352
	ds_read_b128 v[44:47], v6 offset:608
	ds_read_b128 v[48:51], v6 offset:864
	s_waitcnt lgkmcnt(2)
	v_pk_mov_b32 v[54:55], v[2:3], v[36:37] op_sel:[1,0]
	v_mov_b32_e32 v3, v37
	v_pk_mul_f32 v[2:3], v[12:13], v[2:3]
	v_mov_b32_e32 v36, v4
	v_pk_fma_f32 v[2:3], v[12:13], v[54:55], v[2:3] op_sel:[1,0,0] op_sel_hi:[0,1,1]
	v_mov_b32_e32 v37, v38
	v_pk_fma_f32 v[2:3], v[14:15], v[36:37], v[2:3] op_sel_hi:[0,1,1]
	v_mov_b32_e32 v4, v15
	v_mov_b32_e32 v38, v5
	v_pk_fma_f32 v[2:3], v[4:5], v[38:39], v[2:3] op_sel_hi:[0,1,1]
	v_pk_add_f32 v[40:41], v[40:41], v[2:3]
	s_waitcnt lgkmcnt(0)
	v_pk_mov_b32 v[2:3], v[44:45], v[48:49] op_sel:[1,0]
	v_mov_b32_e32 v45, v49
	v_pk_mul_f32 v[36:37], v[12:13], v[44:45]
	s_nop 0
	v_pk_fma_f32 v[2:3], v[12:13], v[2:3], v[36:37] op_sel:[1,0,0] op_sel_hi:[0,1,1]
	v_mov_b32_e32 v12, v46
	v_mov_b32_e32 v13, v50
	v_pk_fma_f32 v[2:3], v[14:15], v[12:13], v[2:3] op_sel_hi:[0,1,1]
	v_mov_b32_e32 v50, v47
	v_pk_fma_f32 v[2:3], v[4:5], v[50:51], v[2:3] op_sel_hi:[0,1,1]
	v_pk_add_f32 v[48:49], v[52:53], v[2:3]
	ds_read_b128 v[2:5], v6 offset:112
	ds_read_b128 v[12:15], v6 offset:368
	ds_read_b128 v[36:39], v6 offset:624
	ds_read_b128 v[44:47], v6 offset:880
	s_waitcnt lgkmcnt(2)
	v_pk_mov_b32 v[6:7], v[2:3], v[12:13] op_sel:[1,0]
	v_mov_b32_e32 v3, v13
	v_pk_mul_f32 v[2:3], v[8:9], v[2:3]
	s_nop 0
	v_pk_fma_f32 v[2:3], v[8:9], v[6:7], v[2:3] op_sel:[1,0,0] op_sel_hi:[0,1,1]
	v_mov_b32_e32 v6, v4
	v_mov_b32_e32 v7, v14
	v_pk_fma_f32 v[2:3], v[10:11], v[6:7], v[2:3] op_sel_hi:[0,1,1]
	v_mov_b32_e32 v6, v11
	v_mov_b32_e32 v14, v5
	v_pk_fma_f32 v[2:3], v[6:7], v[14:15], v[2:3] op_sel_hi:[0,1,1]
	v_pk_add_f32 v[4:5], v[40:41], v[2:3]
	s_waitcnt lgkmcnt(0)
	v_pk_mov_b32 v[2:3], v[36:37], v[44:45] op_sel:[1,0]
	v_mov_b32_e32 v37, v45
	v_pk_mul_f32 v[12:13], v[8:9], v[36:37]
	s_nop 0
	v_pk_fma_f32 v[2:3], v[8:9], v[2:3], v[12:13] op_sel:[1,0,0] op_sel_hi:[0,1,1]
	v_mov_b32_e32 v8, v38
	v_mov_b32_e32 v9, v46
	v_pk_fma_f32 v[2:3], v[10:11], v[8:9], v[2:3] op_sel_hi:[0,1,1]
	v_mov_b32_e32 v46, v39
	v_pk_fma_f32 v[2:3], v[6:7], v[46:47], v[2:3] op_sel_hi:[0,1,1]
	v_pk_add_f32 v[2:3], v[48:49], v[2:3]
	s_cbranch_scc1 .LBB0_486
	v_or_b32_e32 v10, 0x80, v20
	s_movk_i32 s0, 0x84
	v_cmp_gt_u32_e64 s[0:1], s0, v10
	v_mov_b32_e32 v7, 0
	v_mov_b32_e32 v6, 0
	v_mov_b32_e32 v1, 0
	v_mov_b32_e32 v0, 0
	s_and_saveexec_b64 s[4:5], s[0:1]
	s_cbranch_execz .LBB0_491
; __device__ __forceinline__ float bf2f(bf16_t b) { return __uint_as_float(((unsigned)b) << 16); }
; __device__ __forceinline__ void swa_sample_unit(const Ctx& P, int li, int b, int qh, LAS unsigned char* wl  , const bf16_t* PROJ, bf16_t* H, int lane) {
;     ...
;         } else if (key < 132) { const bf16_t* kp = PROJ + (prow + key - 128) * EIN + 5120 + kvh * 64;
; #pragma unroll 2
;             for (int d = 0; d < 64; ++d) { const float kx = bf2f(kp[d]); a0 += kx * qs[d]; a1 += kx * qs[64 + d]; a2 += kx * qs[128 + d]; a3 += kx * qs[192 + d]; } }
;         const float a[4] = {a0, a1, a2, a3};
; #pragma unroll
;         for (int i = 0; i < 4; ++i) { const int dist = 128 + i - key; const bool valid = key < 132 && dist >= 0 && dist <= 128;
;             s[sl][i] = valid ? a[i] * 0.125f - slope * (float)dist : -INFINITY; } }
	v_add_u32_e32 v0, v28, v20
	v_mad_i64_i32 v[0:1], s[18:19], v0, s35, 0
	v_lshl_or_b32 v0, v30, 7, v0
	v_mov_b32_e32 v8, 0
	v_lshl_add_u64 v[0:1], s[16:17], 0, v[0:1]
	v_lshrrev_b32_e32 v201, 6, v179
	v_and_b32_e32 v200, 63, v179
	v_lshlrev_b32_e32 v201, 13, v201
	v_add_u32_e32 v201, 0x10000, v201
	v_lshl_add_u32 v200, v200, 2, v201
	s_mov_b32 s18, -2
	s_mov_b32 s19, -1
	v_lshl_add_u64 v[202:203], v[0:1], 0, s[18:19]
	v_readfirstlane_b32 s18, v201
	s_nop 0
	s_mov_b32 m0, s18
	s_nop 0
	global_load_lds_dword v[202:203], off
	v_lshl_add_u64 v[202:203], v[202:203], 0, 4
	s_add_i32 m0, m0, 0x100
	s_nop 0
	global_load_lds_dword v[202:203], off
	v_lshl_add_u64 v[202:203], v[202:203], 0, 4
	s_add_i32 m0, m0, 0x100
	s_nop 0
	global_load_lds_dword v[202:203], off
	v_lshl_add_u64 v[202:203], v[202:203], 0, 4
	s_add_i32 m0, m0, 0x100
	s_nop 0
	global_load_lds_dword v[202:203], off
	v_lshl_add_u64 v[202:203], v[202:203], 0, 4
	s_add_i32 m0, m0, 0x100
	s_nop 0
	global_load_lds_dword v[202:203], off
	v_lshl_add_u64 v[202:203], v[202:203], 0, 4
	s_add_i32 m0, m0, 0x100
	s_nop 0
	global_load_lds_dword v[202:203], off
	v_lshl_add_u64 v[202:203], v[202:203], 0, 4
	s_add_i32 m0, m0, 0x100
	s_nop 0
	global_load_lds_dword v[202:203], off
	v_lshl_add_u64 v[202:203], v[202:203], 0, 4
	s_add_i32 m0, m0, 0x100
	s_nop 0
	global_load_lds_dword v[202:203], off
	v_lshl_add_u64 v[202:203], v[202:203], 0, 4
	s_add_i32 m0, m0, 0x100
	s_nop 0
	global_load_lds_dword v[202:203], off
	v_lshl_add_u64 v[202:203], v[202:203], 0, 4
	s_add_i32 m0, m0, 0x100
	s_nop 0
	global_load_lds_dword v[202:203], off
	v_lshl_add_u64 v[202:203], v[202:203], 0, 4
	s_add_i32 m0, m0, 0x100
	s_nop 0
	global_load_lds_dword v[202:203], off
	v_lshl_add_u64 v[202:203], v[202:203], 0, 4
	s_add_i32 m0, m0, 0x100
	s_nop 0
	global_load_lds_dword v[202:203], off
	v_lshl_add_u64 v[202:203], v[202:203], 0, 4
	s_add_i32 m0, m0, 0x100
	s_nop 0
	global_load_lds_dword v[202:203], off
	v_lshl_add_u64 v[202:203], v[202:203], 0, 4
	s_add_i32 m0, m0, 0x100
	s_nop 0
	global_load_lds_dword v[202:203], off
	v_lshl_add_u64 v[202:203], v[202:203], 0, 4
	s_add_i32 m0, m0, 0x100
	s_nop 0
	global_load_lds_dword v[202:203], off
	v_lshl_add_u64 v[202:203], v[202:203], 0, 4
	s_add_i32 m0, m0, 0x100
	s_nop 0
	global_load_lds_dword v[202:203], off
	v_lshl_add_u64 v[202:203], v[202:203], 0, 4
	s_add_i32 m0, m0, 0x100
	s_nop 0
	global_load_lds_dword v[202:203], off
	v_lshl_add_u64 v[202:203], v[202:203], 0, 4
	s_add_i32 m0, m0, 0x100
	s_nop 0
	global_load_lds_dword v[202:203], off
	v_lshl_add_u64 v[202:203], v[202:203], 0, 4
	s_add_i32 m0, m0, 0x100
	s_nop 0
	global_load_lds_dword v[202:203], off
	v_lshl_add_u64 v[202:203], v[202:203], 0, 4
	s_add_i32 m0, m0, 0x100
	s_nop 0
	global_load_lds_dword v[202:203], off
	v_lshl_add_u64 v[202:203], v[202:203], 0, 4
	s_add_i32 m0, m0, 0x100
	s_nop 0
	global_load_lds_dword v[202:203], off
	v_lshl_add_u64 v[202:203], v[202:203], 0, 4
	s_add_i32 m0, m0, 0x100
	s_nop 0
	global_load_lds_dword v[202:203], off
	v_lshl_add_u64 v[202:203], v[202:203], 0, 4
	s_add_i32 m0, m0, 0x100
	s_nop 0
	global_load_lds_dword v[202:203], off
	v_lshl_add_u64 v[202:203], v[202:203], 0, 4
	s_add_i32 m0, m0, 0x100
	s_nop 0
	global_load_lds_dword v[202:203], off
	v_lshl_add_u64 v[202:203], v[202:203], 0, 4
	s_add_i32 m0, m0, 0x100
	s_nop 0
	global_load_lds_dword v[202:203], off
	v_lshl_add_u64 v[202:203], v[202:203], 0, 4
	s_add_i32 m0, m0, 0x100
	s_nop 0
	global_load_lds_dword v[202:203], off
	v_lshl_add_u64 v[202:203], v[202:203], 0, 4
	s_add_i32 m0, m0, 0x100
	s_nop 0
	global_load_lds_dword v[202:203], off
	v_lshl_add_u64 v[202:203], v[202:203], 0, 4
	s_add_i32 m0, m0, 0x100
	s_nop 0
	global_load_lds_dword v[202:203], off
	v_lshl_add_u64 v[202:203], v[202:203], 0, 4
	s_add_i32 m0, m0, 0x100
	s_nop 0
	global_load_lds_dword v[202:203], off
	v_lshl_add_u64 v[202:203], v[202:203], 0, 4
	s_add_i32 m0, m0, 0x100
	s_nop 0
	global_load_lds_dword v[202:203], off
	v_lshl_add_u64 v[202:203], v[202:203], 0, 4
	s_add_i32 m0, m0, 0x100
	s_nop 0
	global_load_lds_dword v[202:203], off
	v_lshl_add_u64 v[202:203], v[202:203], 0, 4
	s_add_i32 m0, m0, 0x100
	s_nop 0
	global_load_lds_dword v[202:203], off
	s_waitcnt vmcnt(0)
	s_mov_b32 s18, 0
	v_mov_b32_e32 v9, v8
	v_mov_b32_e32 v6, v8
	v_mov_b32_e32 v7, v8
.LBB0_489:
	ds_read_b32 v11, v200
	v_add_u32_e32 v30, s18, v19
	ds_read2_b64 v[12:15], v30 offset1:32
	s_add_i32 s18, s18, 8
	v_add_u32_e32 v200, 0x100, v200
	s_cmpk_lg_i32 s18, 0x100
	s_waitcnt lgkmcnt(0)
	v_mov_b32_e32 v36, v14
	v_mov_b32_e32 v37, v12
	v_mov_b32_e32 v12, v15
	v_lshlrev_b32_e32 v28, 16, v11
	v_pk_fma_f32 v[6:7], v[36:37], v[28:29], v[6:7] op_sel_hi:[1,0,1]
	ds_read2_b64 v[36:39], v30 offset0:64 offset1:96
	v_and_b32_e32 v14, 0xffff0000, v11
	v_pk_fma_f32 v[6:7], v[12:13], v[14:15], v[6:7] op_sel_hi:[1,0,1]
	s_waitcnt lgkmcnt(0)
	v_mov_b32_e32 v40, v38
	v_mov_b32_e32 v41, v36
	v_pk_fma_f32 v[8:9], v[40:41], v[28:29], v[8:9] op_sel_hi:[1,0,1]
	v_mov_b32_e32 v36, v39
	v_pk_fma_f32 v[8:9], v[36:37], v[14:15], v[8:9] op_sel_hi:[1,0,1]
	s_cbranch_scc1 .LBB0_489
	s_mov_b32 s18, 0x3e000000
	v_pk_mul_f32 v[6:7], v[6:7], s[18:19] op_sel_hi:[1,0]
	v_pk_mul_f32 v[0:1], v[8:9], s[18:19] op_sel_hi:[1,0]
